# residual-add GEMM epilogues (o-proj, FFN-down): gate/base loads batched 8 blocks ahead with counted vmcnt instead of one load-wait-store round trip per block
# speedup vs baseline: 1.0152x; 1.0062x over previous
; template <bool SWAP, class Epi, bool THIN = false> ...
;     ...
;     for (int st = 0; st < ns; ++st) {
;       asm volatile("s_waitcnt vmcnt(0)" ::: "memory");
;       __builtin_amdgcn_s_barrier();
;       asm volatile("" ::: "memory");
;       if (st + 1 < ns) {
;         char* nb = smem + ((st + 1) & 1) * 65536;
;         const int ko = (st + 1) * 64;
; #pragma unroll
;         for (int i = 0; i < 4; ++i) { GLDS16(A + (size_t)(ap[i] + ko), nb + tid * 16 + i * 8192); GLDS16(Bt + (size_t)(bp[i] + ko), nb + 32768 + tid * 16 + i * 8192); }
;       }
;       const char* sa = smem + (st & 1) * 65536 + (wr * 64 + fr) * 128;
;       const char* sb = smem + (st & 1) * 65536 + 32768 + (wc * 128 + fr) * 128;
;       if constexpr (THIN) {
;         if (wc == 0) {
; #pragma unroll
;           for (int ks = 0; ks < 2; ++ks) {
;             bf16x8 af[4], bf[2];
; #pragma unroll
;             for (int m = 0; m < 4; ++m) af[m] = *(const bf16x8*)(sa + m * 2048 + (((ks * 4 + fq) ^ swz) << 4));
; #pragma unroll
;             for (int n = 0; n < 2; ++n) bf[n] = *(const bf16x8*)(sb + n * 2048 + (((ks * 4 + fq) ^ swz) << 4));
; #pragma unroll
;             for (int m = 0; m < 4; ++m)
; #pragma unroll
;               for (int n = 0; n < 2; ++n)
;                 acc[m][n] = SWAP ? __builtin_amdgcn_mfma_f32_16x16x32_bf16(bf[n], af[m], acc[m][n], 0, 0, 0)
;                                  : __builtin_amdgcn_mfma_f32_16x16x32_bf16(af[m], bf[n], acc[m][n], 0, 0, 0);
;           }
;         }
;       } else {
;       bf16x8 afA[4], afB[4], bfb[2][2];
; #pragma unroll
;       for (int m = 0; m < 4; ++m) afA[m] = *(const bf16x8*)(sa + m * 2048 + ((fq ^ swz) << 4));
; #pragma unroll
;       for (int n = 0; n < 2; ++n) bfb[0][n] = *(const bf16x8*)(sb + n * 2048 + ((fq ^ swz) << 4));
; #pragma unroll
;       for (int gq = 0; gq < 8; ++gq) {
;         const int ks = gq >> 2, nh = gq & 3;
;         if (gq < 7) {
;           const int ks2 = (gq + 1) >> 2, nh2 = (gq + 1) & 3;
; #pragma unroll
;           for (int n = 0; n < 2; ++n) bfb[(gq + 1) & 1][n] = *(const bf16x8*)(sb + (nh2 * 2 + n) * 2048 + (((ks2 * 4 + fq) ^ swz) << 4));
;         }
;         if (gq == 3) {
; #pragma unroll
;           for (int m = 0; m < 4; ++m) afB[m] = *(const bf16x8*)(sa + m * 2048 + (((4 + fq) ^ swz) << 4));
;         }
;         __builtin_amdgcn_sched_barrier(0);
; #pragma unroll
.LBB0_2116:
	s_add_i32 s8, s7, 0x10000
	s_and_b32 s9, s8, 0x10000
	v_add_u32_e32 v169, s9, v144
	s_nop 0
	v_readfirstlane_b32 s9, v169
	s_waitcnt vmcnt(0)
	s_barrier
	s_and_b32 s7, s7, 0x10000
	v_add_u32_e32 v130, s7, v145
	v_add_u32_e32 v140, v130, v147
	ds_read_b128 v[170:173], v140
	ds_read_b128 v[174:177], v140 offset:2048
	ds_read_b128 v[178:181], v140 offset:4096
	ds_read_b128 v[182:185], v140 offset:6144
	v_or_b32_e32 v140, s7, v146
	v_add_u32_e32 v141, v140, v147
	ds_read_b128 v[186:189], v141 offset:32768
	ds_read_b128 v[190:193], v141 offset:34816
	ds_read_b128 v[194:197], v141 offset:36864
	ds_read_b128 v[198:201], v141 offset:38912
	v_add_u32_e32 v130, v130, v148
	s_waitcnt lgkmcnt(3)
	v_mfma_f32_16x16x32_bf16 v[126:129], v[186:189], v[170:173], v[126:129]
	s_mov_b32 m0, s9
	v_mfma_f32_16x16x32_bf16 v[110:113], v[186:189], v[174:177], v[110:113]
	global_load_lds_dwordx4 v139, s[18:19]
	v_add_u32_e32 v139, 0x80, v139
	v_mfma_f32_16x16x32_bf16 v[82:85], v[186:189], v[178:181], v[82:85]
	v_mfma_f32_16x16x32_bf16 v[50:53], v[186:189], v[182:185], v[50:53]
	ds_read_b128 v[186:189], v141 offset:40960
	ds_read_b128 v[202:205], v141 offset:43008
	s_waitcnt lgkmcnt(4)
	v_mfma_f32_16x16x32_bf16 v[122:125], v[190:193], v[170:173], v[122:125]
	s_add_u32 m0, s9, 0x8000
	v_mfma_f32_16x16x32_bf16 v[106:109], v[190:193], v[174:177], v[106:109]
	global_load_lds_dwordx4 v138, s[24:25]
	v_add_u32_e32 v138, 0x80, v138
	v_mfma_f32_16x16x32_bf16 v[78:81], v[190:193], v[178:181], v[78:81]
	v_mfma_f32_16x16x32_bf16 v[42:45], v[190:193], v[182:185], v[42:45]
	s_waitcnt lgkmcnt(3)
	v_mfma_f32_16x16x32_bf16 v[118:121], v[194:197], v[170:173], v[118:121]
	s_add_u32 m0, s9, 0x2000
	v_mfma_f32_16x16x32_bf16 v[94:97], v[194:197], v[174:177], v[94:97]
	global_load_lds_dwordx4 v137, s[18:19]
	v_add_u32_e32 v137, 0x80, v137
	v_mfma_f32_16x16x32_bf16 v[58:61], v[194:197], v[178:181], v[58:61]
	v_mfma_f32_16x16x32_bf16 v[26:29], v[194:197], v[182:185], v[26:29]
	ds_read_b128 v[190:193], v141 offset:45056
	ds_read_b128 v[194:197], v141 offset:47104
	s_waitcnt lgkmcnt(4)
	v_mfma_f32_16x16x32_bf16 v[114:117], v[198:201], v[170:173], v[114:117]
	s_add_u32 m0, s9, 0xa000
	v_mfma_f32_16x16x32_bf16 v[86:89], v[198:201], v[174:177], v[86:89]
	global_load_lds_dwordx4 v136, s[24:25]
	v_add_u32_e32 v136, 0x80, v136
	v_mfma_f32_16x16x32_bf16 v[54:57], v[198:201], v[178:181], v[54:57]
	v_mfma_f32_16x16x32_bf16 v[22:25], v[198:201], v[182:185], v[22:25]
	v_add_u32_e32 v140, v140, v148
	s_waitcnt lgkmcnt(3)
	v_mfma_f32_16x16x32_bf16 v[102:105], v[186:189], v[170:173], v[102:105]
	ds_read_b128 v[198:201], v140 offset:32768
	ds_read_b128 v[206:209], v140 offset:34816
	s_add_u32 m0, s9, 0x4000
	v_mfma_f32_16x16x32_bf16 v[74:77], v[186:189], v[174:177], v[74:77]
	global_load_lds_dwordx4 v135, s[18:19]
	v_add_u32_e32 v135, 0x80, v135
	v_mfma_f32_16x16x32_bf16 v[46:49], v[186:189], v[178:181], v[46:49]
	v_mfma_f32_16x16x32_bf16 v[10:13], v[186:189], v[182:185], v[10:13]
	ds_read_b128 v[186:189], v130
	ds_read_b128 v[210:213], v130 offset:2048
	ds_read_b128 v[214:217], v130 offset:4096
	ds_read_b128 v[218:221], v130 offset:6144
	s_waitcnt lgkmcnt(8)
	v_mfma_f32_16x16x32_bf16 v[98:101], v[202:205], v[170:173], v[98:101]
	s_add_u32 m0, s9, 0xc000
	v_mfma_f32_16x16x32_bf16 v[66:69], v[202:205], v[174:177], v[66:69]
	global_load_lds_dwordx4 v134, s[24:25]
	v_add_u32_e32 v134, 0x80, v134
	v_mfma_f32_16x16x32_bf16 v[30:33], v[202:205], v[178:181], v[30:33]
	v_mfma_f32_16x16x32_bf16 v[6:9], v[202:205], v[182:185], v[6:9]
	s_waitcnt lgkmcnt(7)
	v_mfma_f32_16x16x32_bf16 v[70:73], v[190:193], v[170:173], v[70:73]
	s_add_u32 m0, s9, 0x6000
	s_waitcnt lgkmcnt(6)
	v_mfma_f32_16x16x32_bf16 v[62:65], v[194:197], v[170:173], v[62:65]
	global_load_lds_dwordx4 v133, s[18:19]
	v_add_u32_e32 v133, 0x80, v133
	v_mfma_f32_16x16x32_bf16 v[38:41], v[190:193], v[174:177], v[38:41]
	v_mfma_f32_16x16x32_bf16 v[34:37], v[194:197], v[174:177], v[34:37]
	ds_read_b128 v[170:173], v140 offset:36864
	ds_read_b128 v[174:177], v140 offset:38912
	v_mfma_f32_16x16x32_bf16 v[18:21], v[190:193], v[178:181], v[18:21]
	s_add_u32 m0, s9, 0xe000
	v_mfma_f32_16x16x32_bf16 v[14:17], v[194:197], v[178:181], v[14:17]
	global_load_lds_dwordx4 v132, s[24:25]
	v_add_u32_e32 v132, 0x80, v132
	v_mfma_f32_16x16x32_bf16 v[2:5], v[190:193], v[182:185], v[2:5]
	v_mfma_f32_16x16x32_bf16 v[90:93], v[194:197], v[182:185], v[90:93]
	ds_read_b128 v[178:181], v140 offset:40960
	ds_read_b128 v[182:185], v140 offset:43008
	s_waitcnt lgkmcnt(7)
	v_mfma_f32_16x16x32_bf16 v[126:129], v[198:201], v[186:189], v[126:129]
	v_mfma_f32_16x16x32_bf16 v[122:125], v[206:209], v[186:189], v[122:125]
	s_waitcnt lgkmcnt(6)
	v_mfma_f32_16x16x32_bf16 v[110:113], v[198:201], v[210:213], v[110:113]
	v_mfma_f32_16x16x32_bf16 v[106:109], v[206:209], v[210:213], v[106:109]
	s_waitcnt lgkmcnt(5)
	v_mfma_f32_16x16x32_bf16 v[82:85], v[198:201], v[214:217], v[82:85]
	v_mfma_f32_16x16x32_bf16 v[78:81], v[206:209], v[214:217], v[78:81]
	s_waitcnt lgkmcnt(4)
	v_mfma_f32_16x16x32_bf16 v[50:53], v[198:201], v[218:221], v[50:53]
	v_mfma_f32_16x16x32_bf16 v[42:45], v[206:209], v[218:221], v[42:45]
	s_waitcnt lgkmcnt(3)
	v_mfma_f32_16x16x32_bf16 v[118:121], v[170:173], v[186:189], v[118:121]
	v_mfma_f32_16x16x32_bf16 v[94:97], v[170:173], v[210:213], v[94:97]
	v_mfma_f32_16x16x32_bf16 v[58:61], v[170:173], v[214:217], v[58:61]
	v_mfma_f32_16x16x32_bf16 v[26:29], v[170:173], v[218:221], v[26:29]
	ds_read_b128 v[170:173], v140 offset:45056
	ds_read_b128 v[190:193], v140 offset:47104
	s_waitcnt lgkmcnt(4)
; template <bool SWAP, class Epi, bool THIN = false> ...
;     ...
;       for (int gq = 0; gq < 8; ++gq) {
;         const int ks = gq >> 2, nh = gq & 3;
;         if (gq < 7) {
;           const int ks2 = (gq + 1) >> 2, nh2 = (gq + 1) & 3;
; #pragma unroll
;           for (int n = 0; n < 2; ++n) bfb[(gq + 1) & 1][n] = *(const bf16x8*)(sb + (nh2 * 2 + n) * 2048 + (((ks2 * 4 + fq) ^ swz) << 4));
;         }
;         if (gq == 3) {
; #pragma unroll
;           for (int m = 0; m < 4; ++m) afB[m] = *(const bf16x8*)(sa + m * 2048 + (((4 + fq) ^ swz) << 4));
;         }
;         __builtin_amdgcn_sched_barrier(0);
; #pragma unroll
;         for (int m = 0; m < 4; ++m)
; #pragma unroll
;           for (int n = 0; n < 2; ++n) {
;             const bf16x8 av = ks ? afB[m] : afA[m];
;             acc[m][nh * 2 + n] = SWAP ? __builtin_amdgcn_mfma_f32_16x16x32_bf16(bfb[gq & 1][n], av, acc[m][nh * 2 + n], 0, 0, 0)
;                                       : __builtin_amdgcn_mfma_f32_16x16x32_bf16(av, bfb[gq & 1][n], acc[m][nh * 2 + n], 0, 0, 0);
;           }
;       }
;       }
;     }
;     __syncthreads();
	v_mfma_f32_16x16x32_bf16 v[114:117], v[174:177], v[186:189], v[114:117]
	v_mfma_f32_16x16x32_bf16 v[86:89], v[174:177], v[210:213], v[86:89]
	v_mfma_f32_16x16x32_bf16 v[54:57], v[174:177], v[214:217], v[54:57]
	v_mfma_f32_16x16x32_bf16 v[22:25], v[174:177], v[218:221], v[22:25]
	s_waitcnt lgkmcnt(3)
	v_mfma_f32_16x16x32_bf16 v[102:105], v[178:181], v[186:189], v[102:105]
	s_waitcnt lgkmcnt(2)
	v_mfma_f32_16x16x32_bf16 v[98:101], v[182:185], v[186:189], v[98:101]
	v_mfma_f32_16x16x32_bf16 v[74:77], v[178:181], v[210:213], v[74:77]
	v_mfma_f32_16x16x32_bf16 v[66:69], v[182:185], v[210:213], v[66:69]
	v_mfma_f32_16x16x32_bf16 v[46:49], v[178:181], v[214:217], v[46:49]
	v_mfma_f32_16x16x32_bf16 v[30:33], v[182:185], v[214:217], v[30:33]
	v_mfma_f32_16x16x32_bf16 v[10:13], v[178:181], v[218:221], v[10:13]
	v_mfma_f32_16x16x32_bf16 v[6:9], v[182:185], v[218:221], v[6:9]
	s_waitcnt lgkmcnt(1)
	v_mfma_f32_16x16x32_bf16 v[70:73], v[170:173], v[186:189], v[70:73]
	s_add_i32 s6, s6, 64
	s_cmpk_eq_i32 s6, 0x3c0
	s_mov_b32 s7, s8
	s_waitcnt lgkmcnt(0)
	v_mfma_f32_16x16x32_bf16 v[62:65], v[190:193], v[186:189], v[62:65]
	v_mfma_f32_16x16x32_bf16 v[38:41], v[170:173], v[210:213], v[38:41]
	v_mfma_f32_16x16x32_bf16 v[34:37], v[190:193], v[210:213], v[34:37]
	v_mfma_f32_16x16x32_bf16 v[18:21], v[170:173], v[214:217], v[18:21]
	v_mfma_f32_16x16x32_bf16 v[14:17], v[190:193], v[214:217], v[14:17]
	v_mfma_f32_16x16x32_bf16 v[2:5], v[170:173], v[218:221], v[2:5]
	v_mfma_f32_16x16x32_bf16 v[90:93], v[190:193], v[218:221], v[90:93]
	s_cbranch_scc0 .LBB0_2116
	s_waitcnt vmcnt(0)
	s_barrier
	v_add_u32_e32 v130, v159, v147
	ds_read_b128 v[132:135], v130
	ds_read_b128 v[136:139], v130 offset:2048
	ds_read_b128 v[170:173], v130 offset:4096
	ds_read_b128 v[174:177], v130 offset:6144
	v_add_u32_e32 v130, v160, v147
	ds_read_b128 v[178:181], v130
	ds_read_b128 v[182:185], v130 offset:2048
	ds_read_b128 v[186:189], v130 offset:4096
	ds_read_b128 v[190:193], v130 offset:6144
	s_waitcnt lgkmcnt(0)
	v_mfma_f32_16x16x32_bf16 v[126:129], v[178:181], v[132:135], v[126:129]
	v_mfma_f32_16x16x32_bf16 v[110:113], v[178:181], v[136:139], v[110:113]
	v_mfma_f32_16x16x32_bf16 v[82:85], v[178:181], v[170:173], v[82:85]
	v_mfma_f32_16x16x32_bf16 v[50:53], v[178:181], v[174:177], v[50:53]
	ds_read_b128 v[178:181], v130 offset:8192
	ds_read_b128 v[194:197], v130 offset:10240
	v_mfma_f32_16x16x32_bf16 v[122:125], v[182:185], v[132:135], v[122:125]
	v_mfma_f32_16x16x32_bf16 v[106:109], v[182:185], v[136:139], v[106:109]
	v_mfma_f32_16x16x32_bf16 v[78:81], v[182:185], v[170:173], v[78:81]
	v_mfma_f32_16x16x32_bf16 v[42:45], v[182:185], v[174:177], v[42:45]
	v_mfma_f32_16x16x32_bf16 v[118:121], v[186:189], v[132:135], v[118:121]
	v_mfma_f32_16x16x32_bf16 v[182:185], v[186:189], v[136:139], v[94:97]
	v_mfma_f32_16x16x32_bf16 v[202:205], v[186:189], v[170:173], v[58:61]
	v_mfma_f32_16x16x32_bf16 v[206:209], v[190:193], v[170:173], v[54:57]
	v_mfma_f32_16x16x32_bf16 v[186:189], v[186:189], v[174:177], v[26:29]
	s_nop 2
	ds_read_b128 v[26:29], v130 offset:12288
	ds_read_b128 v[54:57], v130 offset:14336
	v_mfma_f32_16x16x32_bf16 v[114:117], v[190:193], v[132:135], v[114:117]
	v_mfma_f32_16x16x32_bf16 v[198:201], v[190:193], v[136:139], v[86:89]
	v_mfma_f32_16x16x32_bf16 v[190:193], v[190:193], v[174:177], v[22:25]
	v_add_u32_e32 v130, v160, v148
	s_waitcnt lgkmcnt(0)
	v_mfma_f32_16x16x32_bf16 v[210:213], v[194:197], v[170:173], v[30:33]
	ds_read_b128 v[22:25], v130
	ds_read_b128 v[86:89], v130 offset:2048
	s_nop 0
	v_add_u32_e32 v30, v159, v148
	v_mfma_f32_16x16x32_bf16 v[102:105], v[178:181], v[132:135], v[102:105]
	v_mfma_f32_16x16x32_bf16 v[74:77], v[178:181], v[136:139], v[74:77]
	v_mfma_f32_16x16x32_bf16 v[46:49], v[178:181], v[170:173], v[46:49]
	v_mfma_f32_16x16x32_bf16 v[10:13], v[178:181], v[174:177], v[10:13]
	ds_read_b128 v[178:181], v30
	ds_read_b128 v[214:217], v30 offset:2048
	ds_read_b128 v[218:221], v30 offset:4096
	ds_read_b128 v[222:225], v30 offset:6144
	v_mfma_f32_16x16x32_bf16 v[98:101], v[194:197], v[132:135], v[98:101]
	v_mfma_f32_16x16x32_bf16 v[66:69], v[194:197], v[136:139], v[66:69]
	v_mfma_f32_16x16x32_bf16 v[6:9], v[194:197], v[174:177], v[6:9]
	v_mfma_f32_16x16x32_bf16 v[38:41], v[26:29], v[136:139], v[38:41]
	v_mfma_f32_16x16x32_bf16 v[34:37], v[54:57], v[136:139], v[34:37]
	v_mfma_f32_16x16x32_bf16 v[136:139], v[26:29], v[170:173], v[18:21]
	v_mfma_f32_16x16x32_bf16 v[170:173], v[54:57], v[170:173], v[14:17]
	s_nop 2
	ds_read_b128 v[14:17], v130 offset:4096
	ds_read_b128 v[18:21], v130 offset:6144
	v_mfma_f32_16x16x32_bf16 v[70:73], v[26:29], v[132:135], v[70:73]
	v_mfma_f32_16x16x32_bf16 v[132:135], v[54:57], v[132:135], v[62:65]
	v_mfma_f32_16x16x32_bf16 v[2:5], v[26:29], v[174:177], v[2:5]
	v_mfma_f32_16x16x32_bf16 v[174:177], v[54:57], v[174:177], v[90:93]
	ds_read_b128 v[194:197], v130 offset:8192
	ds_read_b128 v[226:229], v130 offset:10240
	s_waitcnt lgkmcnt(0)
	v_mfma_f32_16x16x32_bf16 v[126:129], v[22:25], v[178:181], v[126:129]
	v_mfma_f32_16x16x32_bf16 v[122:125], v[86:89], v[178:181], v[122:125]
	v_mfma_f32_16x16x32_bf16 v[94:97], v[22:25], v[214:217], v[110:113]
	v_mfma_f32_16x16x32_bf16 v[90:93], v[86:89], v[214:217], v[106:109]
	v_mfma_f32_16x16x32_bf16 v[62:65], v[22:25], v[218:221], v[82:85]
	v_mfma_f32_16x16x32_bf16 v[58:61], v[86:89], v[218:221], v[78:81]
	v_mfma_f32_16x16x32_bf16 v[30:33], v[22:25], v[222:225], v[50:53]
	v_mfma_f32_16x16x32_bf16 v[26:29], v[86:89], v[222:225], v[42:45]
	v_mfma_f32_16x16x32_bf16 v[86:89], v[14:17], v[214:217], v[182:185]
	v_mfma_f32_16x16x32_bf16 v[22:25], v[14:17], v[222:225], v[186:189]
	s_nop 1
	ds_read_b128 v[182:185], v130 offset:12288
	ds_read_b128 v[186:189], v130 offset:14336
	v_mfma_f32_16x16x32_bf16 v[118:121], v[14:17], v[178:181], v[118:121]
	v_mfma_f32_16x16x32_bf16 v[114:117], v[18:21], v[178:181], v[114:117]
	v_mfma_f32_16x16x32_bf16 v[82:85], v[18:21], v[214:217], v[198:201]
	v_mfma_f32_16x16x32_bf16 v[54:57], v[14:17], v[218:221], v[202:205]
	v_mfma_f32_16x16x32_bf16 v[50:53], v[18:21], v[218:221], v[206:209]
	v_mfma_f32_16x16x32_bf16 v[18:21], v[18:21], v[222:225], v[190:193]
	v_mfma_f32_16x16x32_bf16 v[110:113], v[194:197], v[178:181], v[102:105]
	v_mfma_f32_16x16x32_bf16 v[106:109], v[226:229], v[178:181], v[98:101]
	v_mfma_f32_16x16x32_bf16 v[78:81], v[194:197], v[214:217], v[74:77]
	v_mfma_f32_16x16x32_bf16 v[74:77], v[226:229], v[214:217], v[66:69]
	v_mfma_f32_16x16x32_bf16 v[46:49], v[194:197], v[218:221], v[46:49]
	v_mfma_f32_16x16x32_bf16 v[42:45], v[226:229], v[218:221], v[210:213]
	v_mfma_f32_16x16x32_bf16 v[14:17], v[194:197], v[222:225], v[10:13]
	v_mfma_f32_16x16x32_bf16 v[6:9], v[226:229], v[222:225], v[6:9]
	v_mov_b32_e32 v130, v1
	s_waitcnt vmcnt(0) lgkmcnt(0)
	s_barrier
; __device__ __forceinline__ int get_tid512() { int t = threadIdx.x; asm volatile("" : "+v"(t)); return t; }
; __device__ __forceinline__ unsigned pack2(float a, float b) { unsigned r; asm("v_cvt_pk_bf16_f32 %0, %1, %2" : "=v"(r) : "v"(a), "v"(b)); return r; }
; __device__ __forceinline__ float bf2f(bf16_t h) { return __uint_as_float(((unsigned)h) << 16); }
;   __device__ __forceinline__ void c4(int g, int rig, int col, f32x4 v) const {
;     const size_t o = ((size_t)g * 2048 + rig) * 1024 + col;
;     f32x4 bs;
;     if (BASE_F32) bs = __builtin_nontemporal_load((const f32x4*)((const float*)base + o));
;     else {
;       const uint2 u = *(const uint2*)((const bf16_t*)base + o);
;       bs[0] = bf2f((bf16_t)(u.x & 0xffff)); bs[1] = bf2f((bf16_t)(u.x >> 16)); bs[2] = bf2f((bf16_t)(u.y & 0xffff)); bs[3] = bf2f((bf16_t)(u.y >> 16));
;     }
;     const f32x4 gt = *(const f32x4*)(gate + (size_t)g * 6144 + col);
;     f32x4 bi = {0.f, 0.f, 0.f, 0.f};
;     if (bias) bi = *(const f32x4*)(bias + col);
;     f32x4 r;
; #pragma unroll
;     for (int j = 0; j < 4; ++j) r[j] = bs[j] + gt[j] * (v[j] + bi[j]);
;     uint2 w; w.x = pack2(r[0], r[1]); w.y = pack2(r[2], r[3]);
;     *(uint2*)(X16 + o) = w;
;   }
; template <bool SWAP, class Epi, bool THIN = false> ...
;     ...
;     const int te = get_tid512();
;     const int fr_e = te & 15, fq_e = (te & 63) >> 4, wr_e = te >> 7, wc_e = (te >> 6) & 1;
;     const int sub = 2 * mt + (wr_e >> 1);
;     const int g = sub / tpg, ti = sub - g * tpg;
;     const int rig0 = ti * step - halo;
;     const int rw = (wr_e & 1) * 64;
;     if constexpr (Epi::KIND == 0) {
; #pragma unroll
;       for (int m = 0; m < 4; ++m) {
;         const int rig = rig0 + rw + m * 16 + fr_e;
;         if constexpr (Epi::ROWSUM) {
;           float ss = 0.f;
; #pragma unroll
;           for (int n = 0; n < 8; ++n) {
;             const int col = nt * 256 + wc_e * 128 + n * 16 + fq_e * 4;
;             if (col < N) ss += epi.c4(g, rig, col, acc[m][n]);
;           }
;           ss += __shfl_xor(ss, 16); ss += __shfl_xor(ss, 32);
;           if (fq_e == 0) epi.rowsum(g, rig, nt * 2 + wc_e, ss);
;         } else {
; #pragma unroll
;           for (int n = 0; n < 8; ++n) {
;             const int col = nt * 256 + wc_e * 128 + n * 16 + fq_e * 4;
;             if (col < N) epi.c4(g, rig, col, acc[m][n]);
;           }
	v_mfma_f32_16x16x32_bf16 v[98:101], v[186:189], v[178:181], v[132:135]
	v_ashrrev_i32_e32 v11, 8, v130
	v_add_u32_e32 v11, s5, v11
	v_ashrrev_i32_e32 v12, 31, v11
	v_lshrrev_b32_e32 v12, 28, v12
	v_add_u32_e32 v12, v11, v12
	v_ashrrev_i32_e32 v134, 4, v12
	v_lshlrev_b32_e32 v12, 11, v134
	v_lshlrev_b32_e32 v11, 7, v11
	v_sub_u32_e32 v11, v11, v12
	v_lshrrev_b32_e32 v12, 1, v130
	v_and_b32_e32 v10, 15, v130
	v_and_b32_e32 v12, 64, v12
	v_mfma_f32_16x16x32_bf16 v[102:105], v[182:185], v[178:181], v[70:73]
	v_ashrrev_i32_e32 v135, 31, v134
	v_mfma_f32_16x16x32_bf16 v[70:73], v[182:185], v[214:217], v[38:41]
	v_mfma_f32_16x16x32_bf16 v[38:41], v[182:185], v[218:221], v[136:139]
	s_nop 2
	v_or3_b32 v136, v11, v12, v10
	v_lshlrev_b32_e32 v10, 1, v130
	v_and_b32_e32 v132, 0x80, v10
	v_mfma_f32_16x16x32_bf16 v[10:13], v[182:185], v[222:225], v[2:5]
	v_ashrrev_i32_e32 v137, 31, v136
	v_lshlrev_b64 v[138:139], 21, v[134:135]
	v_lshlrev_b64 v[140:141], 10, v[136:137]
	v_lshrrev_b32_e32 v2, 2, v130
	v_and_b32_e32 v2, 12, v2
	v_mfma_f32_16x16x32_bf16 v[66:69], v[186:189], v[214:217], v[34:37]
	v_or3_b32 v132, v2, v132, s4
	v_mad_i64_i32 v[134:135], s[4:5], v134, s33, 0
	v_mfma_f32_16x16x32_bf16 v[34:37], v[186:189], v[218:221], v[170:173]
	v_lshl_add_u64 v[140:141], v[140:141], 0, v[138:139]
	v_cmp_gt_i32_e32 vcc, s34, v132
	v_ashrrev_i32_e32 v133, 31, v132
	v_mfma_f32_16x16x32_bf16 v[2:5], v[186:189], v[222:225], v[174:177]
	v_lshl_add_u64 v[134:135], s[26:27], 0, v[134:135]
	v_lshl_add_u64 v[168:169], v[132:133], 2, v[134:135]
	global_load_dwordx4 v[180:183], v[168:169], off
	global_load_dwordx4 v[184:187], v[168:169], off offset:64
	global_load_dwordx4 v[188:191], v[168:169], off offset:128
	global_load_dwordx4 v[192:195], v[168:169], off offset:192
	global_load_dwordx4 v[196:199], v[168:169], off offset:256
	global_load_dwordx4 v[200:203], v[168:169], off offset:320
	global_load_dwordx4 v[204:207], v[168:169], off offset:384
	global_load_dwordx4 v[208:211], v[168:169], off offset:448
	v_lshl_add_u64 v[178:179], v[140:141], 0, v[132:133]
	v_lshl_add_u64 v[244:245], v[140:141], 0, v[132:133]
	v_lshl_add_u64 v[244:245], v[244:245], 2, s[22:23]
	global_load_dwordx4 v[212:215], v[244:245], off nt
	global_load_dwordx4 v[216:219], v[244:245], off offset:64 nt
	global_load_dwordx4 v[220:223], v[244:245], off offset:128 nt
	global_load_dwordx4 v[224:227], v[244:245], off offset:192 nt
	global_load_dwordx4 v[228:231], v[244:245], off offset:256 nt
	global_load_dwordx4 v[232:235], v[244:245], off offset:320 nt
	global_load_dwordx4 v[236:239], v[244:245], off offset:384 nt
	global_load_dwordx4 v[240:243], v[244:245], off offset:448 nt
	s_nop 0
	v_add_f32_e32 v126, 0, v126
	v_add_f32_e32 v127, 0, v127
	v_add_f32_e32 v128, 0, v128
	v_add_f32_e32 v129, 0, v129
	s_waitcnt vmcnt(7)
	v_fma_f32 v126, v126, v180, v212
	v_fma_f32 v127, v127, v181, v213
	v_fma_f32 v128, v128, v182, v214
	v_fma_f32 v177, v129, v183, v215
	v_cvt_pk_bf16_f32 v126, v126, v127
	v_cvt_pk_bf16_f32 v127, v128, v177
	v_lshl_add_u64 v[128:129], v[178:179], 1, s[20:21]
	global_store_dwordx2 v[128:129], v[126:127], off
	v_or_b32_e32 v126, 16, v132
	v_lshl_add_u64 v[174:175], v[140:141], 0, v[132:133]
	s_nop 0
	v_add_f32_e32 v122, 0, v122
	v_add_f32_e32 v123, 0, v123
	v_add_f32_e32 v124, 0, v124
	v_add_f32_e32 v125, 0, v125
	s_waitcnt vmcnt(7)
	v_fma_f32 v122, v122, v184, v216
	v_fma_f32 v123, v123, v185, v217
	v_fma_f32 v124, v124, v186, v218
	v_fma_f32 v173, v125, v187, v219
	v_cvt_pk_bf16_f32 v122, v122, v123
	v_cvt_pk_bf16_f32 v123, v124, v173
	v_lshl_add_u64 v[124:125], v[174:175], 1, s[20:21]
	global_store_dwordx2 v[124:125], v[122:123], off offset:32
	v_or_b32_e32 v122, 32, v132
	v_lshl_add_u64 v[170:171], v[140:141], 0, v[132:133]
	s_nop 0
	v_add_f32_e32 v118, 0, v118
	v_add_f32_e32 v119, 0, v119
	v_add_f32_e32 v120, 0, v120
	v_add_f32_e32 v121, 0, v121
	s_waitcnt vmcnt(7)
	v_fma_f32 v118, v118, v188, v220
	v_fma_f32 v119, v119, v189, v221
	v_fma_f32 v120, v120, v190, v222
	v_fma_f32 v129, v121, v191, v223
	v_cvt_pk_bf16_f32 v118, v118, v119
	v_cvt_pk_bf16_f32 v119, v120, v129
	v_lshl_add_u64 v[120:121], v[170:171], 1, s[20:21]
	global_store_dwordx2 v[120:121], v[118:119], off offset:64
	v_or_b32_e32 v118, 48, v132
	v_lshl_add_u64 v[126:127], v[140:141], 0, v[132:133]
	s_nop 0
	v_add_f32_e32 v114, 0, v114
	v_add_f32_e32 v115, 0, v115
	v_add_f32_e32 v116, 0, v116
	v_add_f32_e32 v117, 0, v117
	s_waitcnt vmcnt(7)
	v_fma_f32 v114, v114, v192, v224
	v_fma_f32 v115, v115, v193, v225
	v_fma_f32 v116, v116, v194, v226
	v_fma_f32 v125, v117, v195, v227
	v_cvt_pk_bf16_f32 v114, v114, v115
	v_cvt_pk_bf16_f32 v115, v116, v125
	v_lshl_add_u64 v[116:117], v[126:127], 1, s[20:21]
	global_store_dwordx2 v[116:117], v[114:115], off offset:96
	v_or_b32_e32 v114, 64, v132
	v_lshl_add_u64 v[122:123], v[140:141], 0, v[132:133]
	s_nop 0
	v_add_f32_e32 v110, 0, v110
	v_add_f32_e32 v111, 0, v111
	v_add_f32_e32 v112, 0, v112
	v_add_f32_e32 v113, 0, v113
	s_waitcnt vmcnt(7)
	v_fma_f32 v110, v110, v196, v228
	v_fma_f32 v111, v111, v197, v229
	v_fma_f32 v112, v112, v198, v230
	v_fma_f32 v121, v113, v199, v231
	v_cvt_pk_bf16_f32 v110, v110, v111
	v_cvt_pk_bf16_f32 v111, v112, v121
	v_lshl_add_u64 v[112:113], v[122:123], 1, s[20:21]
	global_store_dwordx2 v[112:113], v[110:111], off offset:128
	v_or_b32_e32 v110, 0x50, v132
	v_lshl_add_u64 v[118:119], v[140:141], 0, v[132:133]
	s_nop 0
	v_add_f32_e32 v106, 0, v106
	v_add_f32_e32 v107, 0, v107
	v_add_f32_e32 v108, 0, v108
	v_add_f32_e32 v109, 0, v109
	s_waitcnt vmcnt(7)
; __device__ __forceinline__ unsigned pack2(float a, float b) { unsigned r; asm("v_cvt_pk_bf16_f32 %0, %1, %2" : "=v"(r) : "v"(a), "v"(b)); return r; }
; __device__ __forceinline__ float bf2f(bf16_t h) { return __uint_as_float(((unsigned)h) << 16); }
;   __device__ __forceinline__ void c4(int g, int rig, int col, f32x4 v) const {
;     const size_t o = ((size_t)g * 2048 + rig) * 1024 + col;
;     f32x4 bs;
;     if (BASE_F32) bs = __builtin_nontemporal_load((const f32x4*)((const float*)base + o));
;     else {
;       const uint2 u = *(const uint2*)((const bf16_t*)base + o);
;       bs[0] = bf2f((bf16_t)(u.x & 0xffff)); bs[1] = bf2f((bf16_t)(u.x >> 16)); bs[2] = bf2f((bf16_t)(u.y & 0xffff)); bs[3] = bf2f((bf16_t)(u.y >> 16));
;     }
;     const f32x4 gt = *(const f32x4*)(gate + (size_t)g * 6144 + col);
;     f32x4 bi = {0.f, 0.f, 0.f, 0.f};
;     if (bias) bi = *(const f32x4*)(bias + col);
;     f32x4 r;
; #pragma unroll
;     for (int j = 0; j < 4; ++j) r[j] = bs[j] + gt[j] * (v[j] + bi[j]);
;     uint2 w; w.x = pack2(r[0], r[1]); w.y = pack2(r[2], r[3]);
;     *(uint2*)(X16 + o) = w;
;   }
; template <bool SWAP, class Epi, bool THIN = false> ...
;     ...
;     if constexpr (Epi::KIND == 0) {
; #pragma unroll
;       for (int m = 0; m < 4; ++m) {
;         const int rig = rig0 + rw + m * 16 + fr_e;
;         if constexpr (Epi::ROWSUM) {
;           float ss = 0.f;
; #pragma unroll
;           for (int n = 0; n < 8; ++n) {
;             const int col = nt * 256 + wc_e * 128 + n * 16 + fq_e * 4;
;             if (col < N) ss += epi.c4(g, rig, col, acc[m][n]);
;           }
;           ss += __shfl_xor(ss, 16); ss += __shfl_xor(ss, 32);
;           if (fq_e == 0) epi.rowsum(g, rig, nt * 2 + wc_e, ss);
;         } else {
; #pragma unroll
;           for (int n = 0; n < 8; ++n) {
;             const int col = nt * 256 + wc_e * 128 + n * 16 + fq_e * 4;
;             if (col < N) epi.c4(g, rig, col, acc[m][n]);
;           }
;         }
	v_fma_f32 v106, v106, v200, v232
	v_fma_f32 v107, v107, v201, v233
	v_fma_f32 v108, v108, v202, v234
	v_fma_f32 v117, v109, v203, v235
	v_cvt_pk_bf16_f32 v106, v106, v107
	v_cvt_pk_bf16_f32 v107, v108, v117
	v_lshl_add_u64 v[108:109], v[118:119], 1, s[20:21]
	global_store_dwordx2 v[108:109], v[106:107], off offset:160
	v_or_b32_e32 v106, 0x60, v132
	v_lshl_add_u64 v[114:115], v[140:141], 0, v[132:133]
	s_nop 0
	v_add_f32_e32 v102, 0, v102
	v_add_f32_e32 v103, 0, v103
	v_add_f32_e32 v104, 0, v104
	v_add_f32_e32 v105, 0, v105
	s_waitcnt vmcnt(7)
	v_fma_f32 v102, v102, v204, v236
	v_fma_f32 v103, v103, v205, v237
	v_fma_f32 v104, v104, v206, v238
	v_fma_f32 v113, v105, v207, v239
	v_cvt_pk_bf16_f32 v102, v102, v103
	v_cvt_pk_bf16_f32 v103, v104, v113
	v_lshl_add_u64 v[104:105], v[114:115], 1, s[20:21]
	global_store_dwordx2 v[104:105], v[102:103], off offset:192
	v_or_b32_e32 v102, 0x70, v132
	v_lshl_add_u64 v[110:111], v[140:141], 0, v[132:133]
	s_nop 0
	v_add_f32_e32 v98, 0, v98
	v_add_f32_e32 v99, 0, v99
	v_add_f32_e32 v100, 0, v100
	v_add_f32_e32 v101, 0, v101
	s_waitcnt vmcnt(7)
	v_fma_f32 v98, v98, v208, v240
	v_fma_f32 v99, v99, v209, v241
	v_fma_f32 v100, v100, v210, v242
	v_fma_f32 v109, v101, v211, v243
	v_cvt_pk_bf16_f32 v98, v98, v99
	v_cvt_pk_bf16_f32 v99, v100, v109
	v_lshl_add_u64 v[100:101], v[110:111], 1, s[20:21]
	global_store_dwordx2 v[100:101], v[98:99], off offset:224
	v_or_b32_e32 v98, 16, v136
	v_ashrrev_i32_e32 v99, 31, v98
	v_lshlrev_b64 v[98:99], 10, v[98:99]
	v_lshl_add_u64 v[98:99], v[98:99], 0, v[138:139]
	v_lshl_add_u64 v[108:109], v[98:99], 0, v[132:133]
	v_lshl_add_u64 v[244:245], v[98:99], 0, v[132:133]
	v_lshl_add_u64 v[244:245], v[244:245], 2, s[22:23]
	global_load_dwordx4 v[212:215], v[244:245], off nt
	global_load_dwordx4 v[216:219], v[244:245], off offset:64 nt
	global_load_dwordx4 v[220:223], v[244:245], off offset:128 nt
	global_load_dwordx4 v[224:227], v[244:245], off offset:192 nt
	global_load_dwordx4 v[228:231], v[244:245], off offset:256 nt
	global_load_dwordx4 v[232:235], v[244:245], off offset:320 nt
	global_load_dwordx4 v[236:239], v[244:245], off offset:384 nt
	global_load_dwordx4 v[240:243], v[244:245], off offset:448 nt
	s_nop 0
	v_add_f32_e32 v94, 0, v94
	v_add_f32_e32 v95, 0, v95
	v_add_f32_e32 v96, 0, v96
	v_add_f32_e32 v97, 0, v97
	s_waitcnt vmcnt(7)
	v_fma_f32 v94, v94, v180, v212
	v_fma_f32 v95, v95, v181, v213
	v_fma_f32 v96, v96, v182, v214
	v_fma_f32 v107, v97, v183, v215
	v_cvt_pk_bf16_f32 v94, v94, v95
	v_cvt_pk_bf16_f32 v95, v96, v107
	v_lshl_add_u64 v[96:97], v[108:109], 1, s[20:21]
	global_store_dwordx2 v[96:97], v[94:95], off
	v_lshl_add_u64 v[104:105], v[98:99], 0, v[132:133]
	s_nop 0
	v_add_f32_e32 v90, 0, v90
	v_add_f32_e32 v91, 0, v91
	v_add_f32_e32 v92, 0, v92
	v_add_f32_e32 v93, 0, v93
	s_waitcnt vmcnt(7)
	v_fma_f32 v90, v90, v184, v216
	v_fma_f32 v91, v91, v185, v217
	v_fma_f32 v92, v92, v186, v218
	v_fma_f32 v103, v93, v187, v219
	v_cvt_pk_bf16_f32 v90, v90, v91
	v_cvt_pk_bf16_f32 v91, v92, v103
	v_lshl_add_u64 v[92:93], v[104:105], 1, s[20:21]
	global_store_dwordx2 v[92:93], v[90:91], off offset:32
	v_lshl_add_u64 v[100:101], v[98:99], 0, v[132:133]
	s_nop 0
	v_add_f32_e32 v86, 0, v86
	v_add_f32_e32 v87, 0, v87
	v_add_f32_e32 v88, 0, v88
	v_add_f32_e32 v89, 0, v89
	s_waitcnt vmcnt(7)
	v_fma_f32 v86, v86, v188, v220
	v_fma_f32 v87, v87, v189, v221
	v_fma_f32 v88, v88, v190, v222
	v_fma_f32 v97, v89, v191, v223
	v_cvt_pk_bf16_f32 v86, v86, v87
	v_cvt_pk_bf16_f32 v87, v88, v97
	v_lshl_add_u64 v[88:89], v[100:101], 1, s[20:21]
	global_store_dwordx2 v[88:89], v[86:87], off offset:64
	v_lshl_add_u64 v[94:95], v[98:99], 0, v[132:133]
	s_nop 0
	v_add_f32_e32 v82, 0, v82
	v_add_f32_e32 v83, 0, v83
	v_add_f32_e32 v84, 0, v84
	v_add_f32_e32 v85, 0, v85
	s_waitcnt vmcnt(7)
	v_fma_f32 v82, v82, v192, v224
	v_fma_f32 v83, v83, v193, v225
	v_fma_f32 v84, v84, v194, v226
	v_fma_f32 v93, v85, v195, v227
	v_cvt_pk_bf16_f32 v82, v82, v83
	v_cvt_pk_bf16_f32 v83, v84, v93
	v_lshl_add_u64 v[84:85], v[94:95], 1, s[20:21]
	global_store_dwordx2 v[84:85], v[82:83], off offset:96
	v_lshl_add_u64 v[90:91], v[98:99], 0, v[132:133]
	s_nop 0
	v_add_f32_e32 v78, 0, v78
	v_add_f32_e32 v79, 0, v79
	v_add_f32_e32 v80, 0, v80
	v_add_f32_e32 v81, 0, v81
	s_waitcnt vmcnt(7)
	v_fma_f32 v78, v78, v196, v228
	v_fma_f32 v79, v79, v197, v229
	v_fma_f32 v80, v80, v198, v230
	v_fma_f32 v89, v81, v199, v231
	v_cvt_pk_bf16_f32 v78, v78, v79
	v_cvt_pk_bf16_f32 v79, v80, v89
	v_lshl_add_u64 v[80:81], v[90:91], 1, s[20:21]
	global_store_dwordx2 v[80:81], v[78:79], off offset:128
	v_lshl_add_u64 v[86:87], v[98:99], 0, v[132:133]
	s_nop 0
	v_add_f32_e32 v74, 0, v74
	v_add_f32_e32 v75, 0, v75
	v_add_f32_e32 v76, 0, v76
	v_add_f32_e32 v77, 0, v77
	s_waitcnt vmcnt(7)
	v_fma_f32 v74, v74, v200, v232
	v_fma_f32 v75, v75, v201, v233
	v_fma_f32 v76, v76, v202, v234
	v_fma_f32 v85, v77, v203, v235
	v_cvt_pk_bf16_f32 v74, v74, v75
	v_cvt_pk_bf16_f32 v75, v76, v85
	v_lshl_add_u64 v[76:77], v[86:87], 1, s[20:21]
	global_store_dwordx2 v[76:77], v[74:75], off offset:160
	v_lshl_add_u64 v[82:83], v[98:99], 0, v[132:133]
	v_add_f32_e32 v70, 0, v70
	v_add_f32_e32 v71, 0, v71
	v_add_f32_e32 v72, 0, v72
	v_add_f32_e32 v73, 0, v73
	s_waitcnt vmcnt(7)
	v_fma_f32 v70, v70, v204, v236
	v_fma_f32 v71, v71, v205, v237
	v_fma_f32 v72, v72, v206, v238
	v_fma_f32 v81, v73, v207, v239
	v_cvt_pk_bf16_f32 v70, v70, v71
	v_cvt_pk_bf16_f32 v71, v72, v81
	v_lshl_add_u64 v[72:73], v[82:83], 1, s[20:21]
	global_store_dwordx2 v[72:73], v[70:71], off offset:192
	v_lshl_add_u64 v[78:79], v[98:99], 0, v[132:133]
	v_add_f32_e32 v66, 0, v66
	v_add_f32_e32 v67, 0, v67
	v_add_f32_e32 v68, 0, v68
	v_add_f32_e32 v69, 0, v69
	s_waitcnt vmcnt(7)
; __device__ __forceinline__ unsigned pack2(float a, float b) { unsigned r; asm("v_cvt_pk_bf16_f32 %0, %1, %2" : "=v"(r) : "v"(a), "v"(b)); return r; }
; __device__ __forceinline__ float bf2f(bf16_t h) { return __uint_as_float(((unsigned)h) << 16); }
;   __device__ __forceinline__ void c4(int g, int rig, int col, f32x4 v) const {
;     const size_t o = ((size_t)g * 2048 + rig) * 1024 + col;
;     f32x4 bs;
;     if (BASE_F32) bs = __builtin_nontemporal_load((const f32x4*)((const float*)base + o));
;     else {
;       const uint2 u = *(const uint2*)((const bf16_t*)base + o);
;       bs[0] = bf2f((bf16_t)(u.x & 0xffff)); bs[1] = bf2f((bf16_t)(u.x >> 16)); bs[2] = bf2f((bf16_t)(u.y & 0xffff)); bs[3] = bf2f((bf16_t)(u.y >> 16));
;     }
;     const f32x4 gt = *(const f32x4*)(gate + (size_t)g * 6144 + col);
;     f32x4 bi = {0.f, 0.f, 0.f, 0.f};
;     if (bias) bi = *(const f32x4*)(bias + col);
;     f32x4 r;
; #pragma unroll
;     for (int j = 0; j < 4; ++j) r[j] = bs[j] + gt[j] * (v[j] + bi[j]);
;     uint2 w; w.x = pack2(r[0], r[1]); w.y = pack2(r[2], r[3]);
;     *(uint2*)(X16 + o) = w;
;   }
; template <bool SWAP, class Epi, bool THIN = false> ...
;     ...
;     if constexpr (Epi::KIND == 0) {
; #pragma unroll
;       for (int m = 0; m < 4; ++m) {
;         const int rig = rig0 + rw + m * 16 + fr_e;
;         if constexpr (Epi::ROWSUM) {
;           float ss = 0.f;
; #pragma unroll
;           for (int n = 0; n < 8; ++n) {
;             const int col = nt * 256 + wc_e * 128 + n * 16 + fq_e * 4;
;             if (col < N) ss += epi.c4(g, rig, col, acc[m][n]);
;           }
;           ss += __shfl_xor(ss, 16); ss += __shfl_xor(ss, 32);
;           if (fq_e == 0) epi.rowsum(g, rig, nt * 2 + wc_e, ss);
;         } else {
; #pragma unroll
;           for (int n = 0; n < 8; ++n) {
;             const int col = nt * 256 + wc_e * 128 + n * 16 + fq_e * 4;
;             if (col < N) epi.c4(g, rig, col, acc[m][n]);
;           }
;         }
	v_fma_f32 v66, v66, v208, v240
	v_fma_f32 v67, v67, v209, v241
	v_fma_f32 v68, v68, v210, v242
	v_fma_f32 v77, v69, v211, v243
	v_cvt_pk_bf16_f32 v66, v66, v67
	v_cvt_pk_bf16_f32 v67, v68, v77
	v_lshl_add_u64 v[68:69], v[78:79], 1, s[20:21]
	global_store_dwordx2 v[68:69], v[66:67], off offset:224
	v_or_b32_e32 v66, 32, v136
	v_ashrrev_i32_e32 v67, 31, v66
	v_lshlrev_b64 v[66:67], 10, v[66:67]
	v_lshl_add_u64 v[66:67], v[66:67], 0, v[138:139]
	v_lshl_add_u64 v[76:77], v[66:67], 0, v[132:133]
	v_lshl_add_u64 v[244:245], v[66:67], 0, v[132:133]
	v_lshl_add_u64 v[244:245], v[244:245], 2, s[22:23]
	global_load_dwordx4 v[212:215], v[244:245], off nt
	global_load_dwordx4 v[216:219], v[244:245], off offset:64 nt
	global_load_dwordx4 v[220:223], v[244:245], off offset:128 nt
	global_load_dwordx4 v[224:227], v[244:245], off offset:192 nt
	global_load_dwordx4 v[228:231], v[244:245], off offset:256 nt
	global_load_dwordx4 v[232:235], v[244:245], off offset:320 nt
	global_load_dwordx4 v[236:239], v[244:245], off offset:384 nt
	global_load_dwordx4 v[240:243], v[244:245], off offset:448 nt
	v_add_f32_e32 v62, 0, v62
	v_add_f32_e32 v63, 0, v63
	v_add_f32_e32 v64, 0, v64
	v_add_f32_e32 v65, 0, v65
	s_waitcnt vmcnt(7)
	v_fma_f32 v62, v62, v180, v212
	v_fma_f32 v63, v63, v181, v213
	v_fma_f32 v64, v64, v182, v214
	v_fma_f32 v75, v65, v183, v215
	v_cvt_pk_bf16_f32 v62, v62, v63
	v_cvt_pk_bf16_f32 v63, v64, v75
	v_lshl_add_u64 v[64:65], v[76:77], 1, s[20:21]
	global_store_dwordx2 v[64:65], v[62:63], off
	v_lshl_add_u64 v[72:73], v[66:67], 0, v[132:133]
	v_add_f32_e32 v58, 0, v58
	v_add_f32_e32 v59, 0, v59
	v_add_f32_e32 v60, 0, v60
	v_add_f32_e32 v61, 0, v61
	s_waitcnt vmcnt(7)
	v_fma_f32 v58, v58, v184, v216
	v_fma_f32 v59, v59, v185, v217
	v_fma_f32 v60, v60, v186, v218
	v_fma_f32 v71, v61, v187, v219
	v_cvt_pk_bf16_f32 v58, v58, v59
	v_cvt_pk_bf16_f32 v59, v60, v71
	v_lshl_add_u64 v[60:61], v[72:73], 1, s[20:21]
	global_store_dwordx2 v[60:61], v[58:59], off offset:32
	v_lshl_add_u64 v[68:69], v[66:67], 0, v[132:133]
	v_add_f32_e32 v54, 0, v54
	v_add_f32_e32 v55, 0, v55
	v_add_f32_e32 v56, 0, v56
	v_add_f32_e32 v57, 0, v57
	s_waitcnt vmcnt(7)
	v_fma_f32 v54, v54, v188, v220
	v_fma_f32 v55, v55, v189, v221
	v_fma_f32 v56, v56, v190, v222
	v_fma_f32 v65, v57, v191, v223
	v_cvt_pk_bf16_f32 v54, v54, v55
	v_cvt_pk_bf16_f32 v55, v56, v65
	v_lshl_add_u64 v[56:57], v[68:69], 1, s[20:21]
	global_store_dwordx2 v[56:57], v[54:55], off offset:64
	v_lshl_add_u64 v[62:63], v[66:67], 0, v[132:133]
	v_add_f32_e32 v50, 0, v50
	v_add_f32_e32 v51, 0, v51
	v_add_f32_e32 v52, 0, v52
	v_add_f32_e32 v53, 0, v53
	s_waitcnt vmcnt(7)
	v_fma_f32 v50, v50, v192, v224
	v_fma_f32 v51, v51, v193, v225
	v_fma_f32 v52, v52, v194, v226
	v_fma_f32 v61, v53, v195, v227
	v_cvt_pk_bf16_f32 v50, v50, v51
	v_cvt_pk_bf16_f32 v51, v52, v61
	v_lshl_add_u64 v[52:53], v[62:63], 1, s[20:21]
	global_store_dwordx2 v[52:53], v[50:51], off offset:96
	v_lshl_add_u64 v[58:59], v[66:67], 0, v[132:133]
	v_add_f32_e32 v46, 0, v46
	v_add_f32_e32 v47, 0, v47
	v_add_f32_e32 v48, 0, v48
	v_add_f32_e32 v49, 0, v49
	s_waitcnt vmcnt(7)
	v_fma_f32 v46, v46, v196, v228
	v_fma_f32 v47, v47, v197, v229
	v_fma_f32 v48, v48, v198, v230
	v_fma_f32 v57, v49, v199, v231
	v_cvt_pk_bf16_f32 v46, v46, v47
	v_cvt_pk_bf16_f32 v47, v48, v57
	v_lshl_add_u64 v[48:49], v[58:59], 1, s[20:21]
	global_store_dwordx2 v[48:49], v[46:47], off offset:128
	v_lshl_add_u64 v[54:55], v[66:67], 0, v[132:133]
	v_add_f32_e32 v42, 0, v42
	v_add_f32_e32 v43, 0, v43
	v_add_f32_e32 v44, 0, v44
	v_add_f32_e32 v45, 0, v45
	s_waitcnt vmcnt(7)
	v_fma_f32 v42, v42, v200, v232
	v_fma_f32 v43, v43, v201, v233
	v_fma_f32 v44, v44, v202, v234
	v_fma_f32 v53, v45, v203, v235
	v_cvt_pk_bf16_f32 v42, v42, v43
	v_cvt_pk_bf16_f32 v43, v44, v53
	v_lshl_add_u64 v[44:45], v[54:55], 1, s[20:21]
	global_store_dwordx2 v[44:45], v[42:43], off offset:160
	v_lshl_add_u64 v[50:51], v[66:67], 0, v[132:133]
	v_add_f32_e32 v38, 0, v38
	v_add_f32_e32 v39, 0, v39
	v_add_f32_e32 v40, 0, v40
	v_add_f32_e32 v41, 0, v41
	s_waitcnt vmcnt(7)
	v_fma_f32 v38, v38, v204, v236
	v_fma_f32 v39, v39, v205, v237
	v_fma_f32 v40, v40, v206, v238
	v_fma_f32 v49, v41, v207, v239
	v_cvt_pk_bf16_f32 v38, v38, v39
	v_cvt_pk_bf16_f32 v39, v40, v49
	v_lshl_add_u64 v[40:41], v[50:51], 1, s[20:21]
	global_store_dwordx2 v[40:41], v[38:39], off offset:192
	v_lshl_add_u64 v[46:47], v[66:67], 0, v[132:133]
	v_add_f32_e32 v34, 0, v34
	v_add_f32_e32 v35, 0, v35
	v_add_f32_e32 v36, 0, v36
	v_add_f32_e32 v37, 0, v37
	s_waitcnt vmcnt(7)
; __device__ __forceinline__ unsigned pack2(float a, float b) { unsigned r; asm("v_cvt_pk_bf16_f32 %0, %1, %2" : "=v"(r) : "v"(a), "v"(b)); return r; }
; __device__ __forceinline__ float bf2f(bf16_t h) { return __uint_as_float(((unsigned)h) << 16); }
;   __device__ __forceinline__ void c4(int g, int rig, int col, f32x4 v) const {
;     const size_t o = ((size_t)g * 2048 + rig) * 1024 + col;
;     f32x4 bs;
;     if (BASE_F32) bs = __builtin_nontemporal_load((const f32x4*)((const float*)base + o));
;     else {
;       const uint2 u = *(const uint2*)((const bf16_t*)base + o);
;       bs[0] = bf2f((bf16_t)(u.x & 0xffff)); bs[1] = bf2f((bf16_t)(u.x >> 16)); bs[2] = bf2f((bf16_t)(u.y & 0xffff)); bs[3] = bf2f((bf16_t)(u.y >> 16));
;     }
;     const f32x4 gt = *(const f32x4*)(gate + (size_t)g * 6144 + col);
;     f32x4 bi = {0.f, 0.f, 0.f, 0.f};
;     if (bias) bi = *(const f32x4*)(bias + col);
;     f32x4 r;
; #pragma unroll
;     for (int j = 0; j < 4; ++j) r[j] = bs[j] + gt[j] * (v[j] + bi[j]);
;     uint2 w; w.x = pack2(r[0], r[1]); w.y = pack2(r[2], r[3]);
;     *(uint2*)(X16 + o) = w;
;   }
; template <bool SWAP, class Epi, bool THIN = false> ...
;     ...
;     if constexpr (Epi::KIND == 0) {
; #pragma unroll
;       for (int m = 0; m < 4; ++m) {
;         const int rig = rig0 + rw + m * 16 + fr_e;
;         if constexpr (Epi::ROWSUM) {
;           float ss = 0.f;
; #pragma unroll
;           for (int n = 0; n < 8; ++n) {
;             const int col = nt * 256 + wc_e * 128 + n * 16 + fq_e * 4;
;             if (col < N) ss += epi.c4(g, rig, col, acc[m][n]);
;           }
;           ss += __shfl_xor(ss, 16); ss += __shfl_xor(ss, 32);
;           if (fq_e == 0) epi.rowsum(g, rig, nt * 2 + wc_e, ss);
;         } else {
; #pragma unroll
;           for (int n = 0; n < 8; ++n) {
;             const int col = nt * 256 + wc_e * 128 + n * 16 + fq_e * 4;
;             if (col < N) epi.c4(g, rig, col, acc[m][n]);
;           }
;         }
	v_fma_f32 v34, v34, v208, v240
	v_fma_f32 v35, v35, v209, v241
	v_fma_f32 v36, v36, v210, v242
	v_fma_f32 v45, v37, v211, v243
	v_cvt_pk_bf16_f32 v34, v34, v35
	v_cvt_pk_bf16_f32 v35, v36, v45
	v_lshl_add_u64 v[36:37], v[46:47], 1, s[20:21]
	global_store_dwordx2 v[36:37], v[34:35], off offset:224
	v_or_b32_e32 v34, 48, v136
	v_ashrrev_i32_e32 v35, 31, v34
	v_lshlrev_b64 v[34:35], 10, v[34:35]
	v_lshl_add_u64 v[34:35], v[34:35], 0, v[138:139]
	v_lshl_add_u64 v[44:45], v[34:35], 0, v[132:133]
	v_lshl_add_u64 v[244:245], v[34:35], 0, v[132:133]
	v_lshl_add_u64 v[244:245], v[244:245], 2, s[22:23]
	global_load_dwordx4 v[212:215], v[244:245], off nt
	global_load_dwordx4 v[216:219], v[244:245], off offset:64 nt
	global_load_dwordx4 v[220:223], v[244:245], off offset:128 nt
	global_load_dwordx4 v[224:227], v[244:245], off offset:192 nt
	global_load_dwordx4 v[228:231], v[244:245], off offset:256 nt
	global_load_dwordx4 v[232:235], v[244:245], off offset:320 nt
	global_load_dwordx4 v[236:239], v[244:245], off offset:384 nt
	global_load_dwordx4 v[240:243], v[244:245], off offset:448 nt
	v_add_f32_e32 v30, 0, v30
	v_add_f32_e32 v31, 0, v31
	v_add_f32_e32 v32, 0, v32
	v_add_f32_e32 v33, 0, v33
	s_waitcnt vmcnt(7)
	v_fma_f32 v30, v30, v180, v212
	v_fma_f32 v31, v31, v181, v213
	v_fma_f32 v32, v32, v182, v214
	v_fma_f32 v43, v33, v183, v215
	v_cvt_pk_bf16_f32 v30, v30, v31
	v_cvt_pk_bf16_f32 v31, v32, v43
	v_lshl_add_u64 v[32:33], v[44:45], 1, s[20:21]
	global_store_dwordx2 v[32:33], v[30:31], off
	v_lshl_add_u64 v[40:41], v[34:35], 0, v[132:133]
	v_add_f32_e32 v26, 0, v26
	v_add_f32_e32 v27, 0, v27
	v_add_f32_e32 v28, 0, v28
	v_add_f32_e32 v29, 0, v29
	s_waitcnt vmcnt(7)
	v_fma_f32 v26, v26, v184, v216
	v_fma_f32 v27, v27, v185, v217
	v_fma_f32 v28, v28, v186, v218
	v_fma_f32 v39, v29, v187, v219
	v_cvt_pk_bf16_f32 v26, v26, v27
	v_cvt_pk_bf16_f32 v27, v28, v39
	v_lshl_add_u64 v[28:29], v[40:41], 1, s[20:21]
	global_store_dwordx2 v[28:29], v[26:27], off offset:32
	v_lshl_add_u64 v[36:37], v[34:35], 0, v[132:133]
	v_add_f32_e32 v22, 0, v22
	v_add_f32_e32 v23, 0, v23
	v_add_f32_e32 v24, 0, v24
	v_add_f32_e32 v25, 0, v25
	s_waitcnt vmcnt(7)
	v_fma_f32 v22, v22, v188, v220
	v_fma_f32 v23, v23, v189, v221
	v_fma_f32 v24, v24, v190, v222
	v_fma_f32 v33, v25, v191, v223
	v_cvt_pk_bf16_f32 v22, v22, v23
	v_cvt_pk_bf16_f32 v23, v24, v33
	v_lshl_add_u64 v[24:25], v[36:37], 1, s[20:21]
	global_store_dwordx2 v[24:25], v[22:23], off offset:64
	v_lshl_add_u64 v[30:31], v[34:35], 0, v[132:133]
	v_add_f32_e32 v18, 0, v18
	v_add_f32_e32 v19, 0, v19
	v_add_f32_e32 v20, 0, v20
	v_add_f32_e32 v21, 0, v21
	s_waitcnt vmcnt(7)
	v_fma_f32 v18, v18, v192, v224
	v_fma_f32 v19, v19, v193, v225
	v_fma_f32 v20, v20, v194, v226
	v_fma_f32 v29, v21, v195, v227
	v_cvt_pk_bf16_f32 v18, v18, v19
	v_cvt_pk_bf16_f32 v19, v20, v29
	v_lshl_add_u64 v[20:21], v[30:31], 1, s[20:21]
	global_store_dwordx2 v[20:21], v[18:19], off offset:96
	v_lshl_add_u64 v[26:27], v[34:35], 0, v[132:133]
	v_add_f32_e32 v14, 0, v14
	v_add_f32_e32 v15, 0, v15
	v_add_f32_e32 v16, 0, v16
	v_add_f32_e32 v17, 0, v17
	s_waitcnt vmcnt(7)
	v_fma_f32 v14, v14, v196, v228
	v_fma_f32 v15, v15, v197, v229
	v_fma_f32 v16, v16, v198, v230
	v_fma_f32 v25, v17, v199, v231
	v_cvt_pk_bf16_f32 v14, v14, v15
	v_cvt_pk_bf16_f32 v15, v16, v25
	v_lshl_add_u64 v[16:17], v[26:27], 1, s[20:21]
	global_store_dwordx2 v[16:17], v[14:15], off offset:128
	v_lshl_add_u64 v[22:23], v[34:35], 0, v[132:133]
	v_add_f32_e32 v6, 0, v6
	v_add_f32_e32 v7, 0, v7
	v_add_f32_e32 v8, 0, v8
	v_add_f32_e32 v9, 0, v9
	s_waitcnt vmcnt(7)
	v_fma_f32 v6, v6, v200, v232
	v_fma_f32 v7, v7, v201, v233
	v_fma_f32 v8, v8, v202, v234
	v_fma_f32 v21, v9, v203, v235
	v_cvt_pk_bf16_f32 v6, v6, v7
	v_cvt_pk_bf16_f32 v7, v8, v21
	v_lshl_add_u64 v[8:9], v[22:23], 1, s[20:21]
	global_store_dwordx2 v[8:9], v[6:7], off offset:160
	v_lshl_add_u64 v[18:19], v[34:35], 0, v[132:133]
	v_add_f32_e32 v10, 0, v10
	v_add_f32_e32 v11, 0, v11
	v_add_f32_e32 v12, 0, v12
	v_add_f32_e32 v13, 0, v13
	s_waitcnt vmcnt(7)
	v_fma_f32 v6, v10, v204, v236
	v_fma_f32 v7, v11, v205, v237
	v_fma_f32 v8, v12, v206, v238
	v_fma_f32 v17, v13, v207, v239
	v_cvt_pk_bf16_f32 v6, v6, v7
	v_cvt_pk_bf16_f32 v7, v8, v17
	v_lshl_add_u64 v[8:9], v[18:19], 1, s[20:21]
	global_store_dwordx2 v[8:9], v[6:7], off offset:192
	v_lshl_add_u64 v[14:15], v[34:35], 0, v[132:133]
	v_add_f32_e32 v2, 0, v2
	v_add_f32_e32 v3, 0, v3
	v_add_f32_e32 v4, 0, v4
	v_add_f32_e32 v5, 0, v5
	s_waitcnt vmcnt(7)
	v_fma_f32 v2, v2, v208, v240
	v_fma_f32 v3, v3, v209, v241
	v_fma_f32 v4, v4, v210, v242
	v_fma_f32 v13, v5, v211, v243
	v_cvt_pk_bf16_f32 v2, v2, v3
	v_cvt_pk_bf16_f32 v3, v4, v13
	v_lshl_add_u64 v[4:5], v[14:15], 1, s[20:21]
	global_store_dwordx2 v[4:5], v[2:3], off offset:224
	s_branch .LBB0_2114

; template <bool SWAP, class Epi, bool THIN = false> ...
;     ...
;     for (int st = 0; st < ns; ++st) {
;       asm volatile("s_waitcnt vmcnt(0)" ::: "memory");
;       __builtin_amdgcn_s_barrier();
;       asm volatile("" ::: "memory");
;       if (st + 1 < ns) {
;         char* nb = smem + ((st + 1) & 1) * 65536;
;         const int ko = (st + 1) * 64;
; #pragma unroll
;         for (int i = 0; i < 4; ++i) { GLDS16(A + (size_t)(ap[i] + ko), nb + tid * 16 + i * 8192); GLDS16(Bt + (size_t)(bp[i] + ko), nb + 32768 + tid * 16 + i * 8192); }
;       }
;       const char* sa = smem + (st & 1) * 65536 + (wr * 64 + fr) * 128;
;       const char* sb = smem + (st & 1) * 65536 + 32768 + (wc * 128 + fr) * 128;
;       if constexpr (THIN) {
;         if (wc == 0) {
; #pragma unroll
;           for (int ks = 0; ks < 2; ++ks) {
;             bf16x8 af[4], bf[2];
; #pragma unroll
;             for (int m = 0; m < 4; ++m) af[m] = *(const bf16x8*)(sa + m * 2048 + (((ks * 4 + fq) ^ swz) << 4));
; #pragma unroll
;             for (int n = 0; n < 2; ++n) bf[n] = *(const bf16x8*)(sb + n * 2048 + (((ks * 4 + fq) ^ swz) << 4));
; #pragma unroll
;             for (int m = 0; m < 4; ++m)
; #pragma unroll
;               for (int n = 0; n < 2; ++n)
;                 acc[m][n] = SWAP ? __builtin_amdgcn_mfma_f32_16x16x32_bf16(bf[n], af[m], acc[m][n], 0, 0, 0)
;                                  : __builtin_amdgcn_mfma_f32_16x16x32_bf16(af[m], bf[n], acc[m][n], 0, 0, 0);
;           }
;         }
;       } else {
;       bf16x8 afA[4], afB[4], bfb[2][2];
; #pragma unroll
;       for (int m = 0; m < 4; ++m) afA[m] = *(const bf16x8*)(sa + m * 2048 + ((fq ^ swz) << 4));
; #pragma unroll
;       for (int n = 0; n < 2; ++n) bfb[0][n] = *(const bf16x8*)(sb + n * 2048 + ((fq ^ swz) << 4));
; #pragma unroll
;       for (int gq = 0; gq < 8; ++gq) {
;         const int ks = gq >> 2, nh = gq & 3;
;         if (gq < 7) {
;           const int ks2 = (gq + 1) >> 2, nh2 = (gq + 1) & 3;
; #pragma unroll
;           for (int n = 0; n < 2; ++n) bfb[(gq + 1) & 1][n] = *(const bf16x8*)(sb + (nh2 * 2 + n) * 2048 + (((ks2 * 4 + fq) ^ swz) << 4));
;         }
;         if (gq == 3) {
; #pragma unroll
;           for (int m = 0; m < 4; ++m) afB[m] = *(const bf16x8*)(sa + m * 2048 + (((4 + fq) ^ swz) << 4));
;         }
;         __builtin_amdgcn_sched_barrier(0);
; #pragma unroll
.LBB0_2429:
	s_add_i32 s9, s7, 0x10000
	s_and_b32 s8, s9, 0x10000
	v_add_u32_e32 v139, s8, v144
	s_nop 0
	v_readfirstlane_b32 s10, v139
	s_waitcnt vmcnt(0)
	s_barrier
	s_and_b32 s7, s7, 0x10000
	v_add_u32_e32 v130, s7, v145
	v_add_u32_e32 v139, v130, v147
	ds_read_b128 v[168:171], v139
	ds_read_b128 v[172:175], v139 offset:2048
	ds_read_b128 v[176:179], v139 offset:4096
	ds_read_b128 v[180:183], v139 offset:6144
	v_or_b32_e32 v139, s7, v146
	v_add_u32_e32 v141, v139, v147
	ds_read_b128 v[184:187], v141 offset:32768
	ds_read_b128 v[188:191], v141 offset:34816
	ds_read_b128 v[192:195], v141 offset:36864
	ds_read_b128 v[196:199], v141 offset:38912
	v_add_u32_e32 v130, v130, v148
	s_waitcnt lgkmcnt(3)
	v_mfma_f32_16x16x32_bf16 v[126:129], v[184:187], v[168:171], v[126:129]
	s_mov_b32 m0, s10
	v_mfma_f32_16x16x32_bf16 v[110:113], v[184:187], v[172:175], v[110:113]
	global_load_lds_dwordx4 v138, s[22:23]
	v_add_u32_e32 v138, 0x80, v138
	v_mfma_f32_16x16x32_bf16 v[82:85], v[184:187], v[176:179], v[82:85]
	v_mfma_f32_16x16x32_bf16 v[50:53], v[184:187], v[180:183], v[50:53]
	ds_read_b128 v[184:187], v141 offset:40960
	ds_read_b128 v[200:203], v141 offset:43008
	s_waitcnt lgkmcnt(4)
	v_mfma_f32_16x16x32_bf16 v[122:125], v[188:191], v[168:171], v[122:125]
	s_add_u32 m0, s10, 0x8000
	v_mfma_f32_16x16x32_bf16 v[106:109], v[188:191], v[172:175], v[106:109]
	global_load_lds_dwordx4 v137, s[18:19]
	v_add_u32_e32 v137, 0x80, v137
	v_mfma_f32_16x16x32_bf16 v[78:81], v[188:191], v[176:179], v[78:81]
	v_mfma_f32_16x16x32_bf16 v[38:41], v[188:191], v[180:183], v[38:41]
	s_waitcnt lgkmcnt(3)
	v_mfma_f32_16x16x32_bf16 v[118:121], v[192:195], v[168:171], v[118:121]
	s_add_u32 m0, s10, 0x2000
	v_mfma_f32_16x16x32_bf16 v[94:97], v[192:195], v[172:175], v[94:97]
	global_load_lds_dwordx4 v136, s[22:23]
	v_add_u32_e32 v136, 0x80, v136
	v_mfma_f32_16x16x32_bf16 v[58:61], v[192:195], v[176:179], v[58:61]
	v_mfma_f32_16x16x32_bf16 v[26:29], v[192:195], v[180:183], v[26:29]
	ds_read_b128 v[188:191], v141 offset:45056
	ds_read_b128 v[192:195], v141 offset:47104
	s_waitcnt lgkmcnt(4)
	v_mfma_f32_16x16x32_bf16 v[114:117], v[196:199], v[168:171], v[114:117]
	s_add_u32 m0, s10, 0xa000
	v_mfma_f32_16x16x32_bf16 v[86:89], v[196:199], v[172:175], v[86:89]
	global_load_lds_dwordx4 v135, s[18:19]
	v_add_u32_e32 v135, 0x80, v135
	v_mfma_f32_16x16x32_bf16 v[54:57], v[196:199], v[176:179], v[54:57]
	v_mfma_f32_16x16x32_bf16 v[22:25], v[196:199], v[180:183], v[22:25]
	v_add_u32_e32 v139, v139, v148
	s_waitcnt lgkmcnt(3)
	v_mfma_f32_16x16x32_bf16 v[102:105], v[184:187], v[168:171], v[102:105]
	ds_read_b128 v[196:199], v139 offset:32768
	ds_read_b128 v[204:207], v139 offset:34816
	s_add_u32 m0, s10, 0x4000
	v_mfma_f32_16x16x32_bf16 v[74:77], v[184:187], v[172:175], v[74:77]
	global_load_lds_dwordx4 v134, s[22:23]
	v_add_u32_e32 v134, 0x80, v134
	v_mfma_f32_16x16x32_bf16 v[46:49], v[184:187], v[176:179], v[46:49]
	v_mfma_f32_16x16x32_bf16 v[10:13], v[184:187], v[180:183], v[10:13]
	ds_read_b128 v[184:187], v130
	ds_read_b128 v[208:211], v130 offset:2048
	ds_read_b128 v[212:215], v130 offset:4096
	ds_read_b128 v[216:219], v130 offset:6144
	s_waitcnt lgkmcnt(8)
	v_mfma_f32_16x16x32_bf16 v[98:101], v[200:203], v[168:171], v[98:101]
	s_add_u32 m0, s10, 0xc000
	v_mfma_f32_16x16x32_bf16 v[66:69], v[200:203], v[172:175], v[66:69]
	global_load_lds_dwordx4 v133, s[18:19]
	v_add_u32_e32 v133, 0x80, v133
	v_mfma_f32_16x16x32_bf16 v[34:37], v[200:203], v[176:179], v[34:37]
	v_mfma_f32_16x16x32_bf16 v[6:9], v[200:203], v[180:183], v[6:9]
	s_waitcnt lgkmcnt(7)
	v_mfma_f32_16x16x32_bf16 v[70:73], v[188:191], v[168:171], v[70:73]
	s_add_u32 m0, s10, 0x6000
	s_waitcnt lgkmcnt(6)
	v_mfma_f32_16x16x32_bf16 v[62:65], v[192:195], v[168:171], v[62:65]
	global_load_lds_dwordx4 v132, s[22:23]
	v_add_u32_e32 v132, 0x80, v132
	v_mfma_f32_16x16x32_bf16 v[42:45], v[188:191], v[172:175], v[42:45]
	v_mfma_f32_16x16x32_bf16 v[30:33], v[192:195], v[172:175], v[30:33]
	ds_read_b128 v[168:171], v139 offset:36864
	ds_read_b128 v[172:175], v139 offset:38912
	v_mfma_f32_16x16x32_bf16 v[18:21], v[188:191], v[176:179], v[18:21]
	s_add_u32 m0, s10, 0xe000
	v_mfma_f32_16x16x32_bf16 v[14:17], v[192:195], v[176:179], v[14:17]
	global_load_lds_dwordx4 v140, s[18:19]
	v_add_u32_e32 v140, 0x80, v140
	v_mfma_f32_16x16x32_bf16 v[2:5], v[188:191], v[180:183], v[2:5]
	v_mfma_f32_16x16x32_bf16 v[90:93], v[192:195], v[180:183], v[90:93]
	ds_read_b128 v[176:179], v139 offset:40960
	ds_read_b128 v[180:183], v139 offset:43008
	s_waitcnt lgkmcnt(7)
	v_mfma_f32_16x16x32_bf16 v[126:129], v[196:199], v[184:187], v[126:129]
	v_mfma_f32_16x16x32_bf16 v[122:125], v[204:207], v[184:187], v[122:125]
	s_waitcnt lgkmcnt(6)
	v_mfma_f32_16x16x32_bf16 v[110:113], v[196:199], v[208:211], v[110:113]
	v_mfma_f32_16x16x32_bf16 v[106:109], v[204:207], v[208:211], v[106:109]
	s_waitcnt lgkmcnt(5)
	v_mfma_f32_16x16x32_bf16 v[82:85], v[196:199], v[212:215], v[82:85]
	v_mfma_f32_16x16x32_bf16 v[78:81], v[204:207], v[212:215], v[78:81]
	s_waitcnt lgkmcnt(4)
	v_mfma_f32_16x16x32_bf16 v[50:53], v[196:199], v[216:219], v[50:53]
	v_mfma_f32_16x16x32_bf16 v[38:41], v[204:207], v[216:219], v[38:41]
	s_waitcnt lgkmcnt(3)
	v_mfma_f32_16x16x32_bf16 v[118:121], v[168:171], v[184:187], v[118:121]
	v_mfma_f32_16x16x32_bf16 v[94:97], v[168:171], v[208:211], v[94:97]
	v_mfma_f32_16x16x32_bf16 v[58:61], v[168:171], v[212:215], v[58:61]
	v_mfma_f32_16x16x32_bf16 v[26:29], v[168:171], v[216:219], v[26:29]
	ds_read_b128 v[168:171], v139 offset:45056
	ds_read_b128 v[188:191], v139 offset:47104
	s_waitcnt lgkmcnt(4)
; template <bool SWAP, class Epi, bool THIN = false> ...
;     ...
;     for (int st = 0; st < ns; ++st) {
;       asm volatile("s_waitcnt vmcnt(0)" ::: "memory");
;       __builtin_amdgcn_s_barrier();
;       asm volatile("" ::: "memory");
;       if (st + 1 < ns) {
;         char* nb = smem + ((st + 1) & 1) * 65536;
;         const int ko = (st + 1) * 64;
; #pragma unroll
;         for (int i = 0; i < 4; ++i) { GLDS16(A + (size_t)(ap[i] + ko), nb + tid * 16 + i * 8192); GLDS16(Bt + (size_t)(bp[i] + ko), nb + 32768 + tid * 16 + i * 8192); }
;       }
;       const char* sa = smem + (st & 1) * 65536 + (wr * 64 + fr) * 128;
;       const char* sb = smem + (st & 1) * 65536 + 32768 + (wc * 128 + fr) * 128;
;       if constexpr (THIN) {
;         if (wc == 0) {
; #pragma unroll
;           for (int ks = 0; ks < 2; ++ks) {
;             bf16x8 af[4], bf[2];
; #pragma unroll
;             for (int m = 0; m < 4; ++m) af[m] = *(const bf16x8*)(sa + m * 2048 + (((ks * 4 + fq) ^ swz) << 4));
; #pragma unroll
;             for (int n = 0; n < 2; ++n) bf[n] = *(const bf16x8*)(sb + n * 2048 + (((ks * 4 + fq) ^ swz) << 4));
; #pragma unroll
;             for (int m = 0; m < 4; ++m)
; #pragma unroll
;               for (int n = 0; n < 2; ++n)
;                 acc[m][n] = SWAP ? __builtin_amdgcn_mfma_f32_16x16x32_bf16(bf[n], af[m], acc[m][n], 0, 0, 0)
;                                  : __builtin_amdgcn_mfma_f32_16x16x32_bf16(af[m], bf[n], acc[m][n], 0, 0, 0);
;           }
;         }
;       } else {
;       bf16x8 afA[4], afB[4], bfb[2][2];
; #pragma unroll
;       for (int m = 0; m < 4; ++m) afA[m] = *(const bf16x8*)(sa + m * 2048 + ((fq ^ swz) << 4));
; #pragma unroll
;       for (int n = 0; n < 2; ++n) bfb[0][n] = *(const bf16x8*)(sb + n * 2048 + ((fq ^ swz) << 4));
; #pragma unroll
;       for (int gq = 0; gq < 8; ++gq) {
;         const int ks = gq >> 2, nh = gq & 3;
;         if (gq < 7) {
;           const int ks2 = (gq + 1) >> 2, nh2 = (gq + 1) & 3;
; #pragma unroll
;           for (int n = 0; n < 2; ++n) bfb[(gq + 1) & 1][n] = *(const bf16x8*)(sb + (nh2 * 2 + n) * 2048 + (((ks2 * 4 + fq) ^ swz) << 4));
;         }
;         if (gq == 3) {
; #pragma unroll
;           for (int m = 0; m < 4; ++m) afB[m] = *(const bf16x8*)(sa + m * 2048 + (((4 + fq) ^ swz) << 4));
;         }
;         __builtin_amdgcn_sched_barrier(0);
; #pragma unroll
	v_mfma_f32_16x16x32_bf16 v[114:117], v[172:175], v[184:187], v[114:117]
	v_mfma_f32_16x16x32_bf16 v[86:89], v[172:175], v[208:211], v[86:89]
	v_mfma_f32_16x16x32_bf16 v[54:57], v[172:175], v[212:215], v[54:57]
	v_mfma_f32_16x16x32_bf16 v[22:25], v[172:175], v[216:219], v[22:25]
	s_waitcnt lgkmcnt(3)
	v_mfma_f32_16x16x32_bf16 v[102:105], v[176:179], v[184:187], v[102:105]
	s_waitcnt lgkmcnt(2)
	v_mfma_f32_16x16x32_bf16 v[98:101], v[180:183], v[184:187], v[98:101]
	v_mfma_f32_16x16x32_bf16 v[74:77], v[176:179], v[208:211], v[74:77]
	v_mfma_f32_16x16x32_bf16 v[66:69], v[180:183], v[208:211], v[66:69]
	v_mfma_f32_16x16x32_bf16 v[46:49], v[176:179], v[212:215], v[46:49]
	v_mfma_f32_16x16x32_bf16 v[34:37], v[180:183], v[212:215], v[34:37]
	v_mfma_f32_16x16x32_bf16 v[10:13], v[176:179], v[216:219], v[10:13]
	v_mfma_f32_16x16x32_bf16 v[6:9], v[180:183], v[216:219], v[6:9]
	s_waitcnt lgkmcnt(1)
	v_mfma_f32_16x16x32_bf16 v[70:73], v[168:171], v[184:187], v[70:73]
	s_add_i32 s6, s6, 64
	s_cmpk_eq_i32 s6, 0xac0
	s_mov_b32 s7, s9
	s_waitcnt lgkmcnt(0)
	v_mfma_f32_16x16x32_bf16 v[62:65], v[188:191], v[184:187], v[62:65]
	v_mfma_f32_16x16x32_bf16 v[42:45], v[168:171], v[208:211], v[42:45]
	v_mfma_f32_16x16x32_bf16 v[30:33], v[188:191], v[208:211], v[30:33]
	v_mfma_f32_16x16x32_bf16 v[18:21], v[168:171], v[212:215], v[18:21]
	v_mfma_f32_16x16x32_bf16 v[14:17], v[188:191], v[212:215], v[14:17]
	v_mfma_f32_16x16x32_bf16 v[2:5], v[168:171], v[216:219], v[2:5]
	v_mfma_f32_16x16x32_bf16 v[90:93], v[188:191], v[216:219], v[90:93]
	s_cbranch_scc0 .LBB0_2429
	v_add_u32_e32 v130, s8, v145
	s_waitcnt vmcnt(0)
	s_barrier
	v_add_u32_e32 v140, v130, v147
	ds_read_b128 v[132:135], v140
	ds_read_b128 v[136:139], v140 offset:2048
	ds_read_b128 v[168:171], v140 offset:4096
	ds_read_b128 v[172:175], v140 offset:6144
	v_add_u32_e32 v140, s8, v146
	v_add_u32_e32 v141, v140, v147
	ds_read_b128 v[176:179], v141 offset:32768
	ds_read_b128 v[180:183], v141 offset:34816
	ds_read_b128 v[184:187], v141 offset:36864
	ds_read_b128 v[188:191], v141 offset:38912
	v_add_u32_e32 v130, v130, v148
	s_waitcnt lgkmcnt(0)
	v_mfma_f32_16x16x32_bf16 v[126:129], v[176:179], v[132:135], v[126:129]
	v_mfma_f32_16x16x32_bf16 v[110:113], v[176:179], v[136:139], v[110:113]
	v_mfma_f32_16x16x32_bf16 v[82:85], v[176:179], v[168:171], v[82:85]
	v_mfma_f32_16x16x32_bf16 v[50:53], v[176:179], v[172:175], v[50:53]
	ds_read_b128 v[176:179], v141 offset:40960
	ds_read_b128 v[192:195], v141 offset:43008
	v_mfma_f32_16x16x32_bf16 v[122:125], v[180:183], v[132:135], v[122:125]
	v_mfma_f32_16x16x32_bf16 v[106:109], v[180:183], v[136:139], v[106:109]
	v_mfma_f32_16x16x32_bf16 v[78:81], v[180:183], v[168:171], v[78:81]
	v_mfma_f32_16x16x32_bf16 v[38:41], v[180:183], v[172:175], v[38:41]
	v_mfma_f32_16x16x32_bf16 v[118:121], v[184:187], v[132:135], v[118:121]
	v_mfma_f32_16x16x32_bf16 v[180:183], v[184:187], v[136:139], v[94:97]
	v_mfma_f32_16x16x32_bf16 v[200:203], v[184:187], v[168:171], v[58:61]
	v_mfma_f32_16x16x32_bf16 v[204:207], v[188:191], v[168:171], v[54:57]
	v_mfma_f32_16x16x32_bf16 v[184:187], v[184:187], v[172:175], v[26:29]
	s_nop 2
	ds_read_b128 v[26:29], v141 offset:45056
	ds_read_b128 v[54:57], v141 offset:47104
	v_mfma_f32_16x16x32_bf16 v[114:117], v[188:191], v[132:135], v[114:117]
	v_mfma_f32_16x16x32_bf16 v[196:199], v[188:191], v[136:139], v[86:89]
	v_mfma_f32_16x16x32_bf16 v[188:191], v[188:191], v[172:175], v[22:25]
	v_add_u32_e32 v140, v140, v148
	s_waitcnt lgkmcnt(0)
	v_mfma_f32_16x16x32_bf16 v[102:105], v[176:179], v[132:135], v[102:105]
	ds_read_b128 v[22:25], v140 offset:32768
	ds_read_b128 v[86:89], v140 offset:34816
	v_mfma_f32_16x16x32_bf16 v[74:77], v[176:179], v[136:139], v[74:77]
	v_mfma_f32_16x16x32_bf16 v[46:49], v[176:179], v[168:171], v[46:49]
	v_mfma_f32_16x16x32_bf16 v[10:13], v[176:179], v[172:175], v[10:13]
	ds_read_b128 v[176:179], v130
	ds_read_b128 v[208:211], v130 offset:2048
	ds_read_b128 v[212:215], v130 offset:4096
	ds_read_b128 v[216:219], v130 offset:6144
	v_mfma_f32_16x16x32_bf16 v[98:101], v[192:195], v[132:135], v[98:101]
	v_mfma_f32_16x16x32_bf16 v[66:69], v[192:195], v[136:139], v[66:69]
	v_mfma_f32_16x16x32_bf16 v[34:37], v[192:195], v[168:171], v[34:37]
	v_mfma_f32_16x16x32_bf16 v[6:9], v[192:195], v[172:175], v[6:9]
	v_mfma_f32_16x16x32_bf16 v[220:223], v[26:29], v[168:171], v[18:21]
	v_mfma_f32_16x16x32_bf16 v[168:171], v[54:57], v[168:171], v[14:17]
	s_nop 2
	ds_read_b128 v[14:17], v140 offset:36864
	ds_read_b128 v[18:21], v140 offset:38912
	v_mfma_f32_16x16x32_bf16 v[70:73], v[26:29], v[132:135], v[70:73]
	v_mfma_f32_16x16x32_bf16 v[132:135], v[54:57], v[132:135], v[62:65]
	v_mfma_f32_16x16x32_bf16 v[192:195], v[26:29], v[136:139], v[42:45]
	v_mfma_f32_16x16x32_bf16 v[136:139], v[54:57], v[136:139], v[30:33]
	v_mfma_f32_16x16x32_bf16 v[2:5], v[26:29], v[172:175], v[2:5]
	v_mfma_f32_16x16x32_bf16 v[172:175], v[54:57], v[172:175], v[90:93]
	ds_read_b128 v[224:227], v140 offset:40960
	ds_read_b128 v[228:231], v140 offset:43008
	s_waitcnt lgkmcnt(0)
	v_mfma_f32_16x16x32_bf16 v[126:129], v[22:25], v[176:179], v[126:129]
	v_mfma_f32_16x16x32_bf16 v[122:125], v[86:89], v[176:179], v[122:125]
	v_mfma_f32_16x16x32_bf16 v[94:97], v[22:25], v[208:211], v[110:113]
	v_mfma_f32_16x16x32_bf16 v[90:93], v[86:89], v[208:211], v[106:109]
	v_mfma_f32_16x16x32_bf16 v[62:65], v[22:25], v[212:215], v[82:85]
	v_mfma_f32_16x16x32_bf16 v[58:61], v[86:89], v[212:215], v[78:81]
	v_mfma_f32_16x16x32_bf16 v[30:33], v[22:25], v[216:219], v[50:53]
	v_mfma_f32_16x16x32_bf16 v[26:29], v[86:89], v[216:219], v[38:41]
	v_mfma_f32_16x16x32_bf16 v[86:89], v[14:17], v[208:211], v[180:183]
	v_mfma_f32_16x16x32_bf16 v[22:25], v[14:17], v[216:219], v[184:187]
	s_nop 1
	ds_read_b128 v[180:183], v140 offset:45056
	ds_read_b128 v[184:187], v140 offset:47104
	v_mfma_f32_16x16x32_bf16 v[118:121], v[14:17], v[176:179], v[118:121]
	v_mfma_f32_16x16x32_bf16 v[114:117], v[18:21], v[176:179], v[114:117]
	v_mfma_f32_16x16x32_bf16 v[82:85], v[18:21], v[208:211], v[196:199]
	v_mfma_f32_16x16x32_bf16 v[54:57], v[14:17], v[212:215], v[200:203]
	v_mfma_f32_16x16x32_bf16 v[50:53], v[18:21], v[212:215], v[204:207]
	v_mfma_f32_16x16x32_bf16 v[18:21], v[18:21], v[216:219], v[188:191]
	v_mfma_f32_16x16x32_bf16 v[110:113], v[224:227], v[176:179], v[102:105]
	v_mfma_f32_16x16x32_bf16 v[106:109], v[228:231], v[176:179], v[98:101]
	v_mfma_f32_16x16x32_bf16 v[78:81], v[224:227], v[208:211], v[74:77]
	v_mfma_f32_16x16x32_bf16 v[74:77], v[228:231], v[208:211], v[66:69]
	v_mfma_f32_16x16x32_bf16 v[46:49], v[224:227], v[212:215], v[46:49]
	v_mfma_f32_16x16x32_bf16 v[42:45], v[228:231], v[212:215], v[34:37]
	v_mfma_f32_16x16x32_bf16 v[14:17], v[224:227], v[216:219], v[10:13]
	v_mfma_f32_16x16x32_bf16 v[10:13], v[228:231], v[216:219], v[6:9]
	v_mov_b32_e32 v130, v1
	s_waitcnt vmcnt(0) lgkmcnt(0)
	s_barrier
; __device__ __forceinline__ int get_tid512() { int t = threadIdx.x; asm volatile("" : "+v"(t)); return t; }
; __device__ __forceinline__ unsigned pack2(float a, float b) { unsigned r; asm("v_cvt_pk_bf16_f32 %0, %1, %2" : "=v"(r) : "v"(a), "v"(b)); return r; }
; __device__ __forceinline__ float bf2f(bf16_t h) { return __uint_as_float(((unsigned)h) << 16); }
;   __device__ __forceinline__ void c4(int g, int rig, int col, f32x4 v) const {
;     const size_t o = ((size_t)g * 2048 + rig) * 1024 + col;
;     f32x4 bs;
;     if (BASE_F32) bs = __builtin_nontemporal_load((const f32x4*)((const float*)base + o));
;     else {
;       const uint2 u = *(const uint2*)((const bf16_t*)base + o);
;       bs[0] = bf2f((bf16_t)(u.x & 0xffff)); bs[1] = bf2f((bf16_t)(u.x >> 16)); bs[2] = bf2f((bf16_t)(u.y & 0xffff)); bs[3] = bf2f((bf16_t)(u.y >> 16));
;     }
;     const f32x4 gt = *(const f32x4*)(gate + (size_t)g * 6144 + col);
;     f32x4 bi = {0.f, 0.f, 0.f, 0.f};
;     if (bias) bi = *(const f32x4*)(bias + col);
;     f32x4 r;
; #pragma unroll
;     for (int j = 0; j < 4; ++j) r[j] = bs[j] + gt[j] * (v[j] + bi[j]);
;     uint2 w; w.x = pack2(r[0], r[1]); w.y = pack2(r[2], r[3]);
;     *(uint2*)(X16 + o) = w;
;   }
; template <bool SWAP, class Epi, bool THIN = false> ...
;     ...
;     const int te = get_tid512();
;     const int fr_e = te & 15, fq_e = (te & 63) >> 4, wr_e = te >> 7, wc_e = (te >> 6) & 1;
;     const int sub = 2 * mt + (wr_e >> 1);
;     const int g = sub / tpg, ti = sub - g * tpg;
;     const int rig0 = ti * step - halo;
;     const int rw = (wr_e & 1) * 64;
;     if constexpr (Epi::KIND == 0) {
; #pragma unroll
;       for (int m = 0; m < 4; ++m) {
;         const int rig = rig0 + rw + m * 16 + fr_e;
;         if constexpr (Epi::ROWSUM) {
;           float ss = 0.f;
; #pragma unroll
;           for (int n = 0; n < 8; ++n) {
;             const int col = nt * 256 + wc_e * 128 + n * 16 + fq_e * 4;
;             if (col < N) ss += epi.c4(g, rig, col, acc[m][n]);
;           }
;           ss += __shfl_xor(ss, 16); ss += __shfl_xor(ss, 32);
;           if (fq_e == 0) epi.rowsum(g, rig, nt * 2 + wc_e, ss);
;         } else {
; #pragma unroll
;           for (int n = 0; n < 8; ++n) {
;             const int col = nt * 256 + wc_e * 128 + n * 16 + fq_e * 4;
;             if (col < N) epi.c4(g, rig, col, acc[m][n]);
	v_mfma_f32_16x16x32_bf16 v[98:101], v[184:187], v[176:179], v[132:135]
	v_ashrrev_i32_e32 v7, 8, v130
	v_add_u32_e32 v7, s5, v7
	v_ashrrev_i32_e32 v8, 31, v7
	v_lshrrev_b32_e32 v8, 28, v8
	v_add_u32_e32 v8, v7, v8
	v_ashrrev_i32_e32 v134, 4, v8
	v_lshlrev_b32_e32 v8, 11, v134
	v_lshlrev_b32_e32 v7, 7, v7
	v_sub_u32_e32 v7, v7, v8
	v_lshrrev_b32_e32 v8, 1, v130
	v_and_b32_e32 v6, 15, v130
	v_and_b32_e32 v8, 64, v8
	v_mfma_f32_16x16x32_bf16 v[66:69], v[184:187], v[208:211], v[136:139]
	v_ashrrev_i32_e32 v135, 31, v134
	s_nop 1
	v_or3_b32 v136, v7, v8, v6
	v_lshlrev_b32_e32 v6, 1, v130
	v_and_b32_e32 v132, 0x80, v6
	v_mfma_f32_16x16x32_bf16 v[6:9], v[180:183], v[216:219], v[2:5]
	v_ashrrev_i32_e32 v137, 31, v136
	v_lshlrev_b64 v[138:139], 21, v[134:135]
	v_lshlrev_b64 v[140:141], 10, v[136:137]
	v_lshrrev_b32_e32 v2, 2, v130
	v_and_b32_e32 v2, 12, v2
	v_mfma_f32_16x16x32_bf16 v[102:105], v[180:183], v[176:179], v[70:73]
	v_or3_b32 v132, v2, v132, s4
	v_mad_i64_i32 v[134:135], s[4:5], v134, s31, 0
	v_mfma_f32_16x16x32_bf16 v[70:73], v[180:183], v[208:211], v[192:195]
	v_lshl_add_u64 v[140:141], v[140:141], 0, v[138:139]
	v_cmp_gt_i32_e32 vcc, s34, v132
	v_ashrrev_i32_e32 v133, 31, v132
	v_mfma_f32_16x16x32_bf16 v[38:41], v[180:183], v[212:215], v[220:223]
	v_lshl_add_u64 v[134:135], s[24:25], 0, v[134:135]
	v_lshl_add_u64 v[140:141], v[140:141], 1, s[20:21]
	v_mfma_f32_16x16x32_bf16 v[34:37], v[184:187], v[212:215], v[168:171]
	v_mfma_f32_16x16x32_bf16 v[2:5], v[184:187], v[216:219], v[172:175]
	v_lshl_add_u64 v[218:219], v[132:133], 2, v[134:135]
	global_load_dwordx4 v[198:201], v[218:219], off
	global_load_dwordx4 v[202:205], v[218:219], off offset:64
	global_load_dwordx4 v[206:209], v[218:219], off offset:128
	global_load_dwordx4 v[210:213], v[218:219], off offset:192
	global_load_dwordx4 v[214:217], v[218:219], off offset:256
	global_load_dwordx4 v[224:227], v[218:219], off offset:320
	global_load_dwordx4 v[228:231], v[218:219], off offset:384
	global_load_dwordx4 v[232:235], v[218:219], off offset:448
	s_nop 0
	v_lshl_add_u64 v[172:173], v[132:133], 1, v[140:141]
	v_lshl_add_u64 v[196:197], v[132:133], 1, v[140:141]
	global_load_dwordx2 v[176:177], v[196:197], off
	global_load_dwordx2 v[178:179], v[196:197], off offset:32
	global_load_dwordx2 v[180:181], v[196:197], off offset:64
	global_load_dwordx2 v[182:183], v[196:197], off offset:96
	global_load_dwordx2 v[184:185], v[196:197], off offset:128
	global_load_dwordx2 v[186:187], v[196:197], off offset:160
	global_load_dwordx2 v[188:189], v[196:197], off offset:192
	global_load_dwordx2 v[190:191], v[196:197], off offset:224
	v_add_f32_e32 v126, 0, v126
	v_add_f32_e32 v127, 0, v127
	v_add_f32_e32 v128, 0, v128
	v_add_f32_e32 v129, 0, v129
	s_waitcnt vmcnt(7)
	v_lshlrev_b32_e32 v130, 16, v176
	v_and_b32_e32 v137, 0xffff0000, v176
	v_lshlrev_b32_e32 v167, 16, v177
	v_and_b32_e32 v174, 0xffff0000, v177
	v_fmac_f32_e32 v130, v126, v198
	v_fmac_f32_e32 v137, v127, v199
	v_fmac_f32_e32 v167, v128, v200
	v_fmac_f32_e32 v174, v129, v201
	v_cvt_pk_bf16_f32 v126, v130, v137
	v_cvt_pk_bf16_f32 v127, v167, v174
	global_store_dwordx2 v[172:173], v[126:127], off
	v_or_b32_e32 v126, 16, v132
	v_lshl_add_u64 v[168:169], v[132:133], 1, v[140:141]
	v_add_f32_e32 v122, 0, v122
	v_add_f32_e32 v123, 0, v123
	v_add_f32_e32 v124, 0, v124
	v_add_f32_e32 v125, 0, v125
	s_waitcnt vmcnt(7)
	v_lshlrev_b32_e32 v130, 16, v178
	v_and_b32_e32 v137, 0xffff0000, v178
	v_lshlrev_b32_e32 v167, 16, v179
	v_and_b32_e32 v170, 0xffff0000, v179
	v_fmac_f32_e32 v130, v122, v202
	v_fmac_f32_e32 v137, v123, v203
	v_fmac_f32_e32 v167, v124, v204
	v_fmac_f32_e32 v170, v125, v205
	v_cvt_pk_bf16_f32 v122, v130, v137
	v_cvt_pk_bf16_f32 v123, v167, v170
	global_store_dwordx2 v[168:169], v[122:123], off offset:32
	v_or_b32_e32 v122, 32, v132
	v_lshl_add_u64 v[126:127], v[132:133], 1, v[140:141]
	v_add_f32_e32 v118, 0, v118
	v_add_f32_e32 v119, 0, v119
	v_add_f32_e32 v120, 0, v120
	v_add_f32_e32 v121, 0, v121
	s_waitcnt vmcnt(7)
	v_lshlrev_b32_e32 v130, 16, v180
	v_and_b32_e32 v128, 0xffff0000, v180
	v_lshlrev_b32_e32 v137, 16, v181
	v_and_b32_e32 v129, 0xffff0000, v181
	v_fmac_f32_e32 v130, v118, v206
	v_fmac_f32_e32 v128, v119, v207
	v_fmac_f32_e32 v137, v120, v208
	v_fmac_f32_e32 v129, v121, v209
	v_cvt_pk_bf16_f32 v118, v130, v128
	v_cvt_pk_bf16_f32 v119, v137, v129
	global_store_dwordx2 v[126:127], v[118:119], off offset:64
	v_or_b32_e32 v118, 48, v132
	v_lshl_add_u64 v[122:123], v[132:133], 1, v[140:141]
	v_add_f32_e32 v114, 0, v114
	v_add_f32_e32 v115, 0, v115
	v_add_f32_e32 v116, 0, v116
	v_add_f32_e32 v117, 0, v117
	s_waitcnt vmcnt(7)
	v_lshlrev_b32_e32 v126, 16, v182
	v_and_b32_e32 v124, 0xffff0000, v182
	v_lshlrev_b32_e32 v127, 16, v183
	v_and_b32_e32 v125, 0xffff0000, v183
	v_fmac_f32_e32 v126, v114, v210
	v_fmac_f32_e32 v124, v115, v211
	v_fmac_f32_e32 v127, v116, v212
	v_fmac_f32_e32 v125, v117, v213
	v_cvt_pk_bf16_f32 v114, v126, v124
	v_cvt_pk_bf16_f32 v115, v127, v125
	global_store_dwordx2 v[122:123], v[114:115], off offset:96
	v_or_b32_e32 v114, 64, v132
	v_lshl_add_u64 v[118:119], v[132:133], 1, v[140:141]
	v_add_f32_e32 v110, 0, v110
	v_add_f32_e32 v111, 0, v111
	v_add_f32_e32 v112, 0, v112
	v_add_f32_e32 v113, 0, v113
	s_waitcnt vmcnt(7)
	v_lshlrev_b32_e32 v122, 16, v184
	v_and_b32_e32 v120, 0xffff0000, v184
	v_lshlrev_b32_e32 v123, 16, v185
	v_and_b32_e32 v121, 0xffff0000, v185
	v_fmac_f32_e32 v122, v110, v214
	v_fmac_f32_e32 v120, v111, v215
	v_fmac_f32_e32 v123, v112, v216
	v_fmac_f32_e32 v121, v113, v217
	v_cvt_pk_bf16_f32 v110, v122, v120
	v_cvt_pk_bf16_f32 v111, v123, v121
	global_store_dwordx2 v[118:119], v[110:111], off offset:128
	v_or_b32_e32 v110, 0x50, v132
	v_lshl_add_u64 v[114:115], v[132:133], 1, v[140:141]
	v_add_f32_e32 v106, 0, v106
	v_add_f32_e32 v107, 0, v107
	v_add_f32_e32 v108, 0, v108
	v_add_f32_e32 v109, 0, v109
	s_waitcnt vmcnt(7)
; __device__ __forceinline__ unsigned pack2(float a, float b) { unsigned r; asm("v_cvt_pk_bf16_f32 %0, %1, %2" : "=v"(r) : "v"(a), "v"(b)); return r; }
; __device__ __forceinline__ float bf2f(bf16_t h) { return __uint_as_float(((unsigned)h) << 16); }
;   __device__ __forceinline__ void c4(int g, int rig, int col, f32x4 v) const {
;     const size_t o = ((size_t)g * 2048 + rig) * 1024 + col;
;     f32x4 bs;
;     if (BASE_F32) bs = __builtin_nontemporal_load((const f32x4*)((const float*)base + o));
;     else {
;       const uint2 u = *(const uint2*)((const bf16_t*)base + o);
;       bs[0] = bf2f((bf16_t)(u.x & 0xffff)); bs[1] = bf2f((bf16_t)(u.x >> 16)); bs[2] = bf2f((bf16_t)(u.y & 0xffff)); bs[3] = bf2f((bf16_t)(u.y >> 16));
;     }
;     const f32x4 gt = *(const f32x4*)(gate + (size_t)g * 6144 + col);
;     f32x4 bi = {0.f, 0.f, 0.f, 0.f};
;     if (bias) bi = *(const f32x4*)(bias + col);
;     f32x4 r;
; #pragma unroll
;     for (int j = 0; j < 4; ++j) r[j] = bs[j] + gt[j] * (v[j] + bi[j]);
;     uint2 w; w.x = pack2(r[0], r[1]); w.y = pack2(r[2], r[3]);
;     *(uint2*)(X16 + o) = w;
;   }
; template <bool SWAP, class Epi, bool THIN = false> ...
;     ...
; #pragma unroll
;       for (int m = 0; m < 4; ++m) {
;         const int rig = rig0 + rw + m * 16 + fr_e;
;         if constexpr (Epi::ROWSUM) {
;           float ss = 0.f;
; #pragma unroll
;           for (int n = 0; n < 8; ++n) {
;             const int col = nt * 256 + wc_e * 128 + n * 16 + fq_e * 4;
;             if (col < N) ss += epi.c4(g, rig, col, acc[m][n]);
;           }
;           ss += __shfl_xor(ss, 16); ss += __shfl_xor(ss, 32);
;           if (fq_e == 0) epi.rowsum(g, rig, nt * 2 + wc_e, ss);
;         } else {
; #pragma unroll
;           for (int n = 0; n < 8; ++n) {
;             const int col = nt * 256 + wc_e * 128 + n * 16 + fq_e * 4;
;             if (col < N) epi.c4(g, rig, col, acc[m][n]);
	v_lshlrev_b32_e32 v118, 16, v186
	v_and_b32_e32 v116, 0xffff0000, v186
	v_lshlrev_b32_e32 v119, 16, v187
	v_and_b32_e32 v117, 0xffff0000, v187
	v_fmac_f32_e32 v118, v106, v224
	v_fmac_f32_e32 v116, v107, v225
	v_fmac_f32_e32 v119, v108, v226
	v_fmac_f32_e32 v117, v109, v227
	v_cvt_pk_bf16_f32 v106, v118, v116
	v_cvt_pk_bf16_f32 v107, v119, v117
	global_store_dwordx2 v[114:115], v[106:107], off offset:160
	v_or_b32_e32 v106, 0x60, v132
	v_lshl_add_u64 v[110:111], v[132:133], 1, v[140:141]
	v_add_f32_e32 v102, 0, v102
	v_add_f32_e32 v103, 0, v103
	v_add_f32_e32 v104, 0, v104
	v_add_f32_e32 v105, 0, v105
	s_waitcnt vmcnt(7)
	v_lshlrev_b32_e32 v114, 16, v188
	v_and_b32_e32 v112, 0xffff0000, v188
	v_lshlrev_b32_e32 v115, 16, v189
	v_and_b32_e32 v113, 0xffff0000, v189
	v_fmac_f32_e32 v114, v102, v228
	v_fmac_f32_e32 v112, v103, v229
	v_fmac_f32_e32 v115, v104, v230
	v_fmac_f32_e32 v113, v105, v231
	v_cvt_pk_bf16_f32 v102, v114, v112
	v_cvt_pk_bf16_f32 v103, v115, v113
	global_store_dwordx2 v[110:111], v[102:103], off offset:192
	v_or_b32_e32 v102, 0x70, v132
	v_lshl_add_u64 v[106:107], v[132:133], 1, v[140:141]
	v_add_f32_e32 v98, 0, v98
	v_add_f32_e32 v99, 0, v99
	v_add_f32_e32 v100, 0, v100
	v_add_f32_e32 v101, 0, v101
	s_waitcnt vmcnt(7)
	v_lshlrev_b32_e32 v110, 16, v190
	v_and_b32_e32 v108, 0xffff0000, v190
	v_lshlrev_b32_e32 v111, 16, v191
	v_and_b32_e32 v109, 0xffff0000, v191
	v_fmac_f32_e32 v110, v98, v232
	v_fmac_f32_e32 v108, v99, v233
	v_fmac_f32_e32 v111, v100, v234
	v_fmac_f32_e32 v109, v101, v235
	v_cvt_pk_bf16_f32 v98, v110, v108
	v_cvt_pk_bf16_f32 v99, v111, v109
	global_store_dwordx2 v[106:107], v[98:99], off offset:224
	v_or_b32_e32 v98, 16, v136
	v_ashrrev_i32_e32 v99, 31, v98
	v_lshlrev_b64 v[98:99], 10, v[98:99]
	v_lshl_add_u64 v[98:99], v[98:99], 0, v[138:139]
	v_lshl_add_u64 v[98:99], v[98:99], 1, s[20:21]
	v_lshl_add_u64 v[104:105], v[132:133], 1, v[98:99]
	v_lshl_add_u64 v[196:197], v[132:133], 1, v[98:99]
	global_load_dwordx2 v[176:177], v[196:197], off
	global_load_dwordx2 v[178:179], v[196:197], off offset:32
	global_load_dwordx2 v[180:181], v[196:197], off offset:64
	global_load_dwordx2 v[182:183], v[196:197], off offset:96
	global_load_dwordx2 v[184:185], v[196:197], off offset:128
	global_load_dwordx2 v[186:187], v[196:197], off offset:160
	global_load_dwordx2 v[188:189], v[196:197], off offset:192
	global_load_dwordx2 v[190:191], v[196:197], off offset:224
	v_add_f32_e32 v94, 0, v94
	v_add_f32_e32 v95, 0, v95
	v_add_f32_e32 v96, 0, v96
	v_add_f32_e32 v97, 0, v97
	s_waitcnt vmcnt(7)
	v_lshlrev_b32_e32 v108, 16, v176
	v_and_b32_e32 v106, 0xffff0000, v176
	v_lshlrev_b32_e32 v109, 16, v177
	v_and_b32_e32 v107, 0xffff0000, v177
	v_fmac_f32_e32 v108, v94, v198
	v_fmac_f32_e32 v106, v95, v199
	v_fmac_f32_e32 v109, v96, v200
	v_fmac_f32_e32 v107, v97, v201
	v_cvt_pk_bf16_f32 v94, v108, v106
	v_cvt_pk_bf16_f32 v95, v109, v107
	global_store_dwordx2 v[104:105], v[94:95], off
	v_lshl_add_u64 v[100:101], v[132:133], 1, v[98:99]
	v_add_f32_e32 v90, 0, v90
	v_add_f32_e32 v91, 0, v91
	v_add_f32_e32 v92, 0, v92
	v_add_f32_e32 v93, 0, v93
	s_waitcnt vmcnt(7)
	v_lshlrev_b32_e32 v104, 16, v178
	v_and_b32_e32 v102, 0xffff0000, v178
	v_lshlrev_b32_e32 v105, 16, v179
	v_and_b32_e32 v103, 0xffff0000, v179
	v_fmac_f32_e32 v104, v90, v202
	v_fmac_f32_e32 v102, v91, v203
	v_fmac_f32_e32 v105, v92, v204
	v_fmac_f32_e32 v103, v93, v205
	v_cvt_pk_bf16_f32 v90, v104, v102
	v_cvt_pk_bf16_f32 v91, v105, v103
	global_store_dwordx2 v[100:101], v[90:91], off offset:32
	v_lshl_add_u64 v[94:95], v[132:133], 1, v[98:99]
	v_add_f32_e32 v86, 0, v86
	v_add_f32_e32 v87, 0, v87
	v_add_f32_e32 v88, 0, v88
	v_add_f32_e32 v89, 0, v89
	s_waitcnt vmcnt(7)
	v_lshlrev_b32_e32 v100, 16, v180
	v_and_b32_e32 v96, 0xffff0000, v180
	v_lshlrev_b32_e32 v101, 16, v181
	v_and_b32_e32 v97, 0xffff0000, v181
	v_fmac_f32_e32 v100, v86, v206
	v_fmac_f32_e32 v96, v87, v207
	v_fmac_f32_e32 v101, v88, v208
	v_fmac_f32_e32 v97, v89, v209
	v_cvt_pk_bf16_f32 v86, v100, v96
	v_cvt_pk_bf16_f32 v87, v101, v97
	global_store_dwordx2 v[94:95], v[86:87], off offset:64
	v_lshl_add_u64 v[90:91], v[132:133], 1, v[98:99]
	v_add_f32_e32 v82, 0, v82
	v_add_f32_e32 v83, 0, v83
	v_add_f32_e32 v84, 0, v84
	v_add_f32_e32 v85, 0, v85
	s_waitcnt vmcnt(7)
	v_lshlrev_b32_e32 v94, 16, v182
	v_and_b32_e32 v92, 0xffff0000, v182
	v_lshlrev_b32_e32 v95, 16, v183
	v_and_b32_e32 v93, 0xffff0000, v183
	v_fmac_f32_e32 v94, v82, v210
	v_fmac_f32_e32 v92, v83, v211
	v_fmac_f32_e32 v95, v84, v212
	v_fmac_f32_e32 v93, v85, v213
	v_cvt_pk_bf16_f32 v82, v94, v92
	v_cvt_pk_bf16_f32 v83, v95, v93
	global_store_dwordx2 v[90:91], v[82:83], off offset:96
	v_lshl_add_u64 v[86:87], v[132:133], 1, v[98:99]
	v_add_f32_e32 v78, 0, v78
	v_add_f32_e32 v79, 0, v79
	v_add_f32_e32 v80, 0, v80
	v_add_f32_e32 v81, 0, v81
	s_waitcnt vmcnt(7)
	v_lshlrev_b32_e32 v90, 16, v184
	v_and_b32_e32 v88, 0xffff0000, v184
	v_lshlrev_b32_e32 v91, 16, v185
	v_and_b32_e32 v89, 0xffff0000, v185
	v_fmac_f32_e32 v90, v78, v214
	v_fmac_f32_e32 v88, v79, v215
	v_fmac_f32_e32 v91, v80, v216
	v_fmac_f32_e32 v89, v81, v217
	v_cvt_pk_bf16_f32 v78, v90, v88
	v_cvt_pk_bf16_f32 v79, v91, v89
	global_store_dwordx2 v[86:87], v[78:79], off offset:128
	v_lshl_add_u64 v[82:83], v[132:133], 1, v[98:99]
	v_add_f32_e32 v74, 0, v74
	v_add_f32_e32 v75, 0, v75
	v_add_f32_e32 v76, 0, v76
	v_add_f32_e32 v77, 0, v77
	s_waitcnt vmcnt(7)
; __device__ __forceinline__ unsigned pack2(float a, float b) { unsigned r; asm("v_cvt_pk_bf16_f32 %0, %1, %2" : "=v"(r) : "v"(a), "v"(b)); return r; }
; __device__ __forceinline__ float bf2f(bf16_t h) { return __uint_as_float(((unsigned)h) << 16); }
;   __device__ __forceinline__ void c4(int g, int rig, int col, f32x4 v) const {
;     const size_t o = ((size_t)g * 2048 + rig) * 1024 + col;
;     f32x4 bs;
;     if (BASE_F32) bs = __builtin_nontemporal_load((const f32x4*)((const float*)base + o));
;     else {
;       const uint2 u = *(const uint2*)((const bf16_t*)base + o);
;       bs[0] = bf2f((bf16_t)(u.x & 0xffff)); bs[1] = bf2f((bf16_t)(u.x >> 16)); bs[2] = bf2f((bf16_t)(u.y & 0xffff)); bs[3] = bf2f((bf16_t)(u.y >> 16));
;     }
;     const f32x4 gt = *(const f32x4*)(gate + (size_t)g * 6144 + col);
;     f32x4 bi = {0.f, 0.f, 0.f, 0.f};
;     if (bias) bi = *(const f32x4*)(bias + col);
;     f32x4 r;
; #pragma unroll
;     for (int j = 0; j < 4; ++j) r[j] = bs[j] + gt[j] * (v[j] + bi[j]);
;     uint2 w; w.x = pack2(r[0], r[1]); w.y = pack2(r[2], r[3]);
;     *(uint2*)(X16 + o) = w;
;   }
; template <bool SWAP, class Epi, bool THIN = false> ...
;     ...
; #pragma unroll
;       for (int m = 0; m < 4; ++m) {
;         const int rig = rig0 + rw + m * 16 + fr_e;
;         if constexpr (Epi::ROWSUM) {
;           float ss = 0.f;
; #pragma unroll
;           for (int n = 0; n < 8; ++n) {
;             const int col = nt * 256 + wc_e * 128 + n * 16 + fq_e * 4;
;             if (col < N) ss += epi.c4(g, rig, col, acc[m][n]);
;           }
;           ss += __shfl_xor(ss, 16); ss += __shfl_xor(ss, 32);
;           if (fq_e == 0) epi.rowsum(g, rig, nt * 2 + wc_e, ss);
;         } else {
; #pragma unroll
;           for (int n = 0; n < 8; ++n) {
;             const int col = nt * 256 + wc_e * 128 + n * 16 + fq_e * 4;
;             if (col < N) epi.c4(g, rig, col, acc[m][n]);
	v_lshlrev_b32_e32 v86, 16, v186
	v_and_b32_e32 v84, 0xffff0000, v186
	v_lshlrev_b32_e32 v87, 16, v187
	v_and_b32_e32 v85, 0xffff0000, v187
	v_fmac_f32_e32 v86, v74, v224
	v_fmac_f32_e32 v84, v75, v225
	v_fmac_f32_e32 v87, v76, v226
	v_fmac_f32_e32 v85, v77, v227
	v_cvt_pk_bf16_f32 v74, v86, v84
	v_cvt_pk_bf16_f32 v75, v87, v85
	global_store_dwordx2 v[82:83], v[74:75], off offset:160
	v_lshl_add_u64 v[78:79], v[132:133], 1, v[98:99]
	v_add_f32_e32 v70, 0, v70
	v_add_f32_e32 v71, 0, v71
	v_add_f32_e32 v72, 0, v72
	v_add_f32_e32 v73, 0, v73
	s_waitcnt vmcnt(7)
	v_lshlrev_b32_e32 v82, 16, v188
	v_and_b32_e32 v80, 0xffff0000, v188
	v_lshlrev_b32_e32 v83, 16, v189
	v_and_b32_e32 v81, 0xffff0000, v189
	v_fmac_f32_e32 v82, v70, v228
	v_fmac_f32_e32 v80, v71, v229
	v_fmac_f32_e32 v83, v72, v230
	v_fmac_f32_e32 v81, v73, v231
	v_cvt_pk_bf16_f32 v70, v82, v80
	v_cvt_pk_bf16_f32 v71, v83, v81
	global_store_dwordx2 v[78:79], v[70:71], off offset:192
	v_lshl_add_u64 v[74:75], v[132:133], 1, v[98:99]
	v_add_f32_e32 v66, 0, v66
	v_add_f32_e32 v67, 0, v67
	v_add_f32_e32 v68, 0, v68
	v_add_f32_e32 v69, 0, v69
	s_waitcnt vmcnt(7)
	v_lshlrev_b32_e32 v78, 16, v190
	v_and_b32_e32 v76, 0xffff0000, v190
	v_lshlrev_b32_e32 v79, 16, v191
	v_and_b32_e32 v77, 0xffff0000, v191
	v_fmac_f32_e32 v78, v66, v232
	v_fmac_f32_e32 v76, v67, v233
	v_fmac_f32_e32 v79, v68, v234
	v_fmac_f32_e32 v77, v69, v235
	v_cvt_pk_bf16_f32 v66, v78, v76
	v_cvt_pk_bf16_f32 v67, v79, v77
	global_store_dwordx2 v[74:75], v[66:67], off offset:224
	v_or_b32_e32 v66, 32, v136
	v_ashrrev_i32_e32 v67, 31, v66
	v_lshlrev_b64 v[66:67], 10, v[66:67]
	v_lshl_add_u64 v[66:67], v[66:67], 0, v[138:139]
	v_lshl_add_u64 v[66:67], v[66:67], 1, s[20:21]
	v_lshl_add_u64 v[72:73], v[132:133], 1, v[66:67]
	v_lshl_add_u64 v[196:197], v[132:133], 1, v[66:67]
	global_load_dwordx2 v[176:177], v[196:197], off
	global_load_dwordx2 v[178:179], v[196:197], off offset:32
	global_load_dwordx2 v[180:181], v[196:197], off offset:64
	global_load_dwordx2 v[182:183], v[196:197], off offset:96
	global_load_dwordx2 v[184:185], v[196:197], off offset:128
	global_load_dwordx2 v[186:187], v[196:197], off offset:160
	global_load_dwordx2 v[188:189], v[196:197], off offset:192
	global_load_dwordx2 v[190:191], v[196:197], off offset:224
	v_add_f32_e32 v62, 0, v62
	v_add_f32_e32 v63, 0, v63
	v_add_f32_e32 v64, 0, v64
	v_add_f32_e32 v65, 0, v65
	s_waitcnt vmcnt(7)
	v_lshlrev_b32_e32 v76, 16, v176
	v_and_b32_e32 v74, 0xffff0000, v176
	v_lshlrev_b32_e32 v77, 16, v177
	v_and_b32_e32 v75, 0xffff0000, v177
	v_fmac_f32_e32 v76, v62, v198
	v_fmac_f32_e32 v74, v63, v199
	v_fmac_f32_e32 v77, v64, v200
	v_fmac_f32_e32 v75, v65, v201
	v_cvt_pk_bf16_f32 v62, v76, v74
	v_cvt_pk_bf16_f32 v63, v77, v75
	global_store_dwordx2 v[72:73], v[62:63], off
	v_lshl_add_u64 v[68:69], v[132:133], 1, v[66:67]
	v_add_f32_e32 v58, 0, v58
	v_add_f32_e32 v59, 0, v59
	v_add_f32_e32 v60, 0, v60
	v_add_f32_e32 v61, 0, v61
	s_waitcnt vmcnt(7)
	v_lshlrev_b32_e32 v72, 16, v178
	v_and_b32_e32 v70, 0xffff0000, v178
	v_lshlrev_b32_e32 v73, 16, v179
	v_and_b32_e32 v71, 0xffff0000, v179
	v_fmac_f32_e32 v72, v58, v202
	v_fmac_f32_e32 v70, v59, v203
	v_fmac_f32_e32 v73, v60, v204
	v_fmac_f32_e32 v71, v61, v205
	v_cvt_pk_bf16_f32 v58, v72, v70
	v_cvt_pk_bf16_f32 v59, v73, v71
	global_store_dwordx2 v[68:69], v[58:59], off offset:32
	v_lshl_add_u64 v[62:63], v[132:133], 1, v[66:67]
	v_add_f32_e32 v54, 0, v54
	v_add_f32_e32 v55, 0, v55
	v_add_f32_e32 v56, 0, v56
	v_add_f32_e32 v57, 0, v57
	s_waitcnt vmcnt(7)
	v_lshlrev_b32_e32 v68, 16, v180
	v_and_b32_e32 v64, 0xffff0000, v180
	v_lshlrev_b32_e32 v69, 16, v181
	v_and_b32_e32 v65, 0xffff0000, v181
	v_fmac_f32_e32 v68, v54, v206
	v_fmac_f32_e32 v64, v55, v207
	v_fmac_f32_e32 v69, v56, v208
	v_fmac_f32_e32 v65, v57, v209
	v_cvt_pk_bf16_f32 v54, v68, v64
	v_cvt_pk_bf16_f32 v55, v69, v65
	global_store_dwordx2 v[62:63], v[54:55], off offset:64
	v_lshl_add_u64 v[58:59], v[132:133], 1, v[66:67]
	v_add_f32_e32 v50, 0, v50
	v_add_f32_e32 v51, 0, v51
	v_add_f32_e32 v52, 0, v52
	v_add_f32_e32 v53, 0, v53
	s_waitcnt vmcnt(7)
	v_lshlrev_b32_e32 v62, 16, v182
	v_and_b32_e32 v60, 0xffff0000, v182
	v_lshlrev_b32_e32 v63, 16, v183
	v_and_b32_e32 v61, 0xffff0000, v183
	v_fmac_f32_e32 v62, v50, v210
	v_fmac_f32_e32 v60, v51, v211
	v_fmac_f32_e32 v63, v52, v212
	v_fmac_f32_e32 v61, v53, v213
	v_cvt_pk_bf16_f32 v50, v62, v60
	v_cvt_pk_bf16_f32 v51, v63, v61
	global_store_dwordx2 v[58:59], v[50:51], off offset:96
	v_lshl_add_u64 v[54:55], v[132:133], 1, v[66:67]
	v_add_f32_e32 v46, 0, v46
	v_add_f32_e32 v47, 0, v47
	v_add_f32_e32 v48, 0, v48
	v_add_f32_e32 v49, 0, v49
	s_waitcnt vmcnt(7)
	v_lshlrev_b32_e32 v58, 16, v184
	v_and_b32_e32 v56, 0xffff0000, v184
	v_lshlrev_b32_e32 v59, 16, v185
	v_and_b32_e32 v57, 0xffff0000, v185
	v_fmac_f32_e32 v58, v46, v214
	v_fmac_f32_e32 v56, v47, v215
	v_fmac_f32_e32 v59, v48, v216
	v_fmac_f32_e32 v57, v49, v217
	v_cvt_pk_bf16_f32 v46, v58, v56
	v_cvt_pk_bf16_f32 v47, v59, v57
	global_store_dwordx2 v[54:55], v[46:47], off offset:128
	v_lshl_add_u64 v[50:51], v[132:133], 1, v[66:67]
	v_add_f32_e32 v42, 0, v42
	v_add_f32_e32 v43, 0, v43
	v_add_f32_e32 v44, 0, v44
	v_add_f32_e32 v45, 0, v45
	s_waitcnt vmcnt(7)
	v_lshlrev_b32_e32 v54, 16, v186
	v_and_b32_e32 v52, 0xffff0000, v186
	v_lshlrev_b32_e32 v55, 16, v187
	v_and_b32_e32 v53, 0xffff0000, v187
	v_fmac_f32_e32 v54, v42, v224
	v_fmac_f32_e32 v52, v43, v225
	v_fmac_f32_e32 v55, v44, v226
	v_fmac_f32_e32 v53, v45, v227
	v_cvt_pk_bf16_f32 v42, v54, v52
	v_cvt_pk_bf16_f32 v43, v55, v53
	global_store_dwordx2 v[50:51], v[42:43], off offset:160
	v_lshl_add_u64 v[46:47], v[132:133], 1, v[66:67]
	v_add_f32_e32 v38, 0, v38
	v_add_f32_e32 v39, 0, v39
	v_add_f32_e32 v40, 0, v40
	v_add_f32_e32 v41, 0, v41
	s_waitcnt vmcnt(7)
; __device__ __forceinline__ unsigned pack2(float a, float b) { unsigned r; asm("v_cvt_pk_bf16_f32 %0, %1, %2" : "=v"(r) : "v"(a), "v"(b)); return r; }
; __device__ __forceinline__ float bf2f(bf16_t h) { return __uint_as_float(((unsigned)h) << 16); }
;   __device__ __forceinline__ void c4(int g, int rig, int col, f32x4 v) const {
;     const size_t o = ((size_t)g * 2048 + rig) * 1024 + col;
;     f32x4 bs;
;     if (BASE_F32) bs = __builtin_nontemporal_load((const f32x4*)((const float*)base + o));
;     else {
;       const uint2 u = *(const uint2*)((const bf16_t*)base + o);
;       bs[0] = bf2f((bf16_t)(u.x & 0xffff)); bs[1] = bf2f((bf16_t)(u.x >> 16)); bs[2] = bf2f((bf16_t)(u.y & 0xffff)); bs[3] = bf2f((bf16_t)(u.y >> 16));
;     }
;     const f32x4 gt = *(const f32x4*)(gate + (size_t)g * 6144 + col);
;     f32x4 bi = {0.f, 0.f, 0.f, 0.f};
;     if (bias) bi = *(const f32x4*)(bias + col);
;     f32x4 r;
; #pragma unroll
;     for (int j = 0; j < 4; ++j) r[j] = bs[j] + gt[j] * (v[j] + bi[j]);
;     uint2 w; w.x = pack2(r[0], r[1]); w.y = pack2(r[2], r[3]);
;     *(uint2*)(X16 + o) = w;
;   }
; template <bool SWAP, class Epi, bool THIN = false> ...
;     ...
; #pragma unroll
;       for (int m = 0; m < 4; ++m) {
;         const int rig = rig0 + rw + m * 16 + fr_e;
;         if constexpr (Epi::ROWSUM) {
;           float ss = 0.f;
; #pragma unroll
;           for (int n = 0; n < 8; ++n) {
;             const int col = nt * 256 + wc_e * 128 + n * 16 + fq_e * 4;
;             if (col < N) ss += epi.c4(g, rig, col, acc[m][n]);
;           }
;           ss += __shfl_xor(ss, 16); ss += __shfl_xor(ss, 32);
;           if (fq_e == 0) epi.rowsum(g, rig, nt * 2 + wc_e, ss);
;         } else {
; #pragma unroll
;           for (int n = 0; n < 8; ++n) {
;             const int col = nt * 256 + wc_e * 128 + n * 16 + fq_e * 4;
;             if (col < N) epi.c4(g, rig, col, acc[m][n]);
	v_lshlrev_b32_e32 v50, 16, v188
	v_and_b32_e32 v48, 0xffff0000, v188
	v_lshlrev_b32_e32 v51, 16, v189
	v_and_b32_e32 v49, 0xffff0000, v189
	v_fmac_f32_e32 v50, v38, v228
	v_fmac_f32_e32 v48, v39, v229
	v_fmac_f32_e32 v51, v40, v230
	v_fmac_f32_e32 v49, v41, v231
	v_cvt_pk_bf16_f32 v38, v50, v48
	v_cvt_pk_bf16_f32 v39, v51, v49
	global_store_dwordx2 v[46:47], v[38:39], off offset:192
	v_lshl_add_u64 v[42:43], v[132:133], 1, v[66:67]
	v_add_f32_e32 v34, 0, v34
	v_add_f32_e32 v35, 0, v35
	v_add_f32_e32 v36, 0, v36
	v_add_f32_e32 v37, 0, v37
	s_waitcnt vmcnt(7)
	v_lshlrev_b32_e32 v46, 16, v190
	v_and_b32_e32 v44, 0xffff0000, v190
	v_lshlrev_b32_e32 v47, 16, v191
	v_and_b32_e32 v45, 0xffff0000, v191
	v_fmac_f32_e32 v46, v34, v232
	v_fmac_f32_e32 v44, v35, v233
	v_fmac_f32_e32 v47, v36, v234
	v_fmac_f32_e32 v45, v37, v235
	v_cvt_pk_bf16_f32 v34, v46, v44
	v_cvt_pk_bf16_f32 v35, v47, v45
	global_store_dwordx2 v[42:43], v[34:35], off offset:224
	v_or_b32_e32 v34, 48, v136
	v_ashrrev_i32_e32 v35, 31, v34
	v_lshlrev_b64 v[34:35], 10, v[34:35]
	v_lshl_add_u64 v[34:35], v[34:35], 0, v[138:139]
	v_lshl_add_u64 v[34:35], v[34:35], 1, s[20:21]
	v_lshl_add_u64 v[40:41], v[132:133], 1, v[34:35]
	v_lshl_add_u64 v[196:197], v[132:133], 1, v[34:35]
	global_load_dwordx2 v[176:177], v[196:197], off
	global_load_dwordx2 v[178:179], v[196:197], off offset:32
	global_load_dwordx2 v[180:181], v[196:197], off offset:64
	global_load_dwordx2 v[182:183], v[196:197], off offset:96
	global_load_dwordx2 v[184:185], v[196:197], off offset:128
	global_load_dwordx2 v[186:187], v[196:197], off offset:160
	global_load_dwordx2 v[188:189], v[196:197], off offset:192
	global_load_dwordx2 v[190:191], v[196:197], off offset:224
	v_add_f32_e32 v30, 0, v30
	v_add_f32_e32 v31, 0, v31
	v_add_f32_e32 v32, 0, v32
	v_add_f32_e32 v33, 0, v33
	s_waitcnt vmcnt(7)
	v_lshlrev_b32_e32 v44, 16, v176
	v_and_b32_e32 v42, 0xffff0000, v176
	v_lshlrev_b32_e32 v45, 16, v177
	v_and_b32_e32 v43, 0xffff0000, v177
	v_fmac_f32_e32 v44, v30, v198
	v_fmac_f32_e32 v42, v31, v199
	v_fmac_f32_e32 v45, v32, v200
	v_fmac_f32_e32 v43, v33, v201
	v_cvt_pk_bf16_f32 v30, v44, v42
	v_cvt_pk_bf16_f32 v31, v45, v43
	global_store_dwordx2 v[40:41], v[30:31], off
	v_lshl_add_u64 v[36:37], v[132:133], 1, v[34:35]
	v_add_f32_e32 v26, 0, v26
	v_add_f32_e32 v27, 0, v27
	v_add_f32_e32 v28, 0, v28
	v_add_f32_e32 v29, 0, v29
	s_waitcnt vmcnt(7)
	v_lshlrev_b32_e32 v40, 16, v178
	v_and_b32_e32 v38, 0xffff0000, v178
	v_lshlrev_b32_e32 v41, 16, v179
	v_and_b32_e32 v39, 0xffff0000, v179
	v_fmac_f32_e32 v40, v26, v202
	v_fmac_f32_e32 v38, v27, v203
	v_fmac_f32_e32 v41, v28, v204
	v_fmac_f32_e32 v39, v29, v205
	v_cvt_pk_bf16_f32 v26, v40, v38
	v_cvt_pk_bf16_f32 v27, v41, v39
	global_store_dwordx2 v[36:37], v[26:27], off offset:32
	v_lshl_add_u64 v[30:31], v[132:133], 1, v[34:35]
	v_add_f32_e32 v22, 0, v22
	v_add_f32_e32 v23, 0, v23
	v_add_f32_e32 v24, 0, v24
	v_add_f32_e32 v25, 0, v25
	s_waitcnt vmcnt(7)
	v_lshlrev_b32_e32 v36, 16, v180
	v_and_b32_e32 v32, 0xffff0000, v180
	v_lshlrev_b32_e32 v37, 16, v181
	v_and_b32_e32 v33, 0xffff0000, v181
	v_fmac_f32_e32 v36, v22, v206
	v_fmac_f32_e32 v32, v23, v207
	v_fmac_f32_e32 v37, v24, v208
	v_fmac_f32_e32 v33, v25, v209
	v_cvt_pk_bf16_f32 v22, v36, v32
	v_cvt_pk_bf16_f32 v23, v37, v33
	global_store_dwordx2 v[30:31], v[22:23], off offset:64
	v_lshl_add_u64 v[26:27], v[132:133], 1, v[34:35]
	v_add_f32_e32 v18, 0, v18
	v_add_f32_e32 v19, 0, v19
	v_add_f32_e32 v20, 0, v20
	v_add_f32_e32 v21, 0, v21
	s_waitcnt vmcnt(7)
	v_lshlrev_b32_e32 v30, 16, v182
	v_and_b32_e32 v28, 0xffff0000, v182
	v_lshlrev_b32_e32 v31, 16, v183
	v_and_b32_e32 v29, 0xffff0000, v183
	v_fmac_f32_e32 v30, v18, v210
	v_fmac_f32_e32 v28, v19, v211
	v_fmac_f32_e32 v31, v20, v212
	v_fmac_f32_e32 v29, v21, v213
	v_cvt_pk_bf16_f32 v18, v30, v28
	v_cvt_pk_bf16_f32 v19, v31, v29
	global_store_dwordx2 v[26:27], v[18:19], off offset:96
	v_lshl_add_u64 v[22:23], v[132:133], 1, v[34:35]
	v_add_f32_e32 v14, 0, v14
	v_add_f32_e32 v15, 0, v15
	v_add_f32_e32 v16, 0, v16
	v_add_f32_e32 v17, 0, v17
	s_waitcnt vmcnt(7)
	v_lshlrev_b32_e32 v26, 16, v184
	v_and_b32_e32 v24, 0xffff0000, v184
	v_lshlrev_b32_e32 v27, 16, v185
	v_and_b32_e32 v25, 0xffff0000, v185
	v_fmac_f32_e32 v26, v14, v214
	v_fmac_f32_e32 v24, v15, v215
	v_fmac_f32_e32 v27, v16, v216
	v_fmac_f32_e32 v25, v17, v217
	v_cvt_pk_bf16_f32 v14, v26, v24
	v_cvt_pk_bf16_f32 v15, v27, v25
	global_store_dwordx2 v[22:23], v[14:15], off offset:128
	v_lshl_add_u64 v[18:19], v[132:133], 1, v[34:35]
	v_add_f32_e32 v10, 0, v10
	v_add_f32_e32 v11, 0, v11
	v_add_f32_e32 v12, 0, v12
	v_add_f32_e32 v13, 0, v13
	s_waitcnt vmcnt(7)
	v_lshlrev_b32_e32 v22, 16, v186
	v_and_b32_e32 v20, 0xffff0000, v186
	v_lshlrev_b32_e32 v23, 16, v187
	v_and_b32_e32 v21, 0xffff0000, v187
	v_fmac_f32_e32 v22, v10, v224
	v_fmac_f32_e32 v20, v11, v225
	v_fmac_f32_e32 v23, v12, v226
	v_fmac_f32_e32 v21, v13, v227
	v_cvt_pk_bf16_f32 v10, v22, v20
	v_cvt_pk_bf16_f32 v11, v23, v21
	global_store_dwordx2 v[18:19], v[10:11], off offset:160
	v_lshl_add_u64 v[14:15], v[132:133], 1, v[34:35]
	v_add_f32_e32 v6, 0, v6
	v_add_f32_e32 v7, 0, v7
	v_add_f32_e32 v8, 0, v8
	v_add_f32_e32 v9, 0, v9
	s_waitcnt vmcnt(7)
	v_lshlrev_b32_e32 v18, 16, v188
	v_and_b32_e32 v16, 0xffff0000, v188
	v_lshlrev_b32_e32 v19, 16, v189
	v_and_b32_e32 v17, 0xffff0000, v189
	v_fmac_f32_e32 v18, v6, v228
	v_fmac_f32_e32 v16, v7, v229
	v_fmac_f32_e32 v19, v8, v230
	v_fmac_f32_e32 v17, v9, v231
	v_cvt_pk_bf16_f32 v6, v18, v16
	v_cvt_pk_bf16_f32 v7, v19, v17
	global_store_dwordx2 v[14:15], v[6:7], off offset:192
	v_lshl_add_u64 v[10:11], v[132:133], 1, v[34:35]
	v_add_f32_e32 v2, 0, v2
	v_add_f32_e32 v3, 0, v3
	v_add_f32_e32 v4, 0, v4
	v_add_f32_e32 v5, 0, v5
	s_waitcnt vmcnt(7)
	v_lshlrev_b32_e32 v14, 16, v190
	v_and_b32_e32 v12, 0xffff0000, v190
	v_lshlrev_b32_e32 v15, 16, v191
	v_and_b32_e32 v13, 0xffff0000, v191
	v_fmac_f32_e32 v14, v2, v232
	v_fmac_f32_e32 v12, v3, v233
	v_fmac_f32_e32 v15, v4, v234
	v_fmac_f32_e32 v13, v5, v235
	v_cvt_pk_bf16_f32 v2, v14, v12
	v_cvt_pk_bf16_f32 v3, v15, v13
	global_store_dwordx2 v[10:11], v[2:3], off offset:224
	s_branch .LBB0_2427

; template <bool SWAP, class Epi, bool THIN = false> ...
;     ...
;     for (int st = 0; st < ns; ++st) {
;       asm volatile("s_waitcnt vmcnt(0)" ::: "memory");
;       __builtin_amdgcn_s_barrier();
;       asm volatile("" ::: "memory");
;       if (st + 1 < ns) {
;         char* nb = smem + ((st + 1) & 1) * 65536;
;         const int ko = (st + 1) * 64;
; #pragma unroll
;         for (int i = 0; i < 4; ++i) { GLDS16(A + (size_t)(ap[i] + ko), nb + tid * 16 + i * 8192); GLDS16(Bt + (size_t)(bp[i] + ko), nb + 32768 + tid * 16 + i * 8192); }
;       }
;       const char* sa = smem + (st & 1) * 65536 + (wr * 64 + fr) * 128;
;       const char* sb = smem + (st & 1) * 65536 + 32768 + (wc * 128 + fr) * 128;
;       if constexpr (THIN) {
;         if (wc == 0) {
; #pragma unroll
;           for (int ks = 0; ks < 2; ++ks) {
;             bf16x8 af[4], bf[2];
; #pragma unroll
;             for (int m = 0; m < 4; ++m) af[m] = *(const bf16x8*)(sa + m * 2048 + (((ks * 4 + fq) ^ swz) << 4));
; #pragma unroll
;             for (int n = 0; n < 2; ++n) bf[n] = *(const bf16x8*)(sb + n * 2048 + (((ks * 4 + fq) ^ swz) << 4));
; #pragma unroll
;             for (int m = 0; m < 4; ++m)
; #pragma unroll
;               for (int n = 0; n < 2; ++n)
;                 acc[m][n] = SWAP ? __builtin_amdgcn_mfma_f32_16x16x32_bf16(bf[n], af[m], acc[m][n], 0, 0, 0)
;                                  : __builtin_amdgcn_mfma_f32_16x16x32_bf16(af[m], bf[n], acc[m][n], 0, 0, 0);
;           }
;         }
;       } else {
;       bf16x8 afA[4], afB[4], bfb[2][2];
; #pragma unroll
;       for (int m = 0; m < 4; ++m) afA[m] = *(const bf16x8*)(sa + m * 2048 + ((fq ^ swz) << 4));
; #pragma unroll
;       for (int n = 0; n < 2; ++n) bfb[0][n] = *(const bf16x8*)(sb + n * 2048 + ((fq ^ swz) << 4));
; #pragma unroll
;       for (int gq = 0; gq < 8; ++gq) {
;         const int ks = gq >> 2, nh = gq & 3;
;         if (gq < 7) {
;           const int ks2 = (gq + 1) >> 2, nh2 = (gq + 1) & 3;
; #pragma unroll
;           for (int n = 0; n < 2; ++n) bfb[(gq + 1) & 1][n] = *(const bf16x8*)(sb + (nh2 * 2 + n) * 2048 + (((ks2 * 4 + fq) ^ swz) << 4));
;         }
;         if (gq == 3) {
; #pragma unroll
;           for (int m = 0; m < 4; ++m) afB[m] = *(const bf16x8*)(sa + m * 2048 + (((4 + fq) ^ swz) << 4));
;         }
;         __builtin_amdgcn_sched_barrier(0);
; #pragma unroll
.LBB0_3516:
	s_add_i32 s9, s7, 0x10000
	s_and_b32 s8, s9, 0x10000
	v_add_u32_e32 v139, s8, v144
	s_nop 0
	v_readfirstlane_b32 s10, v139
	s_waitcnt vmcnt(0)
	s_barrier
	s_and_b32 s7, s7, 0x10000
	v_add_u32_e32 v130, s7, v145
	v_add_u32_e32 v139, v130, v147
	ds_read_b128 v[168:171], v139
	ds_read_b128 v[172:175], v139 offset:2048
	ds_read_b128 v[176:179], v139 offset:4096
	ds_read_b128 v[180:183], v139 offset:6144
	v_or_b32_e32 v139, s7, v146
	v_add_u32_e32 v141, v139, v147
	ds_read_b128 v[184:187], v141 offset:32768
	ds_read_b128 v[188:191], v141 offset:34816
	ds_read_b128 v[192:195], v141 offset:36864
	ds_read_b128 v[196:199], v141 offset:38912
	v_add_u32_e32 v130, v130, v148
	s_waitcnt lgkmcnt(3)
	v_mfma_f32_16x16x32_bf16 v[126:129], v[184:187], v[168:171], v[126:129]
	s_mov_b32 m0, s10
	v_mfma_f32_16x16x32_bf16 v[110:113], v[184:187], v[172:175], v[110:113]
	global_load_lds_dwordx4 v138, s[24:25]
	v_add_u32_e32 v138, 0x80, v138
	v_mfma_f32_16x16x32_bf16 v[82:85], v[184:187], v[176:179], v[82:85]
	v_mfma_f32_16x16x32_bf16 v[50:53], v[184:187], v[180:183], v[50:53]
	ds_read_b128 v[184:187], v141 offset:40960
	ds_read_b128 v[200:203], v141 offset:43008
	s_waitcnt lgkmcnt(4)
	v_mfma_f32_16x16x32_bf16 v[122:125], v[188:191], v[168:171], v[122:125]
	s_add_u32 m0, s10, 0x8000
	v_mfma_f32_16x16x32_bf16 v[106:109], v[188:191], v[172:175], v[106:109]
	global_load_lds_dwordx4 v137, s[20:21]
	v_add_u32_e32 v137, 0x80, v137
	v_mfma_f32_16x16x32_bf16 v[78:81], v[188:191], v[176:179], v[78:81]
	v_mfma_f32_16x16x32_bf16 v[38:41], v[188:191], v[180:183], v[38:41]
	s_waitcnt lgkmcnt(3)
	v_mfma_f32_16x16x32_bf16 v[118:121], v[192:195], v[168:171], v[118:121]
	s_add_u32 m0, s10, 0x2000
	v_mfma_f32_16x16x32_bf16 v[94:97], v[192:195], v[172:175], v[94:97]
	global_load_lds_dwordx4 v136, s[24:25]
	v_add_u32_e32 v136, 0x80, v136
	v_mfma_f32_16x16x32_bf16 v[58:61], v[192:195], v[176:179], v[58:61]
	v_mfma_f32_16x16x32_bf16 v[26:29], v[192:195], v[180:183], v[26:29]
	ds_read_b128 v[188:191], v141 offset:45056
	ds_read_b128 v[192:195], v141 offset:47104
	s_waitcnt lgkmcnt(4)
	v_mfma_f32_16x16x32_bf16 v[114:117], v[196:199], v[168:171], v[114:117]
	s_add_u32 m0, s10, 0xa000
	v_mfma_f32_16x16x32_bf16 v[86:89], v[196:199], v[172:175], v[86:89]
	global_load_lds_dwordx4 v135, s[20:21]
	v_add_u32_e32 v135, 0x80, v135
	v_mfma_f32_16x16x32_bf16 v[54:57], v[196:199], v[176:179], v[54:57]
	v_mfma_f32_16x16x32_bf16 v[22:25], v[196:199], v[180:183], v[22:25]
	v_add_u32_e32 v139, v139, v148
	s_waitcnt lgkmcnt(3)
	v_mfma_f32_16x16x32_bf16 v[102:105], v[184:187], v[168:171], v[102:105]
	ds_read_b128 v[196:199], v139 offset:32768
	ds_read_b128 v[204:207], v139 offset:34816
	s_add_u32 m0, s10, 0x4000
	v_mfma_f32_16x16x32_bf16 v[74:77], v[184:187], v[172:175], v[74:77]
	global_load_lds_dwordx4 v134, s[24:25]
	v_add_u32_e32 v134, 0x80, v134
	v_mfma_f32_16x16x32_bf16 v[46:49], v[184:187], v[176:179], v[46:49]
	v_mfma_f32_16x16x32_bf16 v[10:13], v[184:187], v[180:183], v[10:13]
	ds_read_b128 v[184:187], v130
	ds_read_b128 v[208:211], v130 offset:2048
	ds_read_b128 v[212:215], v130 offset:4096
	ds_read_b128 v[216:219], v130 offset:6144
	s_waitcnt lgkmcnt(8)
	v_mfma_f32_16x16x32_bf16 v[98:101], v[200:203], v[168:171], v[98:101]
	s_add_u32 m0, s10, 0xc000
	v_mfma_f32_16x16x32_bf16 v[66:69], v[200:203], v[172:175], v[66:69]
	global_load_lds_dwordx4 v133, s[20:21]
	v_add_u32_e32 v133, 0x80, v133
	v_mfma_f32_16x16x32_bf16 v[34:37], v[200:203], v[176:179], v[34:37]
	v_mfma_f32_16x16x32_bf16 v[6:9], v[200:203], v[180:183], v[6:9]
	s_waitcnt lgkmcnt(7)
	v_mfma_f32_16x16x32_bf16 v[70:73], v[188:191], v[168:171], v[70:73]
	s_add_u32 m0, s10, 0x6000
	s_waitcnt lgkmcnt(6)
	v_mfma_f32_16x16x32_bf16 v[62:65], v[192:195], v[168:171], v[62:65]
	global_load_lds_dwordx4 v132, s[24:25]
	v_add_u32_e32 v132, 0x80, v132
	v_mfma_f32_16x16x32_bf16 v[42:45], v[188:191], v[172:175], v[42:45]
	v_mfma_f32_16x16x32_bf16 v[30:33], v[192:195], v[172:175], v[30:33]
	ds_read_b128 v[168:171], v139 offset:36864
	ds_read_b128 v[172:175], v139 offset:38912
	v_mfma_f32_16x16x32_bf16 v[18:21], v[188:191], v[176:179], v[18:21]
	s_add_u32 m0, s10, 0xe000
	v_mfma_f32_16x16x32_bf16 v[14:17], v[192:195], v[176:179], v[14:17]
	global_load_lds_dwordx4 v140, s[20:21]
	v_add_u32_e32 v140, 0x80, v140
	v_mfma_f32_16x16x32_bf16 v[2:5], v[188:191], v[180:183], v[2:5]
	v_mfma_f32_16x16x32_bf16 v[90:93], v[192:195], v[180:183], v[90:93]
	ds_read_b128 v[176:179], v139 offset:40960
	ds_read_b128 v[180:183], v139 offset:43008
	s_waitcnt lgkmcnt(7)
	v_mfma_f32_16x16x32_bf16 v[126:129], v[196:199], v[184:187], v[126:129]
	v_mfma_f32_16x16x32_bf16 v[122:125], v[204:207], v[184:187], v[122:125]
	s_waitcnt lgkmcnt(6)
	v_mfma_f32_16x16x32_bf16 v[110:113], v[196:199], v[208:211], v[110:113]
	v_mfma_f32_16x16x32_bf16 v[106:109], v[204:207], v[208:211], v[106:109]
	s_waitcnt lgkmcnt(5)
	v_mfma_f32_16x16x32_bf16 v[82:85], v[196:199], v[212:215], v[82:85]
	v_mfma_f32_16x16x32_bf16 v[78:81], v[204:207], v[212:215], v[78:81]
	s_waitcnt lgkmcnt(4)
	v_mfma_f32_16x16x32_bf16 v[50:53], v[196:199], v[216:219], v[50:53]
	v_mfma_f32_16x16x32_bf16 v[38:41], v[204:207], v[216:219], v[38:41]
	s_waitcnt lgkmcnt(3)
	v_mfma_f32_16x16x32_bf16 v[118:121], v[168:171], v[184:187], v[118:121]
	v_mfma_f32_16x16x32_bf16 v[94:97], v[168:171], v[208:211], v[94:97]
	v_mfma_f32_16x16x32_bf16 v[58:61], v[168:171], v[212:215], v[58:61]
	v_mfma_f32_16x16x32_bf16 v[26:29], v[168:171], v[216:219], v[26:29]
	ds_read_b128 v[168:171], v139 offset:45056
	ds_read_b128 v[188:191], v139 offset:47104
	s_waitcnt lgkmcnt(4)
; template <bool SWAP, class Epi, bool THIN = false> ...
;     ...
;     for (int st = 0; st < ns; ++st) {
;       asm volatile("s_waitcnt vmcnt(0)" ::: "memory");
;       __builtin_amdgcn_s_barrier();
;       asm volatile("" ::: "memory");
;       if (st + 1 < ns) {
;         char* nb = smem + ((st + 1) & 1) * 65536;
;         const int ko = (st + 1) * 64;
; #pragma unroll
;         for (int i = 0; i < 4; ++i) { GLDS16(A + (size_t)(ap[i] + ko), nb + tid * 16 + i * 8192); GLDS16(Bt + (size_t)(bp[i] + ko), nb + 32768 + tid * 16 + i * 8192); }
;       }
;       const char* sa = smem + (st & 1) * 65536 + (wr * 64 + fr) * 128;
;       const char* sb = smem + (st & 1) * 65536 + 32768 + (wc * 128 + fr) * 128;
;       if constexpr (THIN) {
;         if (wc == 0) {
; #pragma unroll
;           for (int ks = 0; ks < 2; ++ks) {
;             bf16x8 af[4], bf[2];
; #pragma unroll
;             for (int m = 0; m < 4; ++m) af[m] = *(const bf16x8*)(sa + m * 2048 + (((ks * 4 + fq) ^ swz) << 4));
; #pragma unroll
;             for (int n = 0; n < 2; ++n) bf[n] = *(const bf16x8*)(sb + n * 2048 + (((ks * 4 + fq) ^ swz) << 4));
; #pragma unroll
;             for (int m = 0; m < 4; ++m)
; #pragma unroll
;               for (int n = 0; n < 2; ++n)
;                 acc[m][n] = SWAP ? __builtin_amdgcn_mfma_f32_16x16x32_bf16(bf[n], af[m], acc[m][n], 0, 0, 0)
;                                  : __builtin_amdgcn_mfma_f32_16x16x32_bf16(af[m], bf[n], acc[m][n], 0, 0, 0);
;           }
;         }
;       } else {
;       bf16x8 afA[4], afB[4], bfb[2][2];
; #pragma unroll
;       for (int m = 0; m < 4; ++m) afA[m] = *(const bf16x8*)(sa + m * 2048 + ((fq ^ swz) << 4));
; #pragma unroll
;       for (int n = 0; n < 2; ++n) bfb[0][n] = *(const bf16x8*)(sb + n * 2048 + ((fq ^ swz) << 4));
; #pragma unroll
;       for (int gq = 0; gq < 8; ++gq) {
;         const int ks = gq >> 2, nh = gq & 3;
;         if (gq < 7) {
;           const int ks2 = (gq + 1) >> 2, nh2 = (gq + 1) & 3;
; #pragma unroll
;           for (int n = 0; n < 2; ++n) bfb[(gq + 1) & 1][n] = *(const bf16x8*)(sb + (nh2 * 2 + n) * 2048 + (((ks2 * 4 + fq) ^ swz) << 4));
;         }
;         if (gq == 3) {
; #pragma unroll
;           for (int m = 0; m < 4; ++m) afB[m] = *(const bf16x8*)(sa + m * 2048 + (((4 + fq) ^ swz) << 4));
;         }
;         __builtin_amdgcn_sched_barrier(0);
; #pragma unroll
	v_mfma_f32_16x16x32_bf16 v[114:117], v[172:175], v[184:187], v[114:117]
	v_mfma_f32_16x16x32_bf16 v[86:89], v[172:175], v[208:211], v[86:89]
	v_mfma_f32_16x16x32_bf16 v[54:57], v[172:175], v[212:215], v[54:57]
	v_mfma_f32_16x16x32_bf16 v[22:25], v[172:175], v[216:219], v[22:25]
	s_waitcnt lgkmcnt(3)
	v_mfma_f32_16x16x32_bf16 v[102:105], v[176:179], v[184:187], v[102:105]
	s_waitcnt lgkmcnt(2)
	v_mfma_f32_16x16x32_bf16 v[98:101], v[180:183], v[184:187], v[98:101]
	v_mfma_f32_16x16x32_bf16 v[74:77], v[176:179], v[208:211], v[74:77]
	v_mfma_f32_16x16x32_bf16 v[66:69], v[180:183], v[208:211], v[66:69]
	v_mfma_f32_16x16x32_bf16 v[46:49], v[176:179], v[212:215], v[46:49]
	v_mfma_f32_16x16x32_bf16 v[34:37], v[180:183], v[212:215], v[34:37]
	v_mfma_f32_16x16x32_bf16 v[10:13], v[176:179], v[216:219], v[10:13]
	v_mfma_f32_16x16x32_bf16 v[6:9], v[180:183], v[216:219], v[6:9]
	s_waitcnt lgkmcnt(1)
	v_mfma_f32_16x16x32_bf16 v[70:73], v[168:171], v[184:187], v[70:73]
	s_add_i32 s6, s6, 64
	s_cmpk_eq_i32 s6, 0xac0
	s_mov_b32 s7, s9
	s_waitcnt lgkmcnt(0)
	v_mfma_f32_16x16x32_bf16 v[62:65], v[188:191], v[184:187], v[62:65]
	v_mfma_f32_16x16x32_bf16 v[42:45], v[168:171], v[208:211], v[42:45]
	v_mfma_f32_16x16x32_bf16 v[30:33], v[188:191], v[208:211], v[30:33]
	v_mfma_f32_16x16x32_bf16 v[18:21], v[168:171], v[212:215], v[18:21]
	v_mfma_f32_16x16x32_bf16 v[14:17], v[188:191], v[212:215], v[14:17]
	v_mfma_f32_16x16x32_bf16 v[2:5], v[168:171], v[216:219], v[2:5]
	v_mfma_f32_16x16x32_bf16 v[90:93], v[188:191], v[216:219], v[90:93]
	s_cbranch_scc0 .LBB0_3516
	v_add_u32_e32 v130, s8, v145
	s_waitcnt vmcnt(0)
	s_barrier
	v_add_u32_e32 v140, v130, v147
	ds_read_b128 v[132:135], v140
	ds_read_b128 v[136:139], v140 offset:2048
	ds_read_b128 v[168:171], v140 offset:4096
	ds_read_b128 v[172:175], v140 offset:6144
	v_add_u32_e32 v140, s8, v146
	v_add_u32_e32 v141, v140, v147
	ds_read_b128 v[176:179], v141 offset:32768
	ds_read_b128 v[180:183], v141 offset:34816
	ds_read_b128 v[184:187], v141 offset:36864
	ds_read_b128 v[188:191], v141 offset:38912
	v_add_u32_e32 v130, v130, v148
	s_waitcnt lgkmcnt(0)
	v_mfma_f32_16x16x32_bf16 v[126:129], v[176:179], v[132:135], v[126:129]
	v_mfma_f32_16x16x32_bf16 v[110:113], v[176:179], v[136:139], v[110:113]
	v_mfma_f32_16x16x32_bf16 v[82:85], v[176:179], v[168:171], v[82:85]
	v_mfma_f32_16x16x32_bf16 v[50:53], v[176:179], v[172:175], v[50:53]
	ds_read_b128 v[176:179], v141 offset:40960
	ds_read_b128 v[192:195], v141 offset:43008
	v_mfma_f32_16x16x32_bf16 v[122:125], v[180:183], v[132:135], v[122:125]
	v_mfma_f32_16x16x32_bf16 v[106:109], v[180:183], v[136:139], v[106:109]
	v_mfma_f32_16x16x32_bf16 v[78:81], v[180:183], v[168:171], v[78:81]
	v_mfma_f32_16x16x32_bf16 v[38:41], v[180:183], v[172:175], v[38:41]
	v_mfma_f32_16x16x32_bf16 v[118:121], v[184:187], v[132:135], v[118:121]
	v_mfma_f32_16x16x32_bf16 v[180:183], v[184:187], v[136:139], v[94:97]
	v_mfma_f32_16x16x32_bf16 v[200:203], v[184:187], v[168:171], v[58:61]
	v_mfma_f32_16x16x32_bf16 v[204:207], v[188:191], v[168:171], v[54:57]
	v_mfma_f32_16x16x32_bf16 v[184:187], v[184:187], v[172:175], v[26:29]
	s_nop 2
	ds_read_b128 v[26:29], v141 offset:45056
	ds_read_b128 v[54:57], v141 offset:47104
	v_mfma_f32_16x16x32_bf16 v[114:117], v[188:191], v[132:135], v[114:117]
	v_mfma_f32_16x16x32_bf16 v[196:199], v[188:191], v[136:139], v[86:89]
	v_mfma_f32_16x16x32_bf16 v[188:191], v[188:191], v[172:175], v[22:25]
	v_add_u32_e32 v140, v140, v148
	s_waitcnt lgkmcnt(0)
	v_mfma_f32_16x16x32_bf16 v[102:105], v[176:179], v[132:135], v[102:105]
	ds_read_b128 v[22:25], v140 offset:32768
	ds_read_b128 v[86:89], v140 offset:34816
	v_mfma_f32_16x16x32_bf16 v[74:77], v[176:179], v[136:139], v[74:77]
	v_mfma_f32_16x16x32_bf16 v[46:49], v[176:179], v[168:171], v[46:49]
	v_mfma_f32_16x16x32_bf16 v[10:13], v[176:179], v[172:175], v[10:13]
	ds_read_b128 v[176:179], v130
	ds_read_b128 v[208:211], v130 offset:2048
	ds_read_b128 v[212:215], v130 offset:4096
	ds_read_b128 v[216:219], v130 offset:6144
	v_mfma_f32_16x16x32_bf16 v[98:101], v[192:195], v[132:135], v[98:101]
	v_mfma_f32_16x16x32_bf16 v[66:69], v[192:195], v[136:139], v[66:69]
	v_mfma_f32_16x16x32_bf16 v[34:37], v[192:195], v[168:171], v[34:37]
	v_mfma_f32_16x16x32_bf16 v[6:9], v[192:195], v[172:175], v[6:9]
	v_mfma_f32_16x16x32_bf16 v[220:223], v[26:29], v[168:171], v[18:21]
	v_mfma_f32_16x16x32_bf16 v[168:171], v[54:57], v[168:171], v[14:17]
	s_nop 2
	ds_read_b128 v[14:17], v140 offset:36864
	ds_read_b128 v[18:21], v140 offset:38912
	v_mfma_f32_16x16x32_bf16 v[70:73], v[26:29], v[132:135], v[70:73]
	v_mfma_f32_16x16x32_bf16 v[132:135], v[54:57], v[132:135], v[62:65]
	v_mfma_f32_16x16x32_bf16 v[192:195], v[26:29], v[136:139], v[42:45]
	v_mfma_f32_16x16x32_bf16 v[136:139], v[54:57], v[136:139], v[30:33]
	v_mfma_f32_16x16x32_bf16 v[2:5], v[26:29], v[172:175], v[2:5]
	v_mfma_f32_16x16x32_bf16 v[172:175], v[54:57], v[172:175], v[90:93]
	ds_read_b128 v[224:227], v140 offset:40960
	ds_read_b128 v[228:231], v140 offset:43008
	s_waitcnt lgkmcnt(0)
	v_mfma_f32_16x16x32_bf16 v[126:129], v[22:25], v[176:179], v[126:129]
	v_mfma_f32_16x16x32_bf16 v[122:125], v[86:89], v[176:179], v[122:125]
	v_mfma_f32_16x16x32_bf16 v[94:97], v[22:25], v[208:211], v[110:113]
	v_mfma_f32_16x16x32_bf16 v[90:93], v[86:89], v[208:211], v[106:109]
	v_mfma_f32_16x16x32_bf16 v[62:65], v[22:25], v[212:215], v[82:85]
	v_mfma_f32_16x16x32_bf16 v[58:61], v[86:89], v[212:215], v[78:81]
	v_mfma_f32_16x16x32_bf16 v[30:33], v[22:25], v[216:219], v[50:53]
	v_mfma_f32_16x16x32_bf16 v[26:29], v[86:89], v[216:219], v[38:41]
	v_mfma_f32_16x16x32_bf16 v[86:89], v[14:17], v[208:211], v[180:183]
	v_mfma_f32_16x16x32_bf16 v[22:25], v[14:17], v[216:219], v[184:187]
	s_nop 1
	ds_read_b128 v[180:183], v140 offset:45056
	ds_read_b128 v[184:187], v140 offset:47104
	v_mfma_f32_16x16x32_bf16 v[118:121], v[14:17], v[176:179], v[118:121]
	v_mfma_f32_16x16x32_bf16 v[114:117], v[18:21], v[176:179], v[114:117]
	v_mfma_f32_16x16x32_bf16 v[82:85], v[18:21], v[208:211], v[196:199]
	v_mfma_f32_16x16x32_bf16 v[54:57], v[14:17], v[212:215], v[200:203]
	v_mfma_f32_16x16x32_bf16 v[50:53], v[18:21], v[212:215], v[204:207]
	v_mfma_f32_16x16x32_bf16 v[18:21], v[18:21], v[216:219], v[188:191]
	v_mfma_f32_16x16x32_bf16 v[110:113], v[224:227], v[176:179], v[102:105]
	v_mfma_f32_16x16x32_bf16 v[106:109], v[228:231], v[176:179], v[98:101]
	v_mfma_f32_16x16x32_bf16 v[78:81], v[224:227], v[208:211], v[74:77]
	v_mfma_f32_16x16x32_bf16 v[74:77], v[228:231], v[208:211], v[66:69]
	v_mfma_f32_16x16x32_bf16 v[46:49], v[224:227], v[212:215], v[46:49]
	v_mfma_f32_16x16x32_bf16 v[42:45], v[228:231], v[212:215], v[34:37]
	v_mfma_f32_16x16x32_bf16 v[14:17], v[224:227], v[216:219], v[10:13]
	v_mfma_f32_16x16x32_bf16 v[10:13], v[228:231], v[216:219], v[6:9]
	v_mov_b32_e32 v130, v1
	s_waitcnt vmcnt(0) lgkmcnt(0)
	s_barrier
; __device__ __forceinline__ int get_tid512() { int t = threadIdx.x; asm volatile("" : "+v"(t)); return t; }
; __device__ __forceinline__ unsigned pack2(float a, float b) { unsigned r; asm("v_cvt_pk_bf16_f32 %0, %1, %2" : "=v"(r) : "v"(a), "v"(b)); return r; }
; __device__ __forceinline__ float bf2f(bf16_t h) { return __uint_as_float(((unsigned)h) << 16); }
;   __device__ __forceinline__ void c4(int g, int rig, int col, f32x4 v) const {
;     const size_t o = ((size_t)g * 2048 + rig) * 1024 + col;
;     f32x4 bs;
;     if (BASE_F32) bs = __builtin_nontemporal_load((const f32x4*)((const float*)base + o));
;     else {
;       const uint2 u = *(const uint2*)((const bf16_t*)base + o);
;       bs[0] = bf2f((bf16_t)(u.x & 0xffff)); bs[1] = bf2f((bf16_t)(u.x >> 16)); bs[2] = bf2f((bf16_t)(u.y & 0xffff)); bs[3] = bf2f((bf16_t)(u.y >> 16));
;     }
;     const f32x4 gt = *(const f32x4*)(gate + (size_t)g * 6144 + col);
;     f32x4 bi = {0.f, 0.f, 0.f, 0.f};
;     if (bias) bi = *(const f32x4*)(bias + col);
;     f32x4 r;
; #pragma unroll
;     for (int j = 0; j < 4; ++j) r[j] = bs[j] + gt[j] * (v[j] + bi[j]);
;     uint2 w; w.x = pack2(r[0], r[1]); w.y = pack2(r[2], r[3]);
;     *(uint2*)(X16 + o) = w;
;   }
; template <bool SWAP, class Epi, bool THIN = false> ...
;     ...
;     const int te = get_tid512();
;     const int fr_e = te & 15, fq_e = (te & 63) >> 4, wr_e = te >> 7, wc_e = (te >> 6) & 1;
;     const int sub = 2 * mt + (wr_e >> 1);
;     const int g = sub / tpg, ti = sub - g * tpg;
;     const int rig0 = ti * step - halo;
;     const int rw = (wr_e & 1) * 64;
;     if constexpr (Epi::KIND == 0) {
; #pragma unroll
;       for (int m = 0; m < 4; ++m) {
;         const int rig = rig0 + rw + m * 16 + fr_e;
;         if constexpr (Epi::ROWSUM) {
;           float ss = 0.f;
; #pragma unroll
;           for (int n = 0; n < 8; ++n) {
;             const int col = nt * 256 + wc_e * 128 + n * 16 + fq_e * 4;
;             if (col < N) ss += epi.c4(g, rig, col, acc[m][n]);
;           }
;           ss += __shfl_xor(ss, 16); ss += __shfl_xor(ss, 32);
;           if (fq_e == 0) epi.rowsum(g, rig, nt * 2 + wc_e, ss);
;         } else {
; #pragma unroll
;           for (int n = 0; n < 8; ++n) {
;             const int col = nt * 256 + wc_e * 128 + n * 16 + fq_e * 4;
;             if (col < N) epi.c4(g, rig, col, acc[m][n]);
	v_mfma_f32_16x16x32_bf16 v[98:101], v[184:187], v[176:179], v[132:135]
	v_ashrrev_i32_e32 v7, 8, v130
	v_add_u32_e32 v7, s5, v7
	v_ashrrev_i32_e32 v8, 31, v7
	v_lshrrev_b32_e32 v8, 28, v8
	v_add_u32_e32 v8, v7, v8
	v_ashrrev_i32_e32 v134, 4, v8
	v_lshlrev_b32_e32 v8, 11, v134
	v_lshlrev_b32_e32 v7, 7, v7
	v_sub_u32_e32 v7, v7, v8
	v_lshrrev_b32_e32 v8, 1, v130
	v_and_b32_e32 v6, 15, v130
	v_and_b32_e32 v8, 64, v8
	v_mfma_f32_16x16x32_bf16 v[66:69], v[184:187], v[208:211], v[136:139]
	v_ashrrev_i32_e32 v135, 31, v134
	s_nop 1
	v_or3_b32 v136, v7, v8, v6
	v_lshlrev_b32_e32 v6, 1, v130
	v_and_b32_e32 v132, 0x80, v6
	v_mfma_f32_16x16x32_bf16 v[6:9], v[180:183], v[216:219], v[2:5]
	v_ashrrev_i32_e32 v137, 31, v136
	v_lshlrev_b64 v[138:139], 21, v[134:135]
	v_lshlrev_b64 v[140:141], 10, v[136:137]
	v_lshrrev_b32_e32 v2, 2, v130
	v_and_b32_e32 v2, 12, v2
	v_mfma_f32_16x16x32_bf16 v[102:105], v[180:183], v[176:179], v[70:73]
	v_or3_b32 v132, v2, v132, s4
	v_mad_i64_i32 v[134:135], s[4:5], v134, s31, 0
	v_mfma_f32_16x16x32_bf16 v[70:73], v[180:183], v[208:211], v[192:195]
	v_lshl_add_u64 v[140:141], v[140:141], 0, v[138:139]
	v_cmp_gt_i32_e32 vcc, s34, v132
	v_ashrrev_i32_e32 v133, 31, v132
	v_mfma_f32_16x16x32_bf16 v[38:41], v[180:183], v[212:215], v[220:223]
	v_lshl_add_u64 v[134:135], s[22:23], 0, v[134:135]
	v_lshl_add_u64 v[140:141], v[140:141], 1, s[18:19]
	v_mfma_f32_16x16x32_bf16 v[34:37], v[184:187], v[212:215], v[168:171]
	v_mfma_f32_16x16x32_bf16 v[2:5], v[184:187], v[216:219], v[172:175]
	v_lshl_add_u64 v[218:219], v[132:133], 2, v[134:135]
	global_load_dwordx4 v[198:201], v[218:219], off
	global_load_dwordx4 v[202:205], v[218:219], off offset:64
	global_load_dwordx4 v[206:209], v[218:219], off offset:128
	global_load_dwordx4 v[210:213], v[218:219], off offset:192
	global_load_dwordx4 v[214:217], v[218:219], off offset:256
	global_load_dwordx4 v[224:227], v[218:219], off offset:320
	global_load_dwordx4 v[228:231], v[218:219], off offset:384
	global_load_dwordx4 v[232:235], v[218:219], off offset:448
	s_nop 0
	v_lshl_add_u64 v[172:173], v[132:133], 1, v[140:141]
	v_lshl_add_u64 v[196:197], v[132:133], 1, v[140:141]
	global_load_dwordx2 v[176:177], v[196:197], off
	global_load_dwordx2 v[178:179], v[196:197], off offset:32
	global_load_dwordx2 v[180:181], v[196:197], off offset:64
	global_load_dwordx2 v[182:183], v[196:197], off offset:96
	global_load_dwordx2 v[184:185], v[196:197], off offset:128
	global_load_dwordx2 v[186:187], v[196:197], off offset:160
	global_load_dwordx2 v[188:189], v[196:197], off offset:192
	global_load_dwordx2 v[190:191], v[196:197], off offset:224
	v_add_f32_e32 v126, 0, v126
	v_add_f32_e32 v127, 0, v127
	v_add_f32_e32 v128, 0, v128
	v_add_f32_e32 v129, 0, v129
	s_waitcnt vmcnt(7)
	v_lshlrev_b32_e32 v130, 16, v176
	v_and_b32_e32 v137, 0xffff0000, v176
	v_lshlrev_b32_e32 v167, 16, v177
	v_and_b32_e32 v174, 0xffff0000, v177
	v_fmac_f32_e32 v130, v126, v198
	v_fmac_f32_e32 v137, v127, v199
	v_fmac_f32_e32 v167, v128, v200
	v_fmac_f32_e32 v174, v129, v201
	v_cvt_pk_bf16_f32 v126, v130, v137
	v_cvt_pk_bf16_f32 v127, v167, v174
	global_store_dwordx2 v[172:173], v[126:127], off
	v_or_b32_e32 v126, 16, v132
	v_lshl_add_u64 v[168:169], v[132:133], 1, v[140:141]
	v_add_f32_e32 v122, 0, v122
	v_add_f32_e32 v123, 0, v123
	v_add_f32_e32 v124, 0, v124
	v_add_f32_e32 v125, 0, v125
	s_waitcnt vmcnt(7)
	v_lshlrev_b32_e32 v130, 16, v178
	v_and_b32_e32 v137, 0xffff0000, v178
	v_lshlrev_b32_e32 v167, 16, v179
	v_and_b32_e32 v170, 0xffff0000, v179
	v_fmac_f32_e32 v130, v122, v202
	v_fmac_f32_e32 v137, v123, v203
	v_fmac_f32_e32 v167, v124, v204
	v_fmac_f32_e32 v170, v125, v205
	v_cvt_pk_bf16_f32 v122, v130, v137
	v_cvt_pk_bf16_f32 v123, v167, v170
	global_store_dwordx2 v[168:169], v[122:123], off offset:32
	v_or_b32_e32 v122, 32, v132
	v_lshl_add_u64 v[126:127], v[132:133], 1, v[140:141]
	v_add_f32_e32 v118, 0, v118
	v_add_f32_e32 v119, 0, v119
	v_add_f32_e32 v120, 0, v120
	v_add_f32_e32 v121, 0, v121
	s_waitcnt vmcnt(7)
	v_lshlrev_b32_e32 v130, 16, v180
	v_and_b32_e32 v128, 0xffff0000, v180
	v_lshlrev_b32_e32 v137, 16, v181
	v_and_b32_e32 v129, 0xffff0000, v181
	v_fmac_f32_e32 v130, v118, v206
	v_fmac_f32_e32 v128, v119, v207
	v_fmac_f32_e32 v137, v120, v208
	v_fmac_f32_e32 v129, v121, v209
	v_cvt_pk_bf16_f32 v118, v130, v128
	v_cvt_pk_bf16_f32 v119, v137, v129
	global_store_dwordx2 v[126:127], v[118:119], off offset:64
	v_or_b32_e32 v118, 48, v132
	v_lshl_add_u64 v[122:123], v[132:133], 1, v[140:141]
	v_add_f32_e32 v114, 0, v114
	v_add_f32_e32 v115, 0, v115
	v_add_f32_e32 v116, 0, v116
	v_add_f32_e32 v117, 0, v117
	s_waitcnt vmcnt(7)
	v_lshlrev_b32_e32 v126, 16, v182
	v_and_b32_e32 v124, 0xffff0000, v182
	v_lshlrev_b32_e32 v127, 16, v183
	v_and_b32_e32 v125, 0xffff0000, v183
	v_fmac_f32_e32 v126, v114, v210
	v_fmac_f32_e32 v124, v115, v211
	v_fmac_f32_e32 v127, v116, v212
	v_fmac_f32_e32 v125, v117, v213
	v_cvt_pk_bf16_f32 v114, v126, v124
	v_cvt_pk_bf16_f32 v115, v127, v125
	global_store_dwordx2 v[122:123], v[114:115], off offset:96
	v_or_b32_e32 v114, 64, v132
	v_lshl_add_u64 v[118:119], v[132:133], 1, v[140:141]
	v_add_f32_e32 v110, 0, v110
	v_add_f32_e32 v111, 0, v111
	v_add_f32_e32 v112, 0, v112
	v_add_f32_e32 v113, 0, v113
	s_waitcnt vmcnt(7)
	v_lshlrev_b32_e32 v122, 16, v184
	v_and_b32_e32 v120, 0xffff0000, v184
	v_lshlrev_b32_e32 v123, 16, v185
	v_and_b32_e32 v121, 0xffff0000, v185
	v_fmac_f32_e32 v122, v110, v214
	v_fmac_f32_e32 v120, v111, v215
	v_fmac_f32_e32 v123, v112, v216
	v_fmac_f32_e32 v121, v113, v217
	v_cvt_pk_bf16_f32 v110, v122, v120
	v_cvt_pk_bf16_f32 v111, v123, v121
	global_store_dwordx2 v[118:119], v[110:111], off offset:128
	v_or_b32_e32 v110, 0x50, v132
	v_lshl_add_u64 v[114:115], v[132:133], 1, v[140:141]
	v_add_f32_e32 v106, 0, v106
	v_add_f32_e32 v107, 0, v107
	v_add_f32_e32 v108, 0, v108
	v_add_f32_e32 v109, 0, v109
	s_waitcnt vmcnt(7)
; __device__ __forceinline__ unsigned pack2(float a, float b) { unsigned r; asm("v_cvt_pk_bf16_f32 %0, %1, %2" : "=v"(r) : "v"(a), "v"(b)); return r; }
; __device__ __forceinline__ float bf2f(bf16_t h) { return __uint_as_float(((unsigned)h) << 16); }
;   __device__ __forceinline__ void c4(int g, int rig, int col, f32x4 v) const {
;     const size_t o = ((size_t)g * 2048 + rig) * 1024 + col;
;     f32x4 bs;
;     if (BASE_F32) bs = __builtin_nontemporal_load((const f32x4*)((const float*)base + o));
;     else {
;       const uint2 u = *(const uint2*)((const bf16_t*)base + o);
;       bs[0] = bf2f((bf16_t)(u.x & 0xffff)); bs[1] = bf2f((bf16_t)(u.x >> 16)); bs[2] = bf2f((bf16_t)(u.y & 0xffff)); bs[3] = bf2f((bf16_t)(u.y >> 16));
;     }
;     const f32x4 gt = *(const f32x4*)(gate + (size_t)g * 6144 + col);
;     f32x4 bi = {0.f, 0.f, 0.f, 0.f};
;     if (bias) bi = *(const f32x4*)(bias + col);
;     f32x4 r;
; #pragma unroll
;     for (int j = 0; j < 4; ++j) r[j] = bs[j] + gt[j] * (v[j] + bi[j]);
;     uint2 w; w.x = pack2(r[0], r[1]); w.y = pack2(r[2], r[3]);
;     *(uint2*)(X16 + o) = w;
;   }
; template <bool SWAP, class Epi, bool THIN = false> ...
;     ...
; #pragma unroll
;       for (int m = 0; m < 4; ++m) {
;         const int rig = rig0 + rw + m * 16 + fr_e;
;         if constexpr (Epi::ROWSUM) {
;           float ss = 0.f;
; #pragma unroll
;           for (int n = 0; n < 8; ++n) {
;             const int col = nt * 256 + wc_e * 128 + n * 16 + fq_e * 4;
;             if (col < N) ss += epi.c4(g, rig, col, acc[m][n]);
;           }
;           ss += __shfl_xor(ss, 16); ss += __shfl_xor(ss, 32);
;           if (fq_e == 0) epi.rowsum(g, rig, nt * 2 + wc_e, ss);
;         } else {
; #pragma unroll
;           for (int n = 0; n < 8; ++n) {
;             const int col = nt * 256 + wc_e * 128 + n * 16 + fq_e * 4;
;             if (col < N) epi.c4(g, rig, col, acc[m][n]);
	v_lshlrev_b32_e32 v118, 16, v186
	v_and_b32_e32 v116, 0xffff0000, v186
	v_lshlrev_b32_e32 v119, 16, v187
	v_and_b32_e32 v117, 0xffff0000, v187
	v_fmac_f32_e32 v118, v106, v224
	v_fmac_f32_e32 v116, v107, v225
	v_fmac_f32_e32 v119, v108, v226
	v_fmac_f32_e32 v117, v109, v227
	v_cvt_pk_bf16_f32 v106, v118, v116
	v_cvt_pk_bf16_f32 v107, v119, v117
	global_store_dwordx2 v[114:115], v[106:107], off offset:160
	v_or_b32_e32 v106, 0x60, v132
	v_lshl_add_u64 v[110:111], v[132:133], 1, v[140:141]
	v_add_f32_e32 v102, 0, v102
	v_add_f32_e32 v103, 0, v103
	v_add_f32_e32 v104, 0, v104
	v_add_f32_e32 v105, 0, v105
	s_waitcnt vmcnt(7)
	v_lshlrev_b32_e32 v114, 16, v188
	v_and_b32_e32 v112, 0xffff0000, v188
	v_lshlrev_b32_e32 v115, 16, v189
	v_and_b32_e32 v113, 0xffff0000, v189
	v_fmac_f32_e32 v114, v102, v228
	v_fmac_f32_e32 v112, v103, v229
	v_fmac_f32_e32 v115, v104, v230
	v_fmac_f32_e32 v113, v105, v231
	v_cvt_pk_bf16_f32 v102, v114, v112
	v_cvt_pk_bf16_f32 v103, v115, v113
	global_store_dwordx2 v[110:111], v[102:103], off offset:192
	v_or_b32_e32 v102, 0x70, v132
	v_lshl_add_u64 v[106:107], v[132:133], 1, v[140:141]
	v_add_f32_e32 v98, 0, v98
	v_add_f32_e32 v99, 0, v99
	v_add_f32_e32 v100, 0, v100
	v_add_f32_e32 v101, 0, v101
	s_waitcnt vmcnt(7)
	v_lshlrev_b32_e32 v110, 16, v190
	v_and_b32_e32 v108, 0xffff0000, v190
	v_lshlrev_b32_e32 v111, 16, v191
	v_and_b32_e32 v109, 0xffff0000, v191
	v_fmac_f32_e32 v110, v98, v232
	v_fmac_f32_e32 v108, v99, v233
	v_fmac_f32_e32 v111, v100, v234
	v_fmac_f32_e32 v109, v101, v235
	v_cvt_pk_bf16_f32 v98, v110, v108
	v_cvt_pk_bf16_f32 v99, v111, v109
	global_store_dwordx2 v[106:107], v[98:99], off offset:224
	v_or_b32_e32 v98, 16, v136
	v_ashrrev_i32_e32 v99, 31, v98
	v_lshlrev_b64 v[98:99], 10, v[98:99]
	v_lshl_add_u64 v[98:99], v[98:99], 0, v[138:139]
	v_lshl_add_u64 v[98:99], v[98:99], 1, s[18:19]
	v_lshl_add_u64 v[104:105], v[132:133], 1, v[98:99]
	v_lshl_add_u64 v[196:197], v[132:133], 1, v[98:99]
	global_load_dwordx2 v[176:177], v[196:197], off
	global_load_dwordx2 v[178:179], v[196:197], off offset:32
	global_load_dwordx2 v[180:181], v[196:197], off offset:64
	global_load_dwordx2 v[182:183], v[196:197], off offset:96
	global_load_dwordx2 v[184:185], v[196:197], off offset:128
	global_load_dwordx2 v[186:187], v[196:197], off offset:160
	global_load_dwordx2 v[188:189], v[196:197], off offset:192
	global_load_dwordx2 v[190:191], v[196:197], off offset:224
	v_add_f32_e32 v94, 0, v94
	v_add_f32_e32 v95, 0, v95
	v_add_f32_e32 v96, 0, v96
	v_add_f32_e32 v97, 0, v97
	s_waitcnt vmcnt(7)
	v_lshlrev_b32_e32 v108, 16, v176
	v_and_b32_e32 v106, 0xffff0000, v176
	v_lshlrev_b32_e32 v109, 16, v177
	v_and_b32_e32 v107, 0xffff0000, v177
	v_fmac_f32_e32 v108, v94, v198
	v_fmac_f32_e32 v106, v95, v199
	v_fmac_f32_e32 v109, v96, v200
	v_fmac_f32_e32 v107, v97, v201
	v_cvt_pk_bf16_f32 v94, v108, v106
	v_cvt_pk_bf16_f32 v95, v109, v107
	global_store_dwordx2 v[104:105], v[94:95], off
	v_lshl_add_u64 v[100:101], v[132:133], 1, v[98:99]
	v_add_f32_e32 v90, 0, v90
	v_add_f32_e32 v91, 0, v91
	v_add_f32_e32 v92, 0, v92
	v_add_f32_e32 v93, 0, v93
	s_waitcnt vmcnt(7)
	v_lshlrev_b32_e32 v104, 16, v178
	v_and_b32_e32 v102, 0xffff0000, v178
	v_lshlrev_b32_e32 v105, 16, v179
	v_and_b32_e32 v103, 0xffff0000, v179
	v_fmac_f32_e32 v104, v90, v202
	v_fmac_f32_e32 v102, v91, v203
	v_fmac_f32_e32 v105, v92, v204
	v_fmac_f32_e32 v103, v93, v205
	v_cvt_pk_bf16_f32 v90, v104, v102
	v_cvt_pk_bf16_f32 v91, v105, v103
	global_store_dwordx2 v[100:101], v[90:91], off offset:32
	v_lshl_add_u64 v[94:95], v[132:133], 1, v[98:99]
	v_add_f32_e32 v86, 0, v86
	v_add_f32_e32 v87, 0, v87
	v_add_f32_e32 v88, 0, v88
	v_add_f32_e32 v89, 0, v89
	s_waitcnt vmcnt(7)
	v_lshlrev_b32_e32 v100, 16, v180
	v_and_b32_e32 v96, 0xffff0000, v180
	v_lshlrev_b32_e32 v101, 16, v181
	v_and_b32_e32 v97, 0xffff0000, v181
	v_fmac_f32_e32 v100, v86, v206
	v_fmac_f32_e32 v96, v87, v207
	v_fmac_f32_e32 v101, v88, v208
	v_fmac_f32_e32 v97, v89, v209
	v_cvt_pk_bf16_f32 v86, v100, v96
	v_cvt_pk_bf16_f32 v87, v101, v97
	global_store_dwordx2 v[94:95], v[86:87], off offset:64
	v_lshl_add_u64 v[90:91], v[132:133], 1, v[98:99]
	v_add_f32_e32 v82, 0, v82
	v_add_f32_e32 v83, 0, v83
	v_add_f32_e32 v84, 0, v84
	v_add_f32_e32 v85, 0, v85
	s_waitcnt vmcnt(7)
	v_lshlrev_b32_e32 v94, 16, v182
	v_and_b32_e32 v92, 0xffff0000, v182
	v_lshlrev_b32_e32 v95, 16, v183
	v_and_b32_e32 v93, 0xffff0000, v183
	v_fmac_f32_e32 v94, v82, v210
	v_fmac_f32_e32 v92, v83, v211
	v_fmac_f32_e32 v95, v84, v212
	v_fmac_f32_e32 v93, v85, v213
	v_cvt_pk_bf16_f32 v82, v94, v92
	v_cvt_pk_bf16_f32 v83, v95, v93
	global_store_dwordx2 v[90:91], v[82:83], off offset:96
	v_lshl_add_u64 v[86:87], v[132:133], 1, v[98:99]
	v_add_f32_e32 v78, 0, v78
	v_add_f32_e32 v79, 0, v79
	v_add_f32_e32 v80, 0, v80
	v_add_f32_e32 v81, 0, v81
	s_waitcnt vmcnt(7)
	v_lshlrev_b32_e32 v90, 16, v184
	v_and_b32_e32 v88, 0xffff0000, v184
	v_lshlrev_b32_e32 v91, 16, v185
	v_and_b32_e32 v89, 0xffff0000, v185
	v_fmac_f32_e32 v90, v78, v214
	v_fmac_f32_e32 v88, v79, v215
	v_fmac_f32_e32 v91, v80, v216
	v_fmac_f32_e32 v89, v81, v217
	v_cvt_pk_bf16_f32 v78, v90, v88
	v_cvt_pk_bf16_f32 v79, v91, v89
	global_store_dwordx2 v[86:87], v[78:79], off offset:128
	v_lshl_add_u64 v[82:83], v[132:133], 1, v[98:99]
	v_add_f32_e32 v74, 0, v74
	v_add_f32_e32 v75, 0, v75
	v_add_f32_e32 v76, 0, v76
	v_add_f32_e32 v77, 0, v77
	s_waitcnt vmcnt(7)
; __device__ __forceinline__ unsigned pack2(float a, float b) { unsigned r; asm("v_cvt_pk_bf16_f32 %0, %1, %2" : "=v"(r) : "v"(a), "v"(b)); return r; }
; __device__ __forceinline__ float bf2f(bf16_t h) { return __uint_as_float(((unsigned)h) << 16); }
;   __device__ __forceinline__ void c4(int g, int rig, int col, f32x4 v) const {
;     const size_t o = ((size_t)g * 2048 + rig) * 1024 + col;
;     f32x4 bs;
;     if (BASE_F32) bs = __builtin_nontemporal_load((const f32x4*)((const float*)base + o));
;     else {
;       const uint2 u = *(const uint2*)((const bf16_t*)base + o);
;       bs[0] = bf2f((bf16_t)(u.x & 0xffff)); bs[1] = bf2f((bf16_t)(u.x >> 16)); bs[2] = bf2f((bf16_t)(u.y & 0xffff)); bs[3] = bf2f((bf16_t)(u.y >> 16));
;     }
;     const f32x4 gt = *(const f32x4*)(gate + (size_t)g * 6144 + col);
;     f32x4 bi = {0.f, 0.f, 0.f, 0.f};
;     if (bias) bi = *(const f32x4*)(bias + col);
;     f32x4 r;
; #pragma unroll
;     for (int j = 0; j < 4; ++j) r[j] = bs[j] + gt[j] * (v[j] + bi[j]);
;     uint2 w; w.x = pack2(r[0], r[1]); w.y = pack2(r[2], r[3]);
;     *(uint2*)(X16 + o) = w;
;   }
; template <bool SWAP, class Epi, bool THIN = false> ...
;     ...
; #pragma unroll
;       for (int m = 0; m < 4; ++m) {
;         const int rig = rig0 + rw + m * 16 + fr_e;
;         if constexpr (Epi::ROWSUM) {
;           float ss = 0.f;
; #pragma unroll
;           for (int n = 0; n < 8; ++n) {
;             const int col = nt * 256 + wc_e * 128 + n * 16 + fq_e * 4;
;             if (col < N) ss += epi.c4(g, rig, col, acc[m][n]);
;           }
;           ss += __shfl_xor(ss, 16); ss += __shfl_xor(ss, 32);
;           if (fq_e == 0) epi.rowsum(g, rig, nt * 2 + wc_e, ss);
;         } else {
; #pragma unroll
;           for (int n = 0; n < 8; ++n) {
;             const int col = nt * 256 + wc_e * 128 + n * 16 + fq_e * 4;
;             if (col < N) epi.c4(g, rig, col, acc[m][n]);
	v_lshlrev_b32_e32 v86, 16, v186
	v_and_b32_e32 v84, 0xffff0000, v186
	v_lshlrev_b32_e32 v87, 16, v187
	v_and_b32_e32 v85, 0xffff0000, v187
	v_fmac_f32_e32 v86, v74, v224
	v_fmac_f32_e32 v84, v75, v225
	v_fmac_f32_e32 v87, v76, v226
	v_fmac_f32_e32 v85, v77, v227
	v_cvt_pk_bf16_f32 v74, v86, v84
	v_cvt_pk_bf16_f32 v75, v87, v85
	global_store_dwordx2 v[82:83], v[74:75], off offset:160
	v_lshl_add_u64 v[78:79], v[132:133], 1, v[98:99]
	v_add_f32_e32 v70, 0, v70
	v_add_f32_e32 v71, 0, v71
	v_add_f32_e32 v72, 0, v72
	v_add_f32_e32 v73, 0, v73
	s_waitcnt vmcnt(7)
	v_lshlrev_b32_e32 v82, 16, v188
	v_and_b32_e32 v80, 0xffff0000, v188
	v_lshlrev_b32_e32 v83, 16, v189
	v_and_b32_e32 v81, 0xffff0000, v189
	v_fmac_f32_e32 v82, v70, v228
	v_fmac_f32_e32 v80, v71, v229
	v_fmac_f32_e32 v83, v72, v230
	v_fmac_f32_e32 v81, v73, v231
	v_cvt_pk_bf16_f32 v70, v82, v80
	v_cvt_pk_bf16_f32 v71, v83, v81
	global_store_dwordx2 v[78:79], v[70:71], off offset:192
	v_lshl_add_u64 v[74:75], v[132:133], 1, v[98:99]
	v_add_f32_e32 v66, 0, v66
	v_add_f32_e32 v67, 0, v67
	v_add_f32_e32 v68, 0, v68
	v_add_f32_e32 v69, 0, v69
	s_waitcnt vmcnt(7)
	v_lshlrev_b32_e32 v78, 16, v190
	v_and_b32_e32 v76, 0xffff0000, v190
	v_lshlrev_b32_e32 v79, 16, v191
	v_and_b32_e32 v77, 0xffff0000, v191
	v_fmac_f32_e32 v78, v66, v232
	v_fmac_f32_e32 v76, v67, v233
	v_fmac_f32_e32 v79, v68, v234
	v_fmac_f32_e32 v77, v69, v235
	v_cvt_pk_bf16_f32 v66, v78, v76
	v_cvt_pk_bf16_f32 v67, v79, v77
	global_store_dwordx2 v[74:75], v[66:67], off offset:224
	v_or_b32_e32 v66, 32, v136
	v_ashrrev_i32_e32 v67, 31, v66
	v_lshlrev_b64 v[66:67], 10, v[66:67]
	v_lshl_add_u64 v[66:67], v[66:67], 0, v[138:139]
	v_lshl_add_u64 v[66:67], v[66:67], 1, s[18:19]
	v_lshl_add_u64 v[72:73], v[132:133], 1, v[66:67]
	v_lshl_add_u64 v[196:197], v[132:133], 1, v[66:67]
	global_load_dwordx2 v[176:177], v[196:197], off
	global_load_dwordx2 v[178:179], v[196:197], off offset:32
	global_load_dwordx2 v[180:181], v[196:197], off offset:64
	global_load_dwordx2 v[182:183], v[196:197], off offset:96
	global_load_dwordx2 v[184:185], v[196:197], off offset:128
	global_load_dwordx2 v[186:187], v[196:197], off offset:160
	global_load_dwordx2 v[188:189], v[196:197], off offset:192
	global_load_dwordx2 v[190:191], v[196:197], off offset:224
	v_add_f32_e32 v62, 0, v62
	v_add_f32_e32 v63, 0, v63
	v_add_f32_e32 v64, 0, v64
	v_add_f32_e32 v65, 0, v65
	s_waitcnt vmcnt(7)
	v_lshlrev_b32_e32 v76, 16, v176
	v_and_b32_e32 v74, 0xffff0000, v176
	v_lshlrev_b32_e32 v77, 16, v177
	v_and_b32_e32 v75, 0xffff0000, v177
	v_fmac_f32_e32 v76, v62, v198
	v_fmac_f32_e32 v74, v63, v199
	v_fmac_f32_e32 v77, v64, v200
	v_fmac_f32_e32 v75, v65, v201
	v_cvt_pk_bf16_f32 v62, v76, v74
	v_cvt_pk_bf16_f32 v63, v77, v75
	global_store_dwordx2 v[72:73], v[62:63], off
	v_lshl_add_u64 v[68:69], v[132:133], 1, v[66:67]
	v_add_f32_e32 v58, 0, v58
	v_add_f32_e32 v59, 0, v59
	v_add_f32_e32 v60, 0, v60
	v_add_f32_e32 v61, 0, v61
	s_waitcnt vmcnt(7)
	v_lshlrev_b32_e32 v72, 16, v178
	v_and_b32_e32 v70, 0xffff0000, v178
	v_lshlrev_b32_e32 v73, 16, v179
	v_and_b32_e32 v71, 0xffff0000, v179
	v_fmac_f32_e32 v72, v58, v202
	v_fmac_f32_e32 v70, v59, v203
	v_fmac_f32_e32 v73, v60, v204
	v_fmac_f32_e32 v71, v61, v205
	v_cvt_pk_bf16_f32 v58, v72, v70
	v_cvt_pk_bf16_f32 v59, v73, v71
	global_store_dwordx2 v[68:69], v[58:59], off offset:32
	v_lshl_add_u64 v[62:63], v[132:133], 1, v[66:67]
	v_add_f32_e32 v54, 0, v54
	v_add_f32_e32 v55, 0, v55
	v_add_f32_e32 v56, 0, v56
	v_add_f32_e32 v57, 0, v57
	s_waitcnt vmcnt(7)
	v_lshlrev_b32_e32 v68, 16, v180
	v_and_b32_e32 v64, 0xffff0000, v180
	v_lshlrev_b32_e32 v69, 16, v181
	v_and_b32_e32 v65, 0xffff0000, v181
	v_fmac_f32_e32 v68, v54, v206
	v_fmac_f32_e32 v64, v55, v207
	v_fmac_f32_e32 v69, v56, v208
	v_fmac_f32_e32 v65, v57, v209
	v_cvt_pk_bf16_f32 v54, v68, v64
	v_cvt_pk_bf16_f32 v55, v69, v65
	global_store_dwordx2 v[62:63], v[54:55], off offset:64
	v_lshl_add_u64 v[58:59], v[132:133], 1, v[66:67]
	v_add_f32_e32 v50, 0, v50
	v_add_f32_e32 v51, 0, v51
	v_add_f32_e32 v52, 0, v52
	v_add_f32_e32 v53, 0, v53
	s_waitcnt vmcnt(7)
	v_lshlrev_b32_e32 v62, 16, v182
	v_and_b32_e32 v60, 0xffff0000, v182
	v_lshlrev_b32_e32 v63, 16, v183
	v_and_b32_e32 v61, 0xffff0000, v183
	v_fmac_f32_e32 v62, v50, v210
	v_fmac_f32_e32 v60, v51, v211
	v_fmac_f32_e32 v63, v52, v212
	v_fmac_f32_e32 v61, v53, v213
	v_cvt_pk_bf16_f32 v50, v62, v60
	v_cvt_pk_bf16_f32 v51, v63, v61
	global_store_dwordx2 v[58:59], v[50:51], off offset:96
	v_lshl_add_u64 v[54:55], v[132:133], 1, v[66:67]
	v_add_f32_e32 v46, 0, v46
	v_add_f32_e32 v47, 0, v47
	v_add_f32_e32 v48, 0, v48
	v_add_f32_e32 v49, 0, v49
	s_waitcnt vmcnt(7)
	v_lshlrev_b32_e32 v58, 16, v184
	v_and_b32_e32 v56, 0xffff0000, v184
	v_lshlrev_b32_e32 v59, 16, v185
	v_and_b32_e32 v57, 0xffff0000, v185
	v_fmac_f32_e32 v58, v46, v214
	v_fmac_f32_e32 v56, v47, v215
	v_fmac_f32_e32 v59, v48, v216
	v_fmac_f32_e32 v57, v49, v217
	v_cvt_pk_bf16_f32 v46, v58, v56
	v_cvt_pk_bf16_f32 v47, v59, v57
	global_store_dwordx2 v[54:55], v[46:47], off offset:128
	v_lshl_add_u64 v[50:51], v[132:133], 1, v[66:67]
	v_add_f32_e32 v42, 0, v42
	v_add_f32_e32 v43, 0, v43
	v_add_f32_e32 v44, 0, v44
	v_add_f32_e32 v45, 0, v45
	s_waitcnt vmcnt(7)
	v_lshlrev_b32_e32 v54, 16, v186
	v_and_b32_e32 v52, 0xffff0000, v186
	v_lshlrev_b32_e32 v55, 16, v187
	v_and_b32_e32 v53, 0xffff0000, v187
	v_fmac_f32_e32 v54, v42, v224
	v_fmac_f32_e32 v52, v43, v225
	v_fmac_f32_e32 v55, v44, v226
	v_fmac_f32_e32 v53, v45, v227
	v_cvt_pk_bf16_f32 v42, v54, v52
	v_cvt_pk_bf16_f32 v43, v55, v53
	global_store_dwordx2 v[50:51], v[42:43], off offset:160
	v_lshl_add_u64 v[46:47], v[132:133], 1, v[66:67]
	v_add_f32_e32 v38, 0, v38
	v_add_f32_e32 v39, 0, v39
	v_add_f32_e32 v40, 0, v40
	v_add_f32_e32 v41, 0, v41
	s_waitcnt vmcnt(7)
; __device__ __forceinline__ unsigned pack2(float a, float b) { unsigned r; asm("v_cvt_pk_bf16_f32 %0, %1, %2" : "=v"(r) : "v"(a), "v"(b)); return r; }
; __device__ __forceinline__ float bf2f(bf16_t h) { return __uint_as_float(((unsigned)h) << 16); }
;   __device__ __forceinline__ void c4(int g, int rig, int col, f32x4 v) const {
;     const size_t o = ((size_t)g * 2048 + rig) * 1024 + col;
;     f32x4 bs;
;     if (BASE_F32) bs = __builtin_nontemporal_load((const f32x4*)((const float*)base + o));
;     else {
;       const uint2 u = *(const uint2*)((const bf16_t*)base + o);
;       bs[0] = bf2f((bf16_t)(u.x & 0xffff)); bs[1] = bf2f((bf16_t)(u.x >> 16)); bs[2] = bf2f((bf16_t)(u.y & 0xffff)); bs[3] = bf2f((bf16_t)(u.y >> 16));
;     }
;     const f32x4 gt = *(const f32x4*)(gate + (size_t)g * 6144 + col);
;     f32x4 bi = {0.f, 0.f, 0.f, 0.f};
;     if (bias) bi = *(const f32x4*)(bias + col);
;     f32x4 r;
; #pragma unroll
;     for (int j = 0; j < 4; ++j) r[j] = bs[j] + gt[j] * (v[j] + bi[j]);
;     uint2 w; w.x = pack2(r[0], r[1]); w.y = pack2(r[2], r[3]);
;     *(uint2*)(X16 + o) = w;
;   }
; template <bool SWAP, class Epi, bool THIN = false> ...
;     ...
; #pragma unroll
;       for (int m = 0; m < 4; ++m) {
;         const int rig = rig0 + rw + m * 16 + fr_e;
;         if constexpr (Epi::ROWSUM) {
;           float ss = 0.f;
; #pragma unroll
;           for (int n = 0; n < 8; ++n) {
;             const int col = nt * 256 + wc_e * 128 + n * 16 + fq_e * 4;
;             if (col < N) ss += epi.c4(g, rig, col, acc[m][n]);
;           }
;           ss += __shfl_xor(ss, 16); ss += __shfl_xor(ss, 32);
;           if (fq_e == 0) epi.rowsum(g, rig, nt * 2 + wc_e, ss);
;         } else {
; #pragma unroll
;           for (int n = 0; n < 8; ++n) {
;             const int col = nt * 256 + wc_e * 128 + n * 16 + fq_e * 4;
;             if (col < N) epi.c4(g, rig, col, acc[m][n]);
	v_lshlrev_b32_e32 v50, 16, v188
	v_and_b32_e32 v48, 0xffff0000, v188
	v_lshlrev_b32_e32 v51, 16, v189
	v_and_b32_e32 v49, 0xffff0000, v189
	v_fmac_f32_e32 v50, v38, v228
	v_fmac_f32_e32 v48, v39, v229
	v_fmac_f32_e32 v51, v40, v230
	v_fmac_f32_e32 v49, v41, v231
	v_cvt_pk_bf16_f32 v38, v50, v48
	v_cvt_pk_bf16_f32 v39, v51, v49
	global_store_dwordx2 v[46:47], v[38:39], off offset:192
	v_lshl_add_u64 v[42:43], v[132:133], 1, v[66:67]
	v_add_f32_e32 v34, 0, v34
	v_add_f32_e32 v35, 0, v35
	v_add_f32_e32 v36, 0, v36
	v_add_f32_e32 v37, 0, v37
	s_waitcnt vmcnt(7)
	v_lshlrev_b32_e32 v46, 16, v190
	v_and_b32_e32 v44, 0xffff0000, v190
	v_lshlrev_b32_e32 v47, 16, v191
	v_and_b32_e32 v45, 0xffff0000, v191
	v_fmac_f32_e32 v46, v34, v232
	v_fmac_f32_e32 v44, v35, v233
	v_fmac_f32_e32 v47, v36, v234
	v_fmac_f32_e32 v45, v37, v235
	v_cvt_pk_bf16_f32 v34, v46, v44
	v_cvt_pk_bf16_f32 v35, v47, v45
	global_store_dwordx2 v[42:43], v[34:35], off offset:224
	v_or_b32_e32 v34, 48, v136
	v_ashrrev_i32_e32 v35, 31, v34
	v_lshlrev_b64 v[34:35], 10, v[34:35]
	v_lshl_add_u64 v[34:35], v[34:35], 0, v[138:139]
	v_lshl_add_u64 v[34:35], v[34:35], 1, s[18:19]
	v_lshl_add_u64 v[40:41], v[132:133], 1, v[34:35]
	v_lshl_add_u64 v[196:197], v[132:133], 1, v[34:35]
	global_load_dwordx2 v[176:177], v[196:197], off
	global_load_dwordx2 v[178:179], v[196:197], off offset:32
	global_load_dwordx2 v[180:181], v[196:197], off offset:64
	global_load_dwordx2 v[182:183], v[196:197], off offset:96
	global_load_dwordx2 v[184:185], v[196:197], off offset:128
	global_load_dwordx2 v[186:187], v[196:197], off offset:160
	global_load_dwordx2 v[188:189], v[196:197], off offset:192
	global_load_dwordx2 v[190:191], v[196:197], off offset:224
	v_add_f32_e32 v30, 0, v30
	v_add_f32_e32 v31, 0, v31
	v_add_f32_e32 v32, 0, v32
	v_add_f32_e32 v33, 0, v33
	s_waitcnt vmcnt(7)
	v_lshlrev_b32_e32 v44, 16, v176
	v_and_b32_e32 v42, 0xffff0000, v176
	v_lshlrev_b32_e32 v45, 16, v177
	v_and_b32_e32 v43, 0xffff0000, v177
	v_fmac_f32_e32 v44, v30, v198
	v_fmac_f32_e32 v42, v31, v199
	v_fmac_f32_e32 v45, v32, v200
	v_fmac_f32_e32 v43, v33, v201
	v_cvt_pk_bf16_f32 v30, v44, v42
	v_cvt_pk_bf16_f32 v31, v45, v43
	global_store_dwordx2 v[40:41], v[30:31], off
	v_lshl_add_u64 v[36:37], v[132:133], 1, v[34:35]
	v_add_f32_e32 v26, 0, v26
	v_add_f32_e32 v27, 0, v27
	v_add_f32_e32 v28, 0, v28
	v_add_f32_e32 v29, 0, v29
	s_waitcnt vmcnt(7)
	v_lshlrev_b32_e32 v40, 16, v178
	v_and_b32_e32 v38, 0xffff0000, v178
	v_lshlrev_b32_e32 v41, 16, v179
	v_and_b32_e32 v39, 0xffff0000, v179
	v_fmac_f32_e32 v40, v26, v202
	v_fmac_f32_e32 v38, v27, v203
	v_fmac_f32_e32 v41, v28, v204
	v_fmac_f32_e32 v39, v29, v205
	v_cvt_pk_bf16_f32 v26, v40, v38
	v_cvt_pk_bf16_f32 v27, v41, v39
	global_store_dwordx2 v[36:37], v[26:27], off offset:32
	v_lshl_add_u64 v[30:31], v[132:133], 1, v[34:35]
	v_add_f32_e32 v22, 0, v22
	v_add_f32_e32 v23, 0, v23
	v_add_f32_e32 v24, 0, v24
	v_add_f32_e32 v25, 0, v25
	s_waitcnt vmcnt(7)
	v_lshlrev_b32_e32 v36, 16, v180
	v_and_b32_e32 v32, 0xffff0000, v180
	v_lshlrev_b32_e32 v37, 16, v181
	v_and_b32_e32 v33, 0xffff0000, v181
	v_fmac_f32_e32 v36, v22, v206
	v_fmac_f32_e32 v32, v23, v207
	v_fmac_f32_e32 v37, v24, v208
	v_fmac_f32_e32 v33, v25, v209
	v_cvt_pk_bf16_f32 v22, v36, v32
	v_cvt_pk_bf16_f32 v23, v37, v33
	global_store_dwordx2 v[30:31], v[22:23], off offset:64
	v_lshl_add_u64 v[26:27], v[132:133], 1, v[34:35]
	v_add_f32_e32 v18, 0, v18
	v_add_f32_e32 v19, 0, v19
	v_add_f32_e32 v20, 0, v20
	v_add_f32_e32 v21, 0, v21
	s_waitcnt vmcnt(7)
	v_lshlrev_b32_e32 v30, 16, v182
	v_and_b32_e32 v28, 0xffff0000, v182
	v_lshlrev_b32_e32 v31, 16, v183
	v_and_b32_e32 v29, 0xffff0000, v183
	v_fmac_f32_e32 v30, v18, v210
	v_fmac_f32_e32 v28, v19, v211
	v_fmac_f32_e32 v31, v20, v212
	v_fmac_f32_e32 v29, v21, v213
	v_cvt_pk_bf16_f32 v18, v30, v28
	v_cvt_pk_bf16_f32 v19, v31, v29
	global_store_dwordx2 v[26:27], v[18:19], off offset:96
	v_lshl_add_u64 v[22:23], v[132:133], 1, v[34:35]
	v_add_f32_e32 v14, 0, v14
	v_add_f32_e32 v15, 0, v15
	v_add_f32_e32 v16, 0, v16
	v_add_f32_e32 v17, 0, v17
	s_waitcnt vmcnt(7)
	v_lshlrev_b32_e32 v26, 16, v184
	v_and_b32_e32 v24, 0xffff0000, v184
	v_lshlrev_b32_e32 v27, 16, v185
	v_and_b32_e32 v25, 0xffff0000, v185
	v_fmac_f32_e32 v26, v14, v214
	v_fmac_f32_e32 v24, v15, v215
	v_fmac_f32_e32 v27, v16, v216
	v_fmac_f32_e32 v25, v17, v217
	v_cvt_pk_bf16_f32 v14, v26, v24
	v_cvt_pk_bf16_f32 v15, v27, v25
	global_store_dwordx2 v[22:23], v[14:15], off offset:128
	v_lshl_add_u64 v[18:19], v[132:133], 1, v[34:35]
	v_add_f32_e32 v10, 0, v10
	v_add_f32_e32 v11, 0, v11
	v_add_f32_e32 v12, 0, v12
	v_add_f32_e32 v13, 0, v13
	s_waitcnt vmcnt(7)
	v_lshlrev_b32_e32 v22, 16, v186
	v_and_b32_e32 v20, 0xffff0000, v186
	v_lshlrev_b32_e32 v23, 16, v187
	v_and_b32_e32 v21, 0xffff0000, v187
	v_fmac_f32_e32 v22, v10, v224
	v_fmac_f32_e32 v20, v11, v225
	v_fmac_f32_e32 v23, v12, v226
	v_fmac_f32_e32 v21, v13, v227
	v_cvt_pk_bf16_f32 v10, v22, v20
	v_cvt_pk_bf16_f32 v11, v23, v21
	global_store_dwordx2 v[18:19], v[10:11], off offset:160
	v_lshl_add_u64 v[14:15], v[132:133], 1, v[34:35]
	v_add_f32_e32 v6, 0, v6
	v_add_f32_e32 v7, 0, v7
	v_add_f32_e32 v8, 0, v8
	v_add_f32_e32 v9, 0, v9
	s_waitcnt vmcnt(7)
	v_lshlrev_b32_e32 v18, 16, v188
	v_and_b32_e32 v16, 0xffff0000, v188
	v_lshlrev_b32_e32 v19, 16, v189
	v_and_b32_e32 v17, 0xffff0000, v189
	v_fmac_f32_e32 v18, v6, v228
	v_fmac_f32_e32 v16, v7, v229
	v_fmac_f32_e32 v19, v8, v230
	v_fmac_f32_e32 v17, v9, v231
	v_cvt_pk_bf16_f32 v6, v18, v16
	v_cvt_pk_bf16_f32 v7, v19, v17
	global_store_dwordx2 v[14:15], v[6:7], off offset:192
	v_lshl_add_u64 v[10:11], v[132:133], 1, v[34:35]
	v_add_f32_e32 v2, 0, v2
	v_add_f32_e32 v3, 0, v3
	v_add_f32_e32 v4, 0, v4
	v_add_f32_e32 v5, 0, v5
	s_waitcnt vmcnt(7)
	v_lshlrev_b32_e32 v14, 16, v190
	v_and_b32_e32 v12, 0xffff0000, v190
	v_lshlrev_b32_e32 v15, 16, v191
	v_and_b32_e32 v13, 0xffff0000, v191
	v_fmac_f32_e32 v14, v2, v232
	v_fmac_f32_e32 v12, v3, v233
	v_fmac_f32_e32 v15, v4, v234
	v_fmac_f32_e32 v13, v5, v235
	v_cvt_pk_bf16_f32 v2, v14, v12
	v_cvt_pk_bf16_f32 v3, v15, v13
	global_store_dwordx2 v[10:11], v[2:3], off offset:224
	s_branch .LBB0_3514
